# GEMM K-loops: merged phase pairs (8 barriers per 2 K-tiles), ds_reads issued before LDS-DMA in load segments
# speedup vs baseline: 1.0153x; 1.0055x over previous
.LBB0_99:
	v_add_u32_e32 v137, 0x10000, v135
	ds_read_b128 v[138:141], v137
	ds_read_b128 v[142:145], v137 offset:1024
	ds_read_b128 v[146:149], v137 offset:2048
	ds_read_b128 v[150:153], v137 offset:3072
	ds_read_b128 v[154:157], v136
	ds_read_b128 v[158:161], v136 offset:1024
	ds_read_b128 v[162:165], v136 offset:2048
	ds_read_b128 v[166:169], v136 offset:3072
	ds_read_b128 v[170:173], v136 offset:4096
	ds_read_b128 v[174:177], v136 offset:5120
	ds_read_b128 v[178:181], v136 offset:6144
	ds_read_b128 v[182:185], v136 offset:7168
	v_add_u32_e32 v137, 0x14000, v135
	ds_read_b128 v[186:189], v137
	ds_read_b128 v[194:197], v137 offset:1024
	ds_read_b128 v[198:201], v137 offset:2048
	ds_read_b128 v[202:205], v137 offset:3072
	s_add_i32 s35, s34, 0x100
	s_and_b64 s[28:29], s[28:29], exec
	s_cselect_b32 s29, 0, s35
	s_cselect_b32 s28, 0, 0
	s_add_u32 s38, s12, s29
	s_addc_u32 s39, s13, s28
	s_add_i32 s47, 0, 0x10000
	s_add_u32 s40, s2, s29
	s_addc_u32 s41, s3, s28
	s_add_u32 s48, s4, s34
	s_addc_u32 s49, s5, 0
	s_add_i32 vcc_lo, s47, s52
	s_add_i32 m0, s9, 0xc000
	s_add_i32 s53, s9, 0xe000
	s_add_i32 vcc_hi, 0, 0x14000
	s_add_i32 s46, vcc_lo, 0x2000
	s_add_u32 s36, s40, 0x28000
	s_addc_u32 s37, s41, 0
	s_add_i32 s75, vcc_hi, s52
	s_add_i32 s74, s75, 0x2000
	s_add_i32 s71, 0, 0x18000
	s_add_u32 s34, s38, 0x10000
	s_addc_u32 s35, s39, 0
	s_add_i32 s69, s71, s52
	s_add_i32 s67, 0, 0x1c000
	s_add_i32 s66, s69, 0x2000
	s_add_u32 s28, s40, 0x28080
	s_addc_u32 s29, s41, 0
	s_add_i32 s79, s67, s52
	s_add_i32 s78, s79, 0x2000
	v_lshl_add_u64 v[218:219], s[48:49], 0, v[128:129]
	v_lshl_add_u64 v[222:223], v[218:219], 0, s[72:73]
	global_load_lds_dwordx4 v[222:223], off
	v_lshl_add_u64 v[222:223], s[48:49], 0, v[130:131]
	v_lshl_add_u64 v[220:221], v[222:223], 0, s[72:73]
	s_mov_b32 m0, s53
	s_nop 0
	global_load_lds_dwordx4 v[220:221], off
	s_waitcnt vmcnt(8)
	s_waitcnt lgkmcnt(0)
	s_barrier
	s_setprio 1
	v_mfma_f32_16x16x32_bf16 v[124:127], v[138:141], v[154:157], v[124:127]
	v_mfma_f32_16x16x32_bf16 v[120:123], v[146:149], v[154:157], v[120:123]
	v_mfma_f32_16x16x32_bf16 v[116:119], v[138:141], v[162:165], v[116:119]
	v_mfma_f32_16x16x32_bf16 v[108:111], v[146:149], v[162:165], v[108:111]
	v_mfma_f32_16x16x32_bf16 v[100:103], v[138:141], v[170:173], v[100:103]
	v_mfma_f32_16x16x32_bf16 v[92:95], v[146:149], v[170:173], v[92:95]
	v_mfma_f32_16x16x32_bf16 v[84:87], v[138:141], v[178:181], v[84:87]
	v_mfma_f32_16x16x32_bf16 v[76:79], v[146:149], v[178:181], v[76:79]
	v_mfma_f32_16x16x32_bf16 v[124:127], v[142:145], v[158:161], v[124:127]
	v_mfma_f32_16x16x32_bf16 v[120:123], v[150:153], v[158:161], v[120:123]
	v_mfma_f32_16x16x32_bf16 v[116:119], v[142:145], v[166:169], v[116:119]
	v_mfma_f32_16x16x32_bf16 v[108:111], v[150:153], v[166:169], v[108:111]
	v_mfma_f32_16x16x32_bf16 v[100:103], v[142:145], v[174:177], v[100:103]
	v_mfma_f32_16x16x32_bf16 v[92:95], v[150:153], v[174:177], v[92:95]
	v_mfma_f32_16x16x32_bf16 v[84:87], v[142:145], v[182:185], v[84:87]
	v_mfma_f32_16x16x32_bf16 v[76:79], v[150:153], v[182:185], v[76:79]
	v_mfma_f32_16x16x32_bf16 v[112:115], v[186:189], v[154:157], v[112:115]
	v_mfma_f32_16x16x32_bf16 v[104:107], v[198:201], v[154:157], v[104:107]
	v_mfma_f32_16x16x32_bf16 v[96:99], v[186:189], v[162:165], v[96:99]
	v_mfma_f32_16x16x32_bf16 v[88:91], v[198:201], v[162:165], v[88:91]
	v_mfma_f32_16x16x32_bf16 v[80:83], v[186:189], v[170:173], v[80:83]
	v_mfma_f32_16x16x32_bf16 v[72:75], v[198:201], v[170:173], v[72:75]
	v_mfma_f32_16x16x32_bf16 v[68:71], v[186:189], v[178:181], v[68:71]
	v_mfma_f32_16x16x32_bf16 v[64:67], v[198:201], v[178:181], v[64:67]
	v_mfma_f32_16x16x32_bf16 v[112:115], v[194:197], v[158:161], v[112:115]
	v_mfma_f32_16x16x32_bf16 v[104:107], v[202:205], v[158:161], v[104:107]
	v_mfma_f32_16x16x32_bf16 v[96:99], v[194:197], v[166:169], v[96:99]
	v_mfma_f32_16x16x32_bf16 v[88:91], v[202:205], v[166:169], v[88:91]
	v_mfma_f32_16x16x32_bf16 v[80:83], v[194:197], v[174:177], v[80:83]
	v_mfma_f32_16x16x32_bf16 v[72:75], v[202:205], v[174:177], v[72:75]
	v_mfma_f32_16x16x32_bf16 v[68:71], v[194:197], v[182:185], v[68:71]
	v_mfma_f32_16x16x32_bf16 v[64:67], v[202:205], v[182:185], v[64:67]
	s_setprio 0
	s_barrier
	ds_read_b128 v[154:157], v136 offset:16384
	ds_read_b128 v[158:161], v136 offset:17408
	ds_read_b128 v[162:165], v136 offset:18432
	ds_read_b128 v[166:169], v136 offset:19456
	ds_read_b128 v[170:173], v136 offset:20480
	ds_read_b128 v[174:177], v136 offset:21504
	ds_read_b128 v[178:181], v136 offset:22528
	ds_read_b128 v[182:185], v136 offset:23552
	s_mov_b32 m0, vcc_lo
	v_lshl_add_u64 v[190:191], s[40:41], 0, v[192:193]
	global_load_lds_dwordx4 v[190:191], off
	v_lshl_add_u64 v[206:207], s[40:41], 0, v[132:133]
	s_mov_b32 m0, s46
	s_nop 0
	global_load_lds_dwordx4 v[206:207], off
	s_mov_b32 m0, s9
	v_lshl_add_u64 v[208:209], s[38:39], 0, v[128:129]
	global_load_lds_dwordx4 v[208:209], off
	v_lshl_add_u64 v[210:211], s[38:39], 0, v[130:131]
	s_mov_b32 m0, s54
	s_nop 0
	global_load_lds_dwordx4 v[210:211], off
	s_mov_b32 m0, s75
	v_lshl_add_u64 v[218:219], s[36:37], 0, v[192:193]
	global_load_lds_dwordx4 v[218:219], off
	v_lshl_add_u64 v[220:221], s[36:37], 0, v[132:133]
	s_mov_b32 m0, s74
	s_nop 0
	global_load_lds_dwordx4 v[220:221], off
	s_waitcnt vmcnt(8)
	s_waitcnt lgkmcnt(0)
	s_barrier
	s_setprio 1
	v_mfma_f32_16x16x32_bf16 v[60:63], v[138:141], v[154:157], v[60:63]
	v_mfma_f32_16x16x32_bf16 v[56:59], v[146:149], v[154:157], v[56:59]
	v_mfma_f32_16x16x32_bf16 v[52:55], v[138:141], v[162:165], v[52:55]
	v_mfma_f32_16x16x32_bf16 v[44:47], v[146:149], v[162:165], v[44:47]
	v_mfma_f32_16x16x32_bf16 v[36:39], v[138:141], v[170:173], v[36:39]
	v_mfma_f32_16x16x32_bf16 v[28:31], v[146:149], v[170:173], v[28:31]
	v_mfma_f32_16x16x32_bf16 v[20:23], v[138:141], v[178:181], v[20:23]
	v_mfma_f32_16x16x32_bf16 v[12:15], v[146:149], v[178:181], v[12:15]
	v_mfma_f32_16x16x32_bf16 v[60:63], v[142:145], v[158:161], v[60:63]
	v_mfma_f32_16x16x32_bf16 v[56:59], v[150:153], v[158:161], v[56:59]
	v_mfma_f32_16x16x32_bf16 v[52:55], v[142:145], v[166:169], v[52:55]
	v_mfma_f32_16x16x32_bf16 v[44:47], v[150:153], v[166:169], v[44:47]
	v_mfma_f32_16x16x32_bf16 v[36:39], v[142:145], v[174:177], v[36:39]
	v_mfma_f32_16x16x32_bf16 v[28:31], v[150:153], v[174:177], v[28:31]
	v_mfma_f32_16x16x32_bf16 v[20:23], v[142:145], v[182:185], v[20:23]
	v_mfma_f32_16x16x32_bf16 v[12:15], v[150:153], v[182:185], v[12:15]
	v_mfma_f32_16x16x32_bf16 v[48:51], v[186:189], v[154:157], v[48:51]
	v_mfma_f32_16x16x32_bf16 v[40:43], v[198:201], v[154:157], v[40:43]
	v_mfma_f32_16x16x32_bf16 v[32:35], v[186:189], v[162:165], v[32:35]
	v_mfma_f32_16x16x32_bf16 v[24:27], v[198:201], v[162:165], v[24:27]
	v_mfma_f32_16x16x32_bf16 v[16:19], v[186:189], v[170:173], v[16:19]
	v_mfma_f32_16x16x32_bf16 v[8:11], v[198:201], v[170:173], v[8:11]
	v_mfma_f32_16x16x32_bf16 v[4:7], v[186:189], v[178:181], v[4:7]
	v_mfma_f32_16x16x32_bf16 v[0:3], v[198:201], v[178:181], v[0:3]
	v_mfma_f32_16x16x32_bf16 v[48:51], v[194:197], v[158:161], v[48:51]
	v_mfma_f32_16x16x32_bf16 v[40:43], v[202:205], v[158:161], v[40:43]
	v_mfma_f32_16x16x32_bf16 v[32:35], v[194:197], v[166:169], v[32:35]
	v_mfma_f32_16x16x32_bf16 v[24:27], v[202:205], v[166:169], v[24:27]
	v_mfma_f32_16x16x32_bf16 v[16:19], v[194:197], v[174:177], v[16:19]
	v_mfma_f32_16x16x32_bf16 v[8:11], v[202:205], v[174:177], v[8:11]
	v_mfma_f32_16x16x32_bf16 v[4:7], v[194:197], v[182:185], v[4:7]
	v_mfma_f32_16x16x32_bf16 v[0:3], v[202:205], v[182:185], v[0:3]
	s_setprio 0
	s_barrier
	v_add_u32_e32 v137, 0x18000, v135
	ds_read_b128 v[138:141], v137
	ds_read_b128 v[142:145], v137 offset:1024
	ds_read_b128 v[146:149], v137 offset:2048
	ds_read_b128 v[150:153], v137 offset:3072
	ds_read_b128 v[154:157], v136 offset:32768
	ds_read_b128 v[158:161], v136 offset:33792
	ds_read_b128 v[162:165], v136 offset:34816
	ds_read_b128 v[166:169], v136 offset:35840
	ds_read_b128 v[170:173], v136 offset:36864
	ds_read_b128 v[174:177], v136 offset:37888
	ds_read_b128 v[178:181], v136 offset:38912
	ds_read_b128 v[182:185], v136 offset:39936
	v_add_u32_e32 v137, 0x1c000, v135
	ds_read_b128 v[186:189], v137
	ds_read_b128 v[194:197], v137 offset:1024
	ds_read_b128 v[198:201], v137 offset:2048
	ds_read_b128 v[202:205], v137 offset:3072
	s_mov_b32 m0, s55
	v_lshl_add_u64 v[218:219], s[34:35], 0, v[128:129]
	global_load_lds_dwordx4 v[218:219], off
	v_lshl_add_u64 v[220:221], s[34:35], 0, v[130:131]
	s_mov_b32 m0, s58
	s_nop 0
	global_load_lds_dwordx4 v[220:221], off
	s_waitcnt vmcnt(8)
	s_waitcnt lgkmcnt(0)
	s_barrier
	s_setprio 1
	v_mfma_f32_16x16x32_bf16 v[124:127], v[138:141], v[154:157], v[124:127]
	v_mfma_f32_16x16x32_bf16 v[120:123], v[146:149], v[154:157], v[120:123]
	v_mfma_f32_16x16x32_bf16 v[116:119], v[138:141], v[162:165], v[116:119]
	v_mfma_f32_16x16x32_bf16 v[108:111], v[146:149], v[162:165], v[108:111]
	v_mfma_f32_16x16x32_bf16 v[100:103], v[138:141], v[170:173], v[100:103]
	v_mfma_f32_16x16x32_bf16 v[92:95], v[146:149], v[170:173], v[92:95]
	v_mfma_f32_16x16x32_bf16 v[84:87], v[138:141], v[178:181], v[84:87]
	v_mfma_f32_16x16x32_bf16 v[76:79], v[146:149], v[178:181], v[76:79]
	v_mfma_f32_16x16x32_bf16 v[124:127], v[142:145], v[158:161], v[124:127]
	v_mfma_f32_16x16x32_bf16 v[120:123], v[150:153], v[158:161], v[120:123]
	v_mfma_f32_16x16x32_bf16 v[116:119], v[142:145], v[166:169], v[116:119]
	v_mfma_f32_16x16x32_bf16 v[108:111], v[150:153], v[166:169], v[108:111]
	v_mfma_f32_16x16x32_bf16 v[100:103], v[142:145], v[174:177], v[100:103]
	v_mfma_f32_16x16x32_bf16 v[92:95], v[150:153], v[174:177], v[92:95]
	v_mfma_f32_16x16x32_bf16 v[84:87], v[142:145], v[182:185], v[84:87]
	v_mfma_f32_16x16x32_bf16 v[76:79], v[150:153], v[182:185], v[76:79]
	v_mfma_f32_16x16x32_bf16 v[112:115], v[186:189], v[154:157], v[112:115]
	v_mfma_f32_16x16x32_bf16 v[104:107], v[198:201], v[154:157], v[104:107]
	v_mfma_f32_16x16x32_bf16 v[96:99], v[186:189], v[162:165], v[96:99]
	v_mfma_f32_16x16x32_bf16 v[88:91], v[198:201], v[162:165], v[88:91]
	v_mfma_f32_16x16x32_bf16 v[80:83], v[186:189], v[170:173], v[80:83]
	v_mfma_f32_16x16x32_bf16 v[72:75], v[198:201], v[170:173], v[72:75]
	v_mfma_f32_16x16x32_bf16 v[68:71], v[186:189], v[178:181], v[68:71]
	v_mfma_f32_16x16x32_bf16 v[64:67], v[198:201], v[178:181], v[64:67]
	v_mfma_f32_16x16x32_bf16 v[112:115], v[194:197], v[158:161], v[112:115]
	v_mfma_f32_16x16x32_bf16 v[104:107], v[202:205], v[158:161], v[104:107]
	v_mfma_f32_16x16x32_bf16 v[96:99], v[194:197], v[166:169], v[96:99]
	v_mfma_f32_16x16x32_bf16 v[88:91], v[202:205], v[166:169], v[88:91]
	v_mfma_f32_16x16x32_bf16 v[80:83], v[194:197], v[174:177], v[80:83]
	v_mfma_f32_16x16x32_bf16 v[72:75], v[202:205], v[174:177], v[72:75]
	v_mfma_f32_16x16x32_bf16 v[68:71], v[194:197], v[182:185], v[68:71]
	v_mfma_f32_16x16x32_bf16 v[64:67], v[202:205], v[182:185], v[64:67]
	s_setprio 0
	s_barrier
	ds_read_b128 v[154:157], v136 offset:49152
	ds_read_b128 v[158:161], v136 offset:50176
	ds_read_b128 v[162:165], v136 offset:51200
	ds_read_b128 v[166:169], v136 offset:52224
	ds_read_b128 v[170:173], v136 offset:53248
	ds_read_b128 v[174:177], v136 offset:54272
	ds_read_b128 v[178:181], v136 offset:55296
	ds_read_b128 v[182:185], v136 offset:56320
	s_mov_b32 m0, s69
	v_lshl_add_u64 v[190:191], v[190:191], 0, s[72:73]
	global_load_lds_dwordx4 v[190:191], off
	v_lshl_add_u64 v[190:191], v[206:207], 0, s[72:73]
	s_mov_b32 m0, s66
	s_nop 0
	global_load_lds_dwordx4 v[190:191], off
	s_mov_b32 m0, s59
	v_lshl_add_u64 v[190:191], v[208:209], 0, s[72:73]
	global_load_lds_dwordx4 v[190:191], off
	v_lshl_add_u64 v[190:191], v[210:211], 0, s[72:73]
	s_mov_b32 m0, s62
	s_nop 0
	global_load_lds_dwordx4 v[190:191], off
	s_mov_b32 m0, s79
	v_lshl_add_u64 v[218:219], s[28:29], 0, v[192:193]
	global_load_lds_dwordx4 v[218:219], off
	v_lshl_add_u64 v[220:221], s[28:29], 0, v[132:133]
	s_mov_b32 m0, s78
	s_nop 0
	global_load_lds_dwordx4 v[220:221], off
	s_waitcnt vmcnt(8)
	s_waitcnt lgkmcnt(0)
	s_barrier
	s_setprio 1
	v_mfma_f32_16x16x32_bf16 v[60:63], v[138:141], v[154:157], v[60:63]
	v_mfma_f32_16x16x32_bf16 v[56:59], v[146:149], v[154:157], v[56:59]
	v_mfma_f32_16x16x32_bf16 v[52:55], v[138:141], v[162:165], v[52:55]
	v_mfma_f32_16x16x32_bf16 v[44:47], v[146:149], v[162:165], v[44:47]
	v_mfma_f32_16x16x32_bf16 v[36:39], v[138:141], v[170:173], v[36:39]
	v_mfma_f32_16x16x32_bf16 v[28:31], v[146:149], v[170:173], v[28:31]
	v_mfma_f32_16x16x32_bf16 v[20:23], v[138:141], v[178:181], v[20:23]
	v_mfma_f32_16x16x32_bf16 v[12:15], v[146:149], v[178:181], v[12:15]
	v_mfma_f32_16x16x32_bf16 v[60:63], v[142:145], v[158:161], v[60:63]
	v_mfma_f32_16x16x32_bf16 v[56:59], v[150:153], v[158:161], v[56:59]
	v_mfma_f32_16x16x32_bf16 v[52:55], v[142:145], v[166:169], v[52:55]
	v_mfma_f32_16x16x32_bf16 v[44:47], v[150:153], v[166:169], v[44:47]
	v_mfma_f32_16x16x32_bf16 v[36:39], v[142:145], v[174:177], v[36:39]
	v_mfma_f32_16x16x32_bf16 v[28:31], v[150:153], v[174:177], v[28:31]
	v_mfma_f32_16x16x32_bf16 v[20:23], v[142:145], v[182:185], v[20:23]
	v_mfma_f32_16x16x32_bf16 v[12:15], v[150:153], v[182:185], v[12:15]
	v_mfma_f32_16x16x32_bf16 v[48:51], v[186:189], v[154:157], v[48:51]
	v_mfma_f32_16x16x32_bf16 v[40:43], v[198:201], v[154:157], v[40:43]
	v_mfma_f32_16x16x32_bf16 v[32:35], v[186:189], v[162:165], v[32:35]
	v_mfma_f32_16x16x32_bf16 v[24:27], v[198:201], v[162:165], v[24:27]
	v_mfma_f32_16x16x32_bf16 v[16:19], v[186:189], v[170:173], v[16:19]
	v_mfma_f32_16x16x32_bf16 v[8:11], v[198:201], v[170:173], v[8:11]
	v_mfma_f32_16x16x32_bf16 v[4:7], v[186:189], v[178:181], v[4:7]
	v_mfma_f32_16x16x32_bf16 v[0:3], v[198:201], v[178:181], v[0:3]
	v_mfma_f32_16x16x32_bf16 v[48:51], v[194:197], v[158:161], v[48:51]
	v_mfma_f32_16x16x32_bf16 v[40:43], v[202:205], v[158:161], v[40:43]
	v_mfma_f32_16x16x32_bf16 v[32:35], v[194:197], v[166:169], v[32:35]
	v_mfma_f32_16x16x32_bf16 v[24:27], v[202:205], v[166:169], v[24:27]
	v_mfma_f32_16x16x32_bf16 v[16:19], v[194:197], v[174:177], v[16:19]
	v_mfma_f32_16x16x32_bf16 v[8:11], v[202:205], v[174:177], v[8:11]
	v_mfma_f32_16x16x32_bf16 v[4:7], v[194:197], v[182:185], v[4:7]
	v_mfma_f32_16x16x32_bf16 v[0:3], v[202:205], v[182:185], v[0:3]
	s_setprio 0
	s_andn2_b64 vcc, exec, s[14:15]
	s_mov_b64 s[28:29], -1
	s_mov_b64 s[14:15], 0
	s_movk_i32 s34, 0x100
	s_barrier
	s_cbranch_vccz .LBB0_99
	s_mul_i32 s2, s10, 0x1400000
	s_mul_hi_i32 s3, s10, 0x1400000
	s_add_u32 s2, s26, s2
	v_and_b32_e32 v128, 63, v134
	s_addc_u32 s3, s27, s3
	v_mov_b32 v128, v128
	s_add_i32 s63, s63, s51
	v_and_or_b32 v130, v128, 15, s63
	s_lshl_b32 s4, s50, 8
	v_ashrrev_i32_e32 v128, 1, v128
	s_or_b32 s4, s64, s4
	v_and_b32_e32 v128, -8, v128
	v_add_u32_e32 v128, s4, v128
	v_ashrrev_i32_e32 v131, 31, v130
	v_ashrrev_i32_e32 v129, 31, v128
	v_lshlrev_b64 v[132:133], 12, v[130:131]
	v_lshl_add_u64 v[132:133], s[2:3], 0, v[132:133]
	v_lshlrev_b64 v[134:135], 1, v[128:129]
	v_lshl_add_u64 v[128:129], v[132:133], 0, v[134:135]
	v_cvt_pk_bf16_f32 v124, v124, v125
	v_cvt_pk_bf16_f32 v125, v126, v127
	v_cvt_pk_bf16_f32 v126, v120, v121
	v_cvt_pk_bf16_f32 v127, v122, v123
	global_store_dwordx4 v[128:129], v[124:127], off
	v_cvt_pk_bf16_f32 v112, v112, v113
	v_cvt_pk_bf16_f32 v113, v114, v115
	v_cvt_pk_bf16_f32 v114, v104, v105
	v_or_b32_e32 v104, 16, v130
	v_ashrrev_i32_e32 v105, 31, v104
	v_lshlrev_b64 v[104:105], 12, v[104:105]
	v_lshl_add_u64 v[104:105], s[2:3], 0, v[104:105]
	v_cvt_pk_bf16_f32 v115, v106, v107
	global_store_dwordx4 v[128:129], v[112:115], off offset:256
	s_cmpk_lt_u32 s11, 0x100
	s_nop 0
	v_lshl_add_u64 v[112:113], v[104:105], 0, v[134:135]
	v_cvt_pk_bf16_f32 v104, v116, v117
	v_cvt_pk_bf16_f32 v105, v118, v119
	v_cvt_pk_bf16_f32 v106, v108, v109
	v_cvt_pk_bf16_f32 v107, v110, v111
	global_store_dwordx4 v[112:113], v[104:107], off
	v_cvt_pk_bf16_f32 v96, v96, v97
	v_cvt_pk_bf16_f32 v97, v98, v99
	v_cvt_pk_bf16_f32 v98, v88, v89
	v_or_b32_e32 v88, 32, v130
	v_ashrrev_i32_e32 v89, 31, v88
	v_lshlrev_b64 v[88:89], 12, v[88:89]
	v_lshl_add_u64 v[88:89], s[2:3], 0, v[88:89]
	v_cvt_pk_bf16_f32 v99, v90, v91
	global_store_dwordx4 v[112:113], v[96:99], off offset:256
	s_nop 1
	v_lshl_add_u64 v[96:97], v[88:89], 0, v[134:135]
	v_cvt_pk_bf16_f32 v88, v100, v101
	v_cvt_pk_bf16_f32 v89, v102, v103
	v_cvt_pk_bf16_f32 v90, v92, v93
	v_cvt_pk_bf16_f32 v91, v94, v95
	global_store_dwordx4 v[96:97], v[88:91], off
	v_cvt_pk_bf16_f32 v80, v80, v81
	v_cvt_pk_bf16_f32 v81, v82, v83
	v_cvt_pk_bf16_f32 v82, v72, v73
	v_or_b32_e32 v72, 48, v130
	v_ashrrev_i32_e32 v73, 31, v72
	v_lshlrev_b64 v[72:73], 12, v[72:73]
	v_lshl_add_u64 v[72:73], s[2:3], 0, v[72:73]
	v_cvt_pk_bf16_f32 v83, v74, v75
	global_store_dwordx4 v[96:97], v[80:83], off offset:256
	s_mov_b64 s[2:3], 0x80000
	s_nop 0
	v_lshl_add_u64 v[80:81], v[72:73], 0, v[134:135]
	v_cvt_pk_bf16_f32 v72, v84, v85
	v_cvt_pk_bf16_f32 v73, v86, v87
	v_cvt_pk_bf16_f32 v74, v76, v77
	v_cvt_pk_bf16_f32 v75, v78, v79
	global_store_dwordx4 v[80:81], v[72:75], off
	v_cvt_pk_bf16_f32 v68, v68, v69
	v_cvt_pk_bf16_f32 v69, v70, v71
	v_cvt_pk_bf16_f32 v70, v64, v65
	v_lshl_add_u64 v[64:65], v[128:129], 0, s[2:3]
	s_mov_b32 s2, 0x80000
	v_cvt_pk_bf16_f32 v71, v66, v67
	global_store_dwordx4 v[80:81], v[68:71], off offset:256
	v_cvt_pk_bf16_f32 v60, v60, v61
	v_cvt_pk_bf16_f32 v61, v62, v63
	v_cvt_pk_bf16_f32 v62, v56, v57
	v_add_co_u32_e32 v56, vcc, s2, v128
	v_cvt_pk_bf16_f32 v63, v58, v59
	s_mov_b64 s[2:3], 0x90000
	s_nop 0
	v_addc_co_u32_e32 v57, vcc, 0, v129, vcc
	global_store_dwordx4 v[56:57], v[60:63], off
	v_cvt_pk_bf16_f32 v48, v48, v49
	v_cvt_pk_bf16_f32 v49, v50, v51
	v_cvt_pk_bf16_f32 v50, v40, v41
	v_cvt_pk_bf16_f32 v51, v42, v43
	global_store_dwordx4 v[64:65], v[48:51], off offset:256
	v_cvt_pk_bf16_f32 v40, v52, v53
	v_cvt_pk_bf16_f32 v41, v54, v55
	v_cvt_pk_bf16_f32 v42, v44, v45
	v_cvt_pk_bf16_f32 v43, v46, v47
	s_nop 1
	v_lshl_add_u64 v[48:49], v[128:129], 0, s[2:3]
	s_mov_b32 s2, 0x90000
	v_add_co_u32_e32 v44, vcc, s2, v128
	s_mov_b64 s[2:3], 0xa0000
	s_nop 0
	v_addc_co_u32_e32 v45, vcc, 0, v129, vcc
	global_store_dwordx4 v[44:45], v[40:43], off
	v_cvt_pk_bf16_f32 v32, v32, v33
	v_cvt_pk_bf16_f32 v33, v34, v35
	v_cvt_pk_bf16_f32 v34, v24, v25
	v_cvt_pk_bf16_f32 v35, v26, v27
	global_store_dwordx4 v[48:49], v[32:35], off offset:256
	v_cvt_pk_bf16_f32 v24, v36, v37
	v_cvt_pk_bf16_f32 v25, v38, v39
	v_cvt_pk_bf16_f32 v26, v28, v29
	v_cvt_pk_bf16_f32 v27, v30, v31
	s_nop 1
	v_lshl_add_u64 v[32:33], v[128:129], 0, s[2:3]
	s_mov_b32 s2, 0xa0000
	v_add_co_u32_e32 v28, vcc, s2, v128
	s_mov_b64 s[2:3], 0xb0000
	s_nop 0
	v_addc_co_u32_e32 v29, vcc, 0, v129, vcc
	global_store_dwordx4 v[28:29], v[24:27], off
	v_cvt_pk_bf16_f32 v16, v16, v17
	v_cvt_pk_bf16_f32 v17, v18, v19
	v_cvt_pk_bf16_f32 v18, v8, v9
	v_cvt_pk_bf16_f32 v19, v10, v11
	global_store_dwordx4 v[32:33], v[16:19], off offset:256
	v_cvt_pk_bf16_f32 v8, v20, v21
	v_cvt_pk_bf16_f32 v9, v22, v23
	v_cvt_pk_bf16_f32 v10, v12, v13
	v_cvt_pk_bf16_f32 v11, v14, v15
	s_nop 1
	v_lshl_add_u64 v[16:17], v[128:129], 0, s[2:3]
	s_mov_b32 s2, 0xb0000
	v_add_co_u32_e32 v12, vcc, s2, v128
	s_nop 1
	v_addc_co_u32_e32 v13, vcc, 0, v129, vcc
	global_store_dwordx4 v[12:13], v[8:11], off
	v_cvt_pk_bf16_f32 v4, v4, v5
	v_cvt_pk_bf16_f32 v5, v6, v7
	v_cvt_pk_bf16_f32 v6, v0, v1
	v_cvt_pk_bf16_f32 v7, v2, v3
	global_store_dwordx4 v[16:17], v[4:7], off offset:256
	s_waitcnt vmcnt(0)
	s_cbranch_scc0 .LBB0_95
	s_barrier
	s_branch .LBB0_95

.LBB0_106:
	v_add_u32_e32 v141, 0x10000, v139
	ds_read_b128 v[142:145], v141
	ds_read_b128 v[146:149], v141 offset:1024
	ds_read_b128 v[150:153], v141 offset:2048
	ds_read_b128 v[154:157], v141 offset:3072
	ds_read_b128 v[158:161], v140
	ds_read_b128 v[162:165], v140 offset:1024
	ds_read_b128 v[166:169], v140 offset:2048
	ds_read_b128 v[170:173], v140 offset:3072
	ds_read_b128 v[174:177], v140 offset:4096
	ds_read_b128 v[178:181], v140 offset:5120
	ds_read_b128 v[182:185], v140 offset:6144
	ds_read_b128 v[186:189], v140 offset:7168
	v_add_u32_e32 v141, 0x14000, v139
	ds_read_b128 v[194:197], v141
	ds_read_b128 v[198:201], v141 offset:1024
	ds_read_b128 v[202:205], v141 offset:2048
	ds_read_b128 v[206:209], v141 offset:3072
	s_add_u32 s4, s2, 0x100
	s_addc_u32 s5, s3, 0
	s_cmp_lg_u32 s54, 4
	s_cselect_b32 s28, s4, 0
	s_cselect_b32 s9, s5, 0
	s_add_u32 s34, s12, s28
	s_addc_u32 s35, s13, s9
	s_add_i32 s46, 0, 0x10000
	s_add_u32 s28, s14, s28
	s_addc_u32 s29, s15, s9
	v_lshl_add_u64 v[190:191], v[134:135], 0, s[2:3]
	s_add_i32 m0, s40, 0xc000
	s_nop 0
	global_load_lds_dwordx4 v[190:191], off
	v_lshl_add_u64 v[190:191], v[136:137], 0, s[2:3]
	s_add_i32 m0, s40, 0xe000
	s_nop 0
	global_load_lds_dwordx4 v[190:191], off
	s_waitcnt vmcnt(8)
	s_waitcnt lgkmcnt(0)
	s_barrier
	s_setprio 1
	v_mfma_f32_16x16x32_bf16 v[124:127], v[142:145], v[158:161], v[124:127]
	v_mfma_f32_16x16x32_bf16 v[120:123], v[150:153], v[158:161], v[120:123]
	v_mfma_f32_16x16x32_bf16 v[116:119], v[142:145], v[166:169], v[116:119]
	v_mfma_f32_16x16x32_bf16 v[108:111], v[150:153], v[166:169], v[108:111]
	v_mfma_f32_16x16x32_bf16 v[100:103], v[142:145], v[174:177], v[100:103]
	v_mfma_f32_16x16x32_bf16 v[92:95], v[150:153], v[174:177], v[92:95]
	v_mfma_f32_16x16x32_bf16 v[84:87], v[142:145], v[182:185], v[84:87]
	v_mfma_f32_16x16x32_bf16 v[76:79], v[150:153], v[182:185], v[76:79]
	v_mfma_f32_16x16x32_bf16 v[124:127], v[146:149], v[162:165], v[124:127]
	v_mfma_f32_16x16x32_bf16 v[120:123], v[154:157], v[162:165], v[120:123]
	v_mfma_f32_16x16x32_bf16 v[116:119], v[146:149], v[170:173], v[116:119]
	v_mfma_f32_16x16x32_bf16 v[108:111], v[154:157], v[170:173], v[108:111]
	v_mfma_f32_16x16x32_bf16 v[100:103], v[146:149], v[178:181], v[100:103]
	v_mfma_f32_16x16x32_bf16 v[92:95], v[154:157], v[178:181], v[92:95]
	v_mfma_f32_16x16x32_bf16 v[84:87], v[146:149], v[186:189], v[84:87]
	v_mfma_f32_16x16x32_bf16 v[76:79], v[154:157], v[186:189], v[76:79]
	v_mfma_f32_16x16x32_bf16 v[112:115], v[194:197], v[158:161], v[112:115]
	v_mfma_f32_16x16x32_bf16 v[104:107], v[202:205], v[158:161], v[104:107]
	v_mfma_f32_16x16x32_bf16 v[96:99], v[194:197], v[166:169], v[96:99]
	v_mfma_f32_16x16x32_bf16 v[88:91], v[202:205], v[166:169], v[88:91]
	v_mfma_f32_16x16x32_bf16 v[80:83], v[194:197], v[174:177], v[80:83]
	v_mfma_f32_16x16x32_bf16 v[72:75], v[202:205], v[174:177], v[72:75]
	v_mfma_f32_16x16x32_bf16 v[68:71], v[194:197], v[182:185], v[68:71]
	v_mfma_f32_16x16x32_bf16 v[64:67], v[202:205], v[182:185], v[64:67]
	v_mfma_f32_16x16x32_bf16 v[112:115], v[198:201], v[162:165], v[112:115]
	v_mfma_f32_16x16x32_bf16 v[104:107], v[206:209], v[162:165], v[104:107]
	v_mfma_f32_16x16x32_bf16 v[96:99], v[198:201], v[170:173], v[96:99]
	v_mfma_f32_16x16x32_bf16 v[88:91], v[206:209], v[170:173], v[88:91]
	v_mfma_f32_16x16x32_bf16 v[80:83], v[198:201], v[178:181], v[80:83]
	v_mfma_f32_16x16x32_bf16 v[72:75], v[206:209], v[178:181], v[72:75]
	v_mfma_f32_16x16x32_bf16 v[68:71], v[198:201], v[186:189], v[68:71]
	v_mfma_f32_16x16x32_bf16 v[64:67], v[206:209], v[186:189], v[64:67]
	s_setprio 0
	s_barrier
	ds_read_b128 v[158:161], v140 offset:16384
	ds_read_b128 v[162:165], v140 offset:17408
	ds_read_b128 v[166:169], v140 offset:18432
	ds_read_b128 v[170:173], v140 offset:19456
	ds_read_b128 v[174:177], v140 offset:20480
	ds_read_b128 v[178:181], v140 offset:21504
	ds_read_b128 v[182:185], v140 offset:22528
	ds_read_b128 v[186:189], v140 offset:23552
	s_add_i32 s9, 0, 0x14000
	s_add_i32 s2, s46, s39
	v_lshl_add_u64 v[190:191], s[28:29], 0, v[192:193]
	s_mov_b32 m0, s2
	s_nop 0
	global_load_lds_dwordx4 v[190:191], off
	v_lshl_add_u64 v[210:211], s[28:29], 0, v[132:133]
	s_add_i32 m0, s2, 0x2000
	s_nop 0
	global_load_lds_dwordx4 v[210:211], off
	s_mov_b32 m0, s40
	v_lshl_add_u64 v[212:213], s[34:35], 0, v[128:129]
	global_load_lds_dwordx4 v[212:213], off
	v_lshl_add_u64 v[214:215], s[34:35], 0, v[130:131]
	s_mov_b32 m0, s41
	s_nop 0
	global_load_lds_dwordx4 v[214:215], off
	s_add_u32 s2, s28, 0x20000
	s_addc_u32 s3, s29, 0
	s_add_i32 s9, s9, s39
	v_lshl_add_u64 v[218:219], s[2:3], 0, v[192:193]
	s_mov_b32 m0, s9
	s_nop 0
	global_load_lds_dwordx4 v[218:219], off
	v_lshl_add_u64 v[220:221], s[2:3], 0, v[132:133]
	s_add_i32 m0, s9, 0x2000
	s_nop 0
	global_load_lds_dwordx4 v[220:221], off
	s_waitcnt vmcnt(8)
	s_waitcnt lgkmcnt(0)
	s_barrier
	s_setprio 1
	v_mfma_f32_16x16x32_bf16 v[60:63], v[142:145], v[158:161], v[60:63]
	v_mfma_f32_16x16x32_bf16 v[56:59], v[150:153], v[158:161], v[56:59]
	v_mfma_f32_16x16x32_bf16 v[52:55], v[142:145], v[166:169], v[52:55]
	v_mfma_f32_16x16x32_bf16 v[44:47], v[150:153], v[166:169], v[44:47]
	v_mfma_f32_16x16x32_bf16 v[36:39], v[142:145], v[174:177], v[36:39]
	v_mfma_f32_16x16x32_bf16 v[28:31], v[150:153], v[174:177], v[28:31]
	v_mfma_f32_16x16x32_bf16 v[20:23], v[142:145], v[182:185], v[20:23]
	v_mfma_f32_16x16x32_bf16 v[12:15], v[150:153], v[182:185], v[12:15]
	v_mfma_f32_16x16x32_bf16 v[60:63], v[146:149], v[162:165], v[60:63]
	v_mfma_f32_16x16x32_bf16 v[56:59], v[154:157], v[162:165], v[56:59]
	v_mfma_f32_16x16x32_bf16 v[52:55], v[146:149], v[170:173], v[52:55]
	v_mfma_f32_16x16x32_bf16 v[44:47], v[154:157], v[170:173], v[44:47]
	v_mfma_f32_16x16x32_bf16 v[36:39], v[146:149], v[178:181], v[36:39]
	v_mfma_f32_16x16x32_bf16 v[28:31], v[154:157], v[178:181], v[28:31]
	v_mfma_f32_16x16x32_bf16 v[20:23], v[146:149], v[186:189], v[20:23]
	v_mfma_f32_16x16x32_bf16 v[12:15], v[154:157], v[186:189], v[12:15]
	v_mfma_f32_16x16x32_bf16 v[48:51], v[194:197], v[158:161], v[48:51]
	v_mfma_f32_16x16x32_bf16 v[40:43], v[202:205], v[158:161], v[40:43]
	v_mfma_f32_16x16x32_bf16 v[32:35], v[194:197], v[166:169], v[32:35]
	v_mfma_f32_16x16x32_bf16 v[24:27], v[202:205], v[166:169], v[24:27]
	v_mfma_f32_16x16x32_bf16 v[16:19], v[194:197], v[174:177], v[16:19]
	v_mfma_f32_16x16x32_bf16 v[8:11], v[202:205], v[174:177], v[8:11]
	v_mfma_f32_16x16x32_bf16 v[4:7], v[194:197], v[182:185], v[4:7]
	v_mfma_f32_16x16x32_bf16 v[0:3], v[202:205], v[182:185], v[0:3]
	v_mfma_f32_16x16x32_bf16 v[48:51], v[198:201], v[162:165], v[48:51]
	v_mfma_f32_16x16x32_bf16 v[40:43], v[206:209], v[162:165], v[40:43]
	v_mfma_f32_16x16x32_bf16 v[32:35], v[198:201], v[170:173], v[32:35]
	v_mfma_f32_16x16x32_bf16 v[24:27], v[206:209], v[170:173], v[24:27]
	v_mfma_f32_16x16x32_bf16 v[16:19], v[198:201], v[178:181], v[16:19]
	v_mfma_f32_16x16x32_bf16 v[8:11], v[206:209], v[178:181], v[8:11]
	v_mfma_f32_16x16x32_bf16 v[4:7], v[198:201], v[186:189], v[4:7]
	v_mfma_f32_16x16x32_bf16 v[0:3], v[206:209], v[186:189], v[0:3]
	s_setprio 0
	s_barrier
	v_add_u32_e32 v141, 0x18000, v139
	ds_read_b128 v[142:145], v141
	ds_read_b128 v[146:149], v141 offset:1024
	ds_read_b128 v[150:153], v141 offset:2048
	ds_read_b128 v[154:157], v141 offset:3072
	ds_read_b128 v[158:161], v140 offset:32768
	ds_read_b128 v[162:165], v140 offset:33792
	ds_read_b128 v[166:169], v140 offset:34816
	ds_read_b128 v[170:173], v140 offset:35840
	ds_read_b128 v[174:177], v140 offset:36864
	ds_read_b128 v[178:181], v140 offset:37888
	ds_read_b128 v[182:185], v140 offset:38912
	ds_read_b128 v[186:189], v140 offset:39936
	v_add_u32_e32 v141, 0x1c000, v139
	ds_read_b128 v[194:197], v141
	ds_read_b128 v[198:201], v141 offset:1024
	ds_read_b128 v[202:205], v141 offset:2048
	ds_read_b128 v[206:209], v141 offset:3072
	s_add_i32 s9, 0, 0x18000
	s_add_u32 s2, s34, 0x20000
	s_addc_u32 s3, s35, 0
	s_mov_b32 m0, s48
	v_lshl_add_u64 v[218:219], s[2:3], 0, v[128:129]
	global_load_lds_dwordx4 v[218:219], off
	v_lshl_add_u64 v[220:221], s[2:3], 0, v[130:131]
	s_mov_b32 m0, s49
	s_nop 0
	global_load_lds_dwordx4 v[220:221], off
	s_waitcnt vmcnt(8)
	s_waitcnt lgkmcnt(0)
	s_barrier
	s_setprio 1
	v_mfma_f32_16x16x32_bf16 v[124:127], v[142:145], v[158:161], v[124:127]
	v_mfma_f32_16x16x32_bf16 v[120:123], v[150:153], v[158:161], v[120:123]
	v_mfma_f32_16x16x32_bf16 v[116:119], v[142:145], v[166:169], v[116:119]
	v_mfma_f32_16x16x32_bf16 v[108:111], v[150:153], v[166:169], v[108:111]
	v_mfma_f32_16x16x32_bf16 v[100:103], v[142:145], v[174:177], v[100:103]
	v_mfma_f32_16x16x32_bf16 v[92:95], v[150:153], v[174:177], v[92:95]
	v_mfma_f32_16x16x32_bf16 v[84:87], v[142:145], v[182:185], v[84:87]
	v_mfma_f32_16x16x32_bf16 v[76:79], v[150:153], v[182:185], v[76:79]
	v_mfma_f32_16x16x32_bf16 v[124:127], v[146:149], v[162:165], v[124:127]
	v_mfma_f32_16x16x32_bf16 v[120:123], v[154:157], v[162:165], v[120:123]
	v_mfma_f32_16x16x32_bf16 v[116:119], v[146:149], v[170:173], v[116:119]
	v_mfma_f32_16x16x32_bf16 v[108:111], v[154:157], v[170:173], v[108:111]
	v_mfma_f32_16x16x32_bf16 v[100:103], v[146:149], v[178:181], v[100:103]
	v_mfma_f32_16x16x32_bf16 v[92:95], v[154:157], v[178:181], v[92:95]
	v_mfma_f32_16x16x32_bf16 v[84:87], v[146:149], v[186:189], v[84:87]
	v_mfma_f32_16x16x32_bf16 v[76:79], v[154:157], v[186:189], v[76:79]
	v_mfma_f32_16x16x32_bf16 v[112:115], v[194:197], v[158:161], v[112:115]
	v_mfma_f32_16x16x32_bf16 v[104:107], v[202:205], v[158:161], v[104:107]
	v_mfma_f32_16x16x32_bf16 v[96:99], v[194:197], v[166:169], v[96:99]
	v_mfma_f32_16x16x32_bf16 v[88:91], v[202:205], v[166:169], v[88:91]
	v_mfma_f32_16x16x32_bf16 v[80:83], v[194:197], v[174:177], v[80:83]
	v_mfma_f32_16x16x32_bf16 v[72:75], v[202:205], v[174:177], v[72:75]
	v_mfma_f32_16x16x32_bf16 v[68:71], v[194:197], v[182:185], v[68:71]
	v_mfma_f32_16x16x32_bf16 v[64:67], v[202:205], v[182:185], v[64:67]
	v_mfma_f32_16x16x32_bf16 v[112:115], v[198:201], v[162:165], v[112:115]
	v_mfma_f32_16x16x32_bf16 v[104:107], v[206:209], v[162:165], v[104:107]
	v_mfma_f32_16x16x32_bf16 v[96:99], v[198:201], v[170:173], v[96:99]
	v_mfma_f32_16x16x32_bf16 v[88:91], v[206:209], v[170:173], v[88:91]
	v_mfma_f32_16x16x32_bf16 v[80:83], v[198:201], v[178:181], v[80:83]
	v_mfma_f32_16x16x32_bf16 v[72:75], v[206:209], v[178:181], v[72:75]
	v_mfma_f32_16x16x32_bf16 v[68:71], v[198:201], v[186:189], v[68:71]
	v_mfma_f32_16x16x32_bf16 v[64:67], v[206:209], v[186:189], v[64:67]
	s_setprio 0
	s_barrier
	ds_read_b128 v[158:161], v140 offset:49152
	ds_read_b128 v[162:165], v140 offset:50176
	ds_read_b128 v[166:169], v140 offset:51200
	ds_read_b128 v[170:173], v140 offset:52224
	ds_read_b128 v[174:177], v140 offset:53248
	ds_read_b128 v[178:181], v140 offset:54272
	ds_read_b128 v[182:185], v140 offset:55296
	ds_read_b128 v[186:189], v140 offset:56320
	s_add_i32 s34, 0, 0x1c000
	s_add_i32 s2, s9, s39
	v_lshl_add_u64 v[190:191], v[190:191], 0, s[72:73]
	s_mov_b32 m0, s2
	s_nop 0
	global_load_lds_dwordx4 v[190:191], off
	v_lshl_add_u64 v[190:191], v[210:211], 0, s[72:73]
	s_add_i32 m0, s2, 0x2000
	s_nop 0
	global_load_lds_dwordx4 v[190:191], off
	s_mov_b32 m0, s50
	v_lshl_add_u64 v[190:191], v[212:213], 0, s[72:73]
	global_load_lds_dwordx4 v[190:191], off
	v_lshl_add_u64 v[190:191], v[214:215], 0, s[72:73]
	s_mov_b32 m0, s51
	s_nop 0
	global_load_lds_dwordx4 v[190:191], off
	s_add_u32 s2, s28, 0x20080
	s_addc_u32 s3, s29, 0
	s_add_i32 s9, s34, s39
	v_lshl_add_u64 v[218:219], s[2:3], 0, v[192:193]
	s_mov_b32 m0, s9
	s_nop 0
	global_load_lds_dwordx4 v[218:219], off
	v_lshl_add_u64 v[220:221], s[2:3], 0, v[132:133]
	s_add_i32 m0, s9, 0x2000
	s_nop 0
	global_load_lds_dwordx4 v[220:221], off
	s_waitcnt vmcnt(8)
	s_waitcnt lgkmcnt(0)
	s_barrier
	s_setprio 1
	v_mfma_f32_16x16x32_bf16 v[60:63], v[142:145], v[158:161], v[60:63]
	v_mfma_f32_16x16x32_bf16 v[56:59], v[150:153], v[158:161], v[56:59]
	v_mfma_f32_16x16x32_bf16 v[52:55], v[142:145], v[166:169], v[52:55]
	v_mfma_f32_16x16x32_bf16 v[44:47], v[150:153], v[166:169], v[44:47]
	v_mfma_f32_16x16x32_bf16 v[36:39], v[142:145], v[174:177], v[36:39]
	v_mfma_f32_16x16x32_bf16 v[28:31], v[150:153], v[174:177], v[28:31]
	v_mfma_f32_16x16x32_bf16 v[20:23], v[142:145], v[182:185], v[20:23]
	v_mfma_f32_16x16x32_bf16 v[12:15], v[150:153], v[182:185], v[12:15]
	v_mfma_f32_16x16x32_bf16 v[60:63], v[146:149], v[162:165], v[60:63]
	v_mfma_f32_16x16x32_bf16 v[56:59], v[154:157], v[162:165], v[56:59]
	v_mfma_f32_16x16x32_bf16 v[52:55], v[146:149], v[170:173], v[52:55]
	v_mfma_f32_16x16x32_bf16 v[44:47], v[154:157], v[170:173], v[44:47]
	v_mfma_f32_16x16x32_bf16 v[36:39], v[146:149], v[178:181], v[36:39]
	v_mfma_f32_16x16x32_bf16 v[28:31], v[154:157], v[178:181], v[28:31]
	v_mfma_f32_16x16x32_bf16 v[20:23], v[146:149], v[186:189], v[20:23]
	v_mfma_f32_16x16x32_bf16 v[12:15], v[154:157], v[186:189], v[12:15]
	v_mfma_f32_16x16x32_bf16 v[48:51], v[194:197], v[158:161], v[48:51]
	v_mfma_f32_16x16x32_bf16 v[40:43], v[202:205], v[158:161], v[40:43]
	v_mfma_f32_16x16x32_bf16 v[32:35], v[194:197], v[166:169], v[32:35]
	v_mfma_f32_16x16x32_bf16 v[24:27], v[202:205], v[166:169], v[24:27]
	v_mfma_f32_16x16x32_bf16 v[16:19], v[194:197], v[174:177], v[16:19]
	v_mfma_f32_16x16x32_bf16 v[8:11], v[202:205], v[174:177], v[8:11]
	v_mfma_f32_16x16x32_bf16 v[4:7], v[194:197], v[182:185], v[4:7]
	v_mfma_f32_16x16x32_bf16 v[0:3], v[202:205], v[182:185], v[0:3]
	v_mfma_f32_16x16x32_bf16 v[48:51], v[198:201], v[162:165], v[48:51]
	v_mfma_f32_16x16x32_bf16 v[40:43], v[206:209], v[162:165], v[40:43]
	v_mfma_f32_16x16x32_bf16 v[32:35], v[198:201], v[170:173], v[32:35]
	v_mfma_f32_16x16x32_bf16 v[24:27], v[206:209], v[170:173], v[24:27]
	v_mfma_f32_16x16x32_bf16 v[16:19], v[198:201], v[178:181], v[16:19]
	v_mfma_f32_16x16x32_bf16 v[8:11], v[206:209], v[178:181], v[8:11]
	v_mfma_f32_16x16x32_bf16 v[4:7], v[198:201], v[186:189], v[4:7]
	v_mfma_f32_16x16x32_bf16 v[0:3], v[206:209], v[186:189], v[0:3]
	s_setprio 0
	s_add_i32 s54, s54, 2
	s_cmp_gt_u32 s54, 5
	s_mov_b64 s[2:3], s[4:5]
	s_barrier
	s_cbranch_scc0 .LBB0_106
	s_lshl_b64 s[2:3], s[10:11], 23
	s_add_u32 s2, s26, s2
	s_addc_u32 s3, s27, s3
	s_add_u32 s2, s2, 0x2e00400
	s_addc_u32 s3, s3, 0
	v_and_b32_e32 v128, 63, v138
	s_lshl_b32 s4, s38, 8
	v_mov_b32 v128, v128
	s_add_i32 s52, s52, s4
	v_and_or_b32 v130, v128, 15, s52
	s_lshl_b32 s4, s37, 8
	v_ashrrev_i32_e32 v128, 1, v128
	s_or_b32 s4, s53, s4
	v_and_b32_e32 v128, -8, v128
	v_add_u32_e32 v128, s4, v128
	v_ashrrev_i32_e32 v131, 31, v130
	v_ashrrev_i32_e32 v129, 31, v128
	v_lshlrev_b64 v[132:133], 12, v[130:131]
	v_lshl_add_u64 v[132:133], s[2:3], 0, v[132:133]
	v_lshlrev_b64 v[134:135], 1, v[128:129]
	v_lshl_add_u64 v[128:129], v[132:133], 0, v[134:135]
	v_cvt_pk_bf16_f32 v124, v124, v125
	v_cvt_pk_bf16_f32 v125, v126, v127
	v_cvt_pk_bf16_f32 v126, v120, v121
	v_cvt_pk_bf16_f32 v127, v122, v123
	global_store_dwordx4 v[128:129], v[124:127], off
	v_cvt_pk_bf16_f32 v112, v112, v113
	v_cvt_pk_bf16_f32 v113, v114, v115
	v_cvt_pk_bf16_f32 v114, v104, v105
	v_or_b32_e32 v104, 16, v130
	v_ashrrev_i32_e32 v105, 31, v104
	v_lshlrev_b64 v[104:105], 12, v[104:105]
	v_lshl_add_u64 v[104:105], s[2:3], 0, v[104:105]
	v_cvt_pk_bf16_f32 v115, v106, v107
	global_store_dwordx4 v[128:129], v[112:115], off offset:256
	s_cmpk_lt_u32 s36, 0x100
	s_nop 0
	v_lshl_add_u64 v[112:113], v[104:105], 0, v[134:135]
	v_cvt_pk_bf16_f32 v104, v116, v117
	v_cvt_pk_bf16_f32 v105, v118, v119
	v_cvt_pk_bf16_f32 v106, v108, v109
	v_cvt_pk_bf16_f32 v107, v110, v111
	global_store_dwordx4 v[112:113], v[104:107], off
	v_cvt_pk_bf16_f32 v96, v96, v97
	v_cvt_pk_bf16_f32 v97, v98, v99
	v_cvt_pk_bf16_f32 v98, v88, v89
	v_or_b32_e32 v88, 32, v130
	v_ashrrev_i32_e32 v89, 31, v88
	v_lshlrev_b64 v[88:89], 12, v[88:89]
	v_lshl_add_u64 v[88:89], s[2:3], 0, v[88:89]
	v_cvt_pk_bf16_f32 v99, v90, v91
	global_store_dwordx4 v[112:113], v[96:99], off offset:256
	s_nop 1
	v_lshl_add_u64 v[96:97], v[88:89], 0, v[134:135]
	v_cvt_pk_bf16_f32 v88, v100, v101
	v_cvt_pk_bf16_f32 v89, v102, v103
	v_cvt_pk_bf16_f32 v90, v92, v93
	v_cvt_pk_bf16_f32 v91, v94, v95
	global_store_dwordx4 v[96:97], v[88:91], off
	v_cvt_pk_bf16_f32 v80, v80, v81
	v_cvt_pk_bf16_f32 v81, v82, v83
	v_cvt_pk_bf16_f32 v82, v72, v73
	v_or_b32_e32 v72, 48, v130
	v_ashrrev_i32_e32 v73, 31, v72
	v_lshlrev_b64 v[72:73], 12, v[72:73]
	v_lshl_add_u64 v[72:73], s[2:3], 0, v[72:73]
	v_cvt_pk_bf16_f32 v83, v74, v75
	global_store_dwordx4 v[96:97], v[80:83], off offset:256
	s_mov_b64 s[2:3], 0x80000
	s_nop 0
	v_lshl_add_u64 v[80:81], v[72:73], 0, v[134:135]
	v_cvt_pk_bf16_f32 v72, v84, v85
	v_cvt_pk_bf16_f32 v73, v86, v87
	v_cvt_pk_bf16_f32 v74, v76, v77
	v_cvt_pk_bf16_f32 v75, v78, v79
	global_store_dwordx4 v[80:81], v[72:75], off
	v_cvt_pk_bf16_f32 v68, v68, v69
	v_cvt_pk_bf16_f32 v69, v70, v71
	v_cvt_pk_bf16_f32 v70, v64, v65
	v_lshl_add_u64 v[64:65], v[128:129], 0, s[2:3]
	s_mov_b32 s2, 0x80000
	v_cvt_pk_bf16_f32 v71, v66, v67
	global_store_dwordx4 v[80:81], v[68:71], off offset:256
	v_cvt_pk_bf16_f32 v60, v60, v61
	v_cvt_pk_bf16_f32 v61, v62, v63
	v_cvt_pk_bf16_f32 v62, v56, v57
	v_add_co_u32_e32 v56, vcc, s2, v128
	v_cvt_pk_bf16_f32 v63, v58, v59
	s_mov_b64 s[2:3], 0x90000
	s_nop 0
	v_addc_co_u32_e32 v57, vcc, 0, v129, vcc
	global_store_dwordx4 v[56:57], v[60:63], off
	v_cvt_pk_bf16_f32 v48, v48, v49
	v_cvt_pk_bf16_f32 v49, v50, v51
	v_cvt_pk_bf16_f32 v50, v40, v41
	v_cvt_pk_bf16_f32 v51, v42, v43
	global_store_dwordx4 v[64:65], v[48:51], off offset:256
	v_cvt_pk_bf16_f32 v40, v52, v53
	v_cvt_pk_bf16_f32 v41, v54, v55
	v_cvt_pk_bf16_f32 v42, v44, v45
	v_cvt_pk_bf16_f32 v43, v46, v47
	s_nop 1
	v_lshl_add_u64 v[48:49], v[128:129], 0, s[2:3]
	s_mov_b32 s2, 0x90000
	v_add_co_u32_e32 v44, vcc, s2, v128
	s_mov_b64 s[2:3], 0xa0000
	s_nop 0
	v_addc_co_u32_e32 v45, vcc, 0, v129, vcc
	global_store_dwordx4 v[44:45], v[40:43], off
	v_cvt_pk_bf16_f32 v32, v32, v33
	v_cvt_pk_bf16_f32 v33, v34, v35
	v_cvt_pk_bf16_f32 v34, v24, v25
	v_cvt_pk_bf16_f32 v35, v26, v27
	global_store_dwordx4 v[48:49], v[32:35], off offset:256
	v_cvt_pk_bf16_f32 v24, v36, v37
	v_cvt_pk_bf16_f32 v25, v38, v39
	v_cvt_pk_bf16_f32 v26, v28, v29
	v_cvt_pk_bf16_f32 v27, v30, v31
	s_nop 1
	v_lshl_add_u64 v[32:33], v[128:129], 0, s[2:3]
	s_mov_b32 s2, 0xa0000
	v_add_co_u32_e32 v28, vcc, s2, v128
	s_mov_b64 s[2:3], 0xb0000
	s_nop 0
	v_addc_co_u32_e32 v29, vcc, 0, v129, vcc
	global_store_dwordx4 v[28:29], v[24:27], off
	v_cvt_pk_bf16_f32 v16, v16, v17
	v_cvt_pk_bf16_f32 v17, v18, v19
	v_cvt_pk_bf16_f32 v18, v8, v9
	v_cvt_pk_bf16_f32 v19, v10, v11
	global_store_dwordx4 v[32:33], v[16:19], off offset:256
	v_cvt_pk_bf16_f32 v8, v20, v21
	v_cvt_pk_bf16_f32 v9, v22, v23
	v_cvt_pk_bf16_f32 v10, v12, v13
	v_cvt_pk_bf16_f32 v11, v14, v15
	s_nop 1
	v_lshl_add_u64 v[16:17], v[128:129], 0, s[2:3]
	s_mov_b32 s2, 0xb0000
	v_add_co_u32_e32 v12, vcc, s2, v128
	s_nop 1
	v_addc_co_u32_e32 v13, vcc, 0, v129, vcc
	global_store_dwordx4 v[12:13], v[8:11], off
	v_cvt_pk_bf16_f32 v4, v4, v5
	v_cvt_pk_bf16_f32 v5, v6, v7
	v_cvt_pk_bf16_f32 v6, v0, v1
	v_cvt_pk_bf16_f32 v7, v2, v3
	global_store_dwordx4 v[16:17], v[4:7], off offset:256
	s_waitcnt vmcnt(0)
	s_cbranch_scc0 .LBB0_102
	s_barrier
	s_branch .LBB0_102

.LBB0_132:
	v_add_u32_e32 v138, 0x10000, v141
	ds_read_b128 v[144:147], v138
	ds_read_b128 v[148:151], v138 offset:1024
	ds_read_b128 v[152:155], v138 offset:2048
	ds_read_b128 v[156:159], v138 offset:3072
	ds_read_b128 v[160:163], v142
	ds_read_b128 v[164:167], v142 offset:1024
	ds_read_b128 v[168:171], v142 offset:2048
	ds_read_b128 v[172:175], v142 offset:3072
	ds_read_b128 v[176:179], v142 offset:4096
	ds_read_b128 v[180:183], v142 offset:5120
	ds_read_b128 v[184:187], v142 offset:6144
	ds_read_b128 v[188:191], v142 offset:7168
	v_add_u32_e32 v138, 0x14000, v141
	ds_read_b128 v[194:197], v138
	ds_read_b128 v[198:201], v138 offset:1024
	ds_read_b128 v[202:205], v138 offset:2048
	ds_read_b128 v[206:209], v138 offset:3072
	s_add_i32 s71, s4, 2
	s_add_u32 s5, s2, 0xfff80080
	s_addc_u32 s9, s3, -1
	s_add_i32 s46, 0, 0x10000
	s_cmp_eq_u32 s64, s4
	s_cselect_b32 s4, s28, s67
	s_cselect_b32 s35, s13, s9
	s_cselect_b32 s34, s12, s5
	s_cselect_b32 s5, s29, s69
	v_lshl_add_u64 v[138:139], s[2:3], 0, v[134:135]
	s_add_i32 m0, s40, 0xc000
	s_nop 0
	global_load_lds_dwordx4 v[138:139], off
	v_lshl_add_u64 v[138:139], s[2:3], 0, v[136:137]
	s_add_i32 m0, s40, 0xe000
	s_nop 0
	global_load_lds_dwordx4 v[138:139], off
	s_waitcnt vmcnt(8)
	s_waitcnt lgkmcnt(0)
	s_barrier
	s_setprio 1
	v_mfma_f32_16x16x32_bf16 v[124:127], v[144:147], v[160:163], v[124:127]
	v_mfma_f32_16x16x32_bf16 v[120:123], v[152:155], v[160:163], v[120:123]
	v_mfma_f32_16x16x32_bf16 v[116:119], v[144:147], v[168:171], v[116:119]
	v_mfma_f32_16x16x32_bf16 v[108:111], v[152:155], v[168:171], v[108:111]
	v_mfma_f32_16x16x32_bf16 v[100:103], v[144:147], v[176:179], v[100:103]
	v_mfma_f32_16x16x32_bf16 v[92:95], v[152:155], v[176:179], v[92:95]
	v_mfma_f32_16x16x32_bf16 v[84:87], v[144:147], v[184:187], v[84:87]
	v_mfma_f32_16x16x32_bf16 v[76:79], v[152:155], v[184:187], v[76:79]
	v_mfma_f32_16x16x32_bf16 v[124:127], v[148:151], v[164:167], v[124:127]
	v_mfma_f32_16x16x32_bf16 v[120:123], v[156:159], v[164:167], v[120:123]
	v_mfma_f32_16x16x32_bf16 v[116:119], v[148:151], v[172:175], v[116:119]
	v_mfma_f32_16x16x32_bf16 v[108:111], v[156:159], v[172:175], v[108:111]
	v_mfma_f32_16x16x32_bf16 v[100:103], v[148:151], v[180:183], v[100:103]
	v_mfma_f32_16x16x32_bf16 v[92:95], v[156:159], v[180:183], v[92:95]
	v_mfma_f32_16x16x32_bf16 v[84:87], v[148:151], v[188:191], v[84:87]
	v_mfma_f32_16x16x32_bf16 v[76:79], v[156:159], v[188:191], v[76:79]
	v_mfma_f32_16x16x32_bf16 v[112:115], v[194:197], v[160:163], v[112:115]
	v_mfma_f32_16x16x32_bf16 v[104:107], v[202:205], v[160:163], v[104:107]
	v_mfma_f32_16x16x32_bf16 v[96:99], v[194:197], v[168:171], v[96:99]
	v_mfma_f32_16x16x32_bf16 v[88:91], v[202:205], v[168:171], v[88:91]
	v_mfma_f32_16x16x32_bf16 v[80:83], v[194:197], v[176:179], v[80:83]
	v_mfma_f32_16x16x32_bf16 v[72:75], v[202:205], v[176:179], v[72:75]
	v_mfma_f32_16x16x32_bf16 v[68:71], v[194:197], v[184:187], v[68:71]
	v_mfma_f32_16x16x32_bf16 v[64:67], v[202:205], v[184:187], v[64:67]
	v_mfma_f32_16x16x32_bf16 v[112:115], v[198:201], v[164:167], v[112:115]
	v_mfma_f32_16x16x32_bf16 v[104:107], v[206:209], v[164:167], v[104:107]
	v_mfma_f32_16x16x32_bf16 v[96:99], v[198:201], v[172:175], v[96:99]
	v_mfma_f32_16x16x32_bf16 v[88:91], v[206:209], v[172:175], v[88:91]
	v_mfma_f32_16x16x32_bf16 v[80:83], v[198:201], v[180:183], v[80:83]
	v_mfma_f32_16x16x32_bf16 v[72:75], v[206:209], v[180:183], v[72:75]
	v_mfma_f32_16x16x32_bf16 v[68:71], v[198:201], v[188:191], v[68:71]
	v_mfma_f32_16x16x32_bf16 v[64:67], v[206:209], v[188:191], v[64:67]
	s_setprio 0
	s_barrier
	ds_read_b128 v[160:163], v142 offset:16384
	ds_read_b128 v[164:167], v142 offset:17408
	ds_read_b128 v[168:171], v142 offset:18432
	ds_read_b128 v[172:175], v142 offset:19456
	ds_read_b128 v[176:179], v142 offset:20480
	ds_read_b128 v[180:183], v142 offset:21504
	ds_read_b128 v[184:187], v142 offset:22528
	ds_read_b128 v[188:191], v142 offset:23552
	s_add_i32 s9, 0, 0x14000
	s_add_i32 s46, s46, s39
	v_lshl_add_u64 v[138:139], s[4:5], 0, v[192:193]
	s_mov_b32 m0, s46
	v_lshl_add_u64 v[210:211], s[4:5], 0, v[132:133]
	global_load_lds_dwordx4 v[138:139], off
	s_add_i32 m0, s46, 0x2000
	s_nop 0
	global_load_lds_dwordx4 v[210:211], off
	s_mov_b32 m0, s40
	v_lshl_add_u64 v[212:213], s[34:35], 0, v[128:129]
	global_load_lds_dwordx4 v[212:213], off
	v_lshl_add_u64 v[214:215], s[34:35], 0, v[130:131]
	s_mov_b32 m0, s41
	s_nop 0
	global_load_lds_dwordx4 v[214:215], off
	s_add_u32 s46, s4, 0x80000
	s_addc_u32 s47, s5, 0
	s_add_i32 s9, s9, s39
	v_lshl_add_u64 v[218:219], s[46:47], 0, v[192:193]
	s_mov_b32 m0, s9
	s_nop 0
	global_load_lds_dwordx4 v[218:219], off
	v_lshl_add_u64 v[220:221], s[46:47], 0, v[132:133]
	s_add_i32 m0, s9, 0x2000
	s_nop 0
	global_load_lds_dwordx4 v[220:221], off
	s_waitcnt vmcnt(8)
	s_waitcnt lgkmcnt(0)
	s_barrier
	s_setprio 1
	v_mfma_f32_16x16x32_bf16 v[60:63], v[144:147], v[160:163], v[60:63]
	v_mfma_f32_16x16x32_bf16 v[56:59], v[152:155], v[160:163], v[56:59]
	v_mfma_f32_16x16x32_bf16 v[52:55], v[144:147], v[168:171], v[52:55]
	v_mfma_f32_16x16x32_bf16 v[44:47], v[152:155], v[168:171], v[44:47]
	v_mfma_f32_16x16x32_bf16 v[36:39], v[144:147], v[176:179], v[36:39]
	v_mfma_f32_16x16x32_bf16 v[28:31], v[152:155], v[176:179], v[28:31]
	v_mfma_f32_16x16x32_bf16 v[20:23], v[144:147], v[184:187], v[20:23]
	v_mfma_f32_16x16x32_bf16 v[12:15], v[152:155], v[184:187], v[12:15]
	v_mfma_f32_16x16x32_bf16 v[60:63], v[148:151], v[164:167], v[60:63]
	v_mfma_f32_16x16x32_bf16 v[56:59], v[156:159], v[164:167], v[56:59]
	v_mfma_f32_16x16x32_bf16 v[52:55], v[148:151], v[172:175], v[52:55]
	v_mfma_f32_16x16x32_bf16 v[44:47], v[156:159], v[172:175], v[44:47]
	v_mfma_f32_16x16x32_bf16 v[36:39], v[148:151], v[180:183], v[36:39]
	v_mfma_f32_16x16x32_bf16 v[28:31], v[156:159], v[180:183], v[28:31]
	v_mfma_f32_16x16x32_bf16 v[20:23], v[148:151], v[188:191], v[20:23]
	v_mfma_f32_16x16x32_bf16 v[12:15], v[156:159], v[188:191], v[12:15]
	v_mfma_f32_16x16x32_bf16 v[48:51], v[194:197], v[160:163], v[48:51]
	v_mfma_f32_16x16x32_bf16 v[40:43], v[202:205], v[160:163], v[40:43]
	v_mfma_f32_16x16x32_bf16 v[32:35], v[194:197], v[168:171], v[32:35]
	v_mfma_f32_16x16x32_bf16 v[24:27], v[202:205], v[168:171], v[24:27]
	v_mfma_f32_16x16x32_bf16 v[16:19], v[194:197], v[176:179], v[16:19]
	v_mfma_f32_16x16x32_bf16 v[8:11], v[202:205], v[176:179], v[8:11]
	v_mfma_f32_16x16x32_bf16 v[4:7], v[194:197], v[184:187], v[4:7]
	v_mfma_f32_16x16x32_bf16 v[0:3], v[202:205], v[184:187], v[0:3]
	v_mfma_f32_16x16x32_bf16 v[48:51], v[198:201], v[164:167], v[48:51]
	v_mfma_f32_16x16x32_bf16 v[40:43], v[206:209], v[164:167], v[40:43]
	v_mfma_f32_16x16x32_bf16 v[32:35], v[198:201], v[172:175], v[32:35]
	v_mfma_f32_16x16x32_bf16 v[24:27], v[206:209], v[172:175], v[24:27]
	v_mfma_f32_16x16x32_bf16 v[16:19], v[198:201], v[180:183], v[16:19]
	v_mfma_f32_16x16x32_bf16 v[8:11], v[206:209], v[180:183], v[8:11]
	v_mfma_f32_16x16x32_bf16 v[4:7], v[198:201], v[188:191], v[4:7]
	v_mfma_f32_16x16x32_bf16 v[0:3], v[206:209], v[188:191], v[0:3]
	s_setprio 0
	s_barrier
	v_add_u32_e32 v143, 0x18000, v141
	ds_read_b128 v[144:147], v143
	ds_read_b128 v[148:151], v143 offset:1024
	ds_read_b128 v[152:155], v143 offset:2048
	ds_read_b128 v[156:159], v143 offset:3072
	ds_read_b128 v[160:163], v142 offset:32768
	ds_read_b128 v[164:167], v142 offset:33792
	ds_read_b128 v[168:171], v142 offset:34816
	ds_read_b128 v[172:175], v142 offset:35840
	ds_read_b128 v[176:179], v142 offset:36864
	ds_read_b128 v[180:183], v142 offset:37888
	ds_read_b128 v[184:187], v142 offset:38912
	ds_read_b128 v[188:191], v142 offset:39936
	v_add_u32_e32 v143, 0x1c000, v141
	ds_read_b128 v[194:197], v143
	ds_read_b128 v[198:201], v143 offset:1024
	ds_read_b128 v[202:205], v143 offset:2048
	ds_read_b128 v[206:209], v143 offset:3072
	s_add_i32 s9, 0, 0x18000
	s_add_u32 s34, s34, 0x80000
	s_addc_u32 s35, s35, 0
	s_mov_b32 m0, s48
	v_lshl_add_u64 v[218:219], s[34:35], 0, v[128:129]
	global_load_lds_dwordx4 v[218:219], off
	v_lshl_add_u64 v[220:221], s[34:35], 0, v[130:131]
	s_mov_b32 m0, s49
	s_nop 0
	global_load_lds_dwordx4 v[220:221], off
	s_waitcnt vmcnt(8)
	s_waitcnt lgkmcnt(0)
	s_barrier
	s_setprio 1
	v_mfma_f32_16x16x32_bf16 v[124:127], v[144:147], v[160:163], v[124:127]
	v_mfma_f32_16x16x32_bf16 v[120:123], v[152:155], v[160:163], v[120:123]
	v_mfma_f32_16x16x32_bf16 v[116:119], v[144:147], v[168:171], v[116:119]
	v_mfma_f32_16x16x32_bf16 v[108:111], v[152:155], v[168:171], v[108:111]
	v_mfma_f32_16x16x32_bf16 v[100:103], v[144:147], v[176:179], v[100:103]
	v_mfma_f32_16x16x32_bf16 v[92:95], v[152:155], v[176:179], v[92:95]
	v_mfma_f32_16x16x32_bf16 v[84:87], v[144:147], v[184:187], v[84:87]
	v_mfma_f32_16x16x32_bf16 v[76:79], v[152:155], v[184:187], v[76:79]
	v_mfma_f32_16x16x32_bf16 v[124:127], v[148:151], v[164:167], v[124:127]
	v_mfma_f32_16x16x32_bf16 v[120:123], v[156:159], v[164:167], v[120:123]
	v_mfma_f32_16x16x32_bf16 v[116:119], v[148:151], v[172:175], v[116:119]
	v_mfma_f32_16x16x32_bf16 v[108:111], v[156:159], v[172:175], v[108:111]
	v_mfma_f32_16x16x32_bf16 v[100:103], v[148:151], v[180:183], v[100:103]
	v_mfma_f32_16x16x32_bf16 v[92:95], v[156:159], v[180:183], v[92:95]
	v_mfma_f32_16x16x32_bf16 v[84:87], v[148:151], v[188:191], v[84:87]
	v_mfma_f32_16x16x32_bf16 v[76:79], v[156:159], v[188:191], v[76:79]
	v_mfma_f32_16x16x32_bf16 v[112:115], v[194:197], v[160:163], v[112:115]
	v_mfma_f32_16x16x32_bf16 v[104:107], v[202:205], v[160:163], v[104:107]
	v_mfma_f32_16x16x32_bf16 v[96:99], v[194:197], v[168:171], v[96:99]
	v_mfma_f32_16x16x32_bf16 v[88:91], v[202:205], v[168:171], v[88:91]
	v_mfma_f32_16x16x32_bf16 v[80:83], v[194:197], v[176:179], v[80:83]
	v_mfma_f32_16x16x32_bf16 v[72:75], v[202:205], v[176:179], v[72:75]
	v_mfma_f32_16x16x32_bf16 v[68:71], v[194:197], v[184:187], v[68:71]
	v_mfma_f32_16x16x32_bf16 v[64:67], v[202:205], v[184:187], v[64:67]
	v_mfma_f32_16x16x32_bf16 v[112:115], v[198:201], v[164:167], v[112:115]
	v_mfma_f32_16x16x32_bf16 v[104:107], v[206:209], v[164:167], v[104:107]
	v_mfma_f32_16x16x32_bf16 v[96:99], v[198:201], v[172:175], v[96:99]
	v_mfma_f32_16x16x32_bf16 v[88:91], v[206:209], v[172:175], v[88:91]
	v_mfma_f32_16x16x32_bf16 v[80:83], v[198:201], v[180:183], v[80:83]
	v_mfma_f32_16x16x32_bf16 v[72:75], v[206:209], v[180:183], v[72:75]
	v_mfma_f32_16x16x32_bf16 v[68:71], v[198:201], v[188:191], v[68:71]
	v_mfma_f32_16x16x32_bf16 v[64:67], v[206:209], v[188:191], v[64:67]
	s_setprio 0
	s_barrier
	ds_read_b128 v[160:163], v142 offset:49152
	ds_read_b128 v[164:167], v142 offset:50176
	ds_read_b128 v[168:171], v142 offset:51200
	ds_read_b128 v[172:175], v142 offset:52224
	ds_read_b128 v[176:179], v142 offset:53248
	ds_read_b128 v[180:183], v142 offset:54272
	ds_read_b128 v[184:187], v142 offset:55296
	ds_read_b128 v[188:191], v142 offset:56320
	s_add_i32 s34, 0, 0x1c000
	s_add_i32 s9, s9, s39
	v_lshl_add_u64 v[138:139], v[138:139], 0, s[72:73]
	s_mov_b32 m0, s9
	s_nop 0
	global_load_lds_dwordx4 v[138:139], off
	v_lshl_add_u64 v[138:139], v[210:211], 0, s[72:73]
	s_add_i32 m0, s9, 0x2000
	s_nop 0
	global_load_lds_dwordx4 v[138:139], off
	s_mov_b32 m0, s50
	v_lshl_add_u64 v[138:139], v[212:213], 0, s[72:73]
	global_load_lds_dwordx4 v[138:139], off
	v_lshl_add_u64 v[138:139], v[214:215], 0, s[72:73]
	s_mov_b32 m0, s51
	s_nop 0
	global_load_lds_dwordx4 v[138:139], off
	s_add_u32 s4, s4, 0x80080
	s_addc_u32 s5, s5, 0
	s_add_i32 s9, s34, s39
	v_lshl_add_u64 v[138:139], s[4:5], 0, v[192:193]
	s_mov_b32 m0, s9
	s_nop 0
	global_load_lds_dwordx4 v[138:139], off
	v_lshl_add_u64 v[138:139], s[4:5], 0, v[132:133]
	s_add_i32 m0, s9, 0x2000
	s_nop 0
	global_load_lds_dwordx4 v[138:139], off
	s_waitcnt vmcnt(8)
	s_waitcnt lgkmcnt(0)
	s_barrier
	s_setprio 1
	v_mfma_f32_16x16x32_bf16 v[60:63], v[144:147], v[160:163], v[60:63]
	v_mfma_f32_16x16x32_bf16 v[56:59], v[152:155], v[160:163], v[56:59]
	v_mfma_f32_16x16x32_bf16 v[52:55], v[144:147], v[168:171], v[52:55]
	v_mfma_f32_16x16x32_bf16 v[44:47], v[152:155], v[168:171], v[44:47]
	v_mfma_f32_16x16x32_bf16 v[36:39], v[144:147], v[176:179], v[36:39]
	v_mfma_f32_16x16x32_bf16 v[28:31], v[152:155], v[176:179], v[28:31]
	v_mfma_f32_16x16x32_bf16 v[20:23], v[144:147], v[184:187], v[20:23]
	v_mfma_f32_16x16x32_bf16 v[12:15], v[152:155], v[184:187], v[12:15]
	v_mfma_f32_16x16x32_bf16 v[60:63], v[148:151], v[164:167], v[60:63]
	v_mfma_f32_16x16x32_bf16 v[56:59], v[156:159], v[164:167], v[56:59]
	v_mfma_f32_16x16x32_bf16 v[52:55], v[148:151], v[172:175], v[52:55]
	v_mfma_f32_16x16x32_bf16 v[44:47], v[156:159], v[172:175], v[44:47]
	v_mfma_f32_16x16x32_bf16 v[36:39], v[148:151], v[180:183], v[36:39]
	v_mfma_f32_16x16x32_bf16 v[28:31], v[156:159], v[180:183], v[28:31]
	v_mfma_f32_16x16x32_bf16 v[20:23], v[148:151], v[188:191], v[20:23]
	v_mfma_f32_16x16x32_bf16 v[12:15], v[156:159], v[188:191], v[12:15]
	v_mfma_f32_16x16x32_bf16 v[48:51], v[194:197], v[160:163], v[48:51]
	v_mfma_f32_16x16x32_bf16 v[40:43], v[202:205], v[160:163], v[40:43]
	v_mfma_f32_16x16x32_bf16 v[32:35], v[194:197], v[168:171], v[32:35]
	v_mfma_f32_16x16x32_bf16 v[24:27], v[202:205], v[168:171], v[24:27]
	v_mfma_f32_16x16x32_bf16 v[16:19], v[194:197], v[176:179], v[16:19]
	v_mfma_f32_16x16x32_bf16 v[8:11], v[202:205], v[176:179], v[8:11]
	v_mfma_f32_16x16x32_bf16 v[4:7], v[194:197], v[184:187], v[4:7]
	v_mfma_f32_16x16x32_bf16 v[0:3], v[202:205], v[184:187], v[0:3]
	v_mfma_f32_16x16x32_bf16 v[48:51], v[198:201], v[164:167], v[48:51]
	v_mfma_f32_16x16x32_bf16 v[40:43], v[206:209], v[164:167], v[40:43]
	v_mfma_f32_16x16x32_bf16 v[32:35], v[198:201], v[172:175], v[32:35]
	v_mfma_f32_16x16x32_bf16 v[24:27], v[206:209], v[172:175], v[24:27]
	v_mfma_f32_16x16x32_bf16 v[16:19], v[198:201], v[180:183], v[16:19]
	v_mfma_f32_16x16x32_bf16 v[8:11], v[206:209], v[180:183], v[8:11]
	v_mfma_f32_16x16x32_bf16 v[4:7], v[198:201], v[188:191], v[4:7]
	v_mfma_f32_16x16x32_bf16 v[0:3], v[206:209], v[188:191], v[0:3]
	s_setprio 0
	s_add_u32 s2, s2, 0x100
	s_addc_u32 s3, s3, 0
	s_add_u32 s67, s67, 0x100
	s_addc_u32 s69, s69, 0
	s_cmp_ge_i32 s71, s63
	s_mov_b32 s4, s71
	s_barrier
	s_cbranch_scc0 .LBB0_132
	v_sub_co_u32_e64 v138, s[2:3], s66, 1
	s_nop 0
	v_readfirstlane_b32 s64, v138
	s_lshl_b64 s[4:5], s[64:65], 22
	v_readlane_b32 s34, v252, 9
	v_readlane_b32 s35, v252, 10
	s_add_u32 s4, s34, s4
	s_addc_u32 s5, s35, s5
	s_sub_i32 s9, s62, 32
	s_and_b64 s[2:3], s[2:3], exec
	v_readlane_b32 s34, v252, 7
	s_cselect_b32 s2, s62, s9
	v_readlane_b32 s35, v252, 8
	s_cselect_b32 s5, s35, s5
	s_cselect_b32 s4, s34, s4
	s_ashr_i32 s3, s2, 31
	s_lshl_b64 s[2:3], s[2:3], 20
	s_add_u32 s2, s4, s2
	v_mov_b32 v139, v140
	s_addc_u32 s3, s5, s3
	v_ashrrev_i32_e32 v138, 1, v139
	s_lshl_b32 s4, s58, 8
	v_and_b32_e32 v138, -8, v138
	s_or_b32 s4, s4, s53
	v_add_u32_e32 v138, s4, v138
	v_and_or_b32 v144, v139, 15, s52
	v_ashrrev_i32_e32 v139, 31, v138
	v_ashrrev_i32_e32 v145, 31, v144
	v_lshl_add_u64 v[146:147], v[138:139], 1, s[2:3]
	v_lshlrev_b64 v[138:139], 12, v[144:145]
	v_lshl_add_u64 v[138:139], v[146:147], 0, v[138:139]
	v_cvt_pk_bf16_f32 v124, v124, v125
	v_cvt_pk_bf16_f32 v125, v126, v127
	v_cvt_pk_bf16_f32 v126, v120, v121
	v_cvt_pk_bf16_f32 v127, v122, v123
	global_store_dwordx4 v[138:139], v[124:127], off
	v_cvt_pk_bf16_f32 v112, v112, v113
	v_cvt_pk_bf16_f32 v113, v114, v115
	v_cvt_pk_bf16_f32 v114, v104, v105
	v_or_b32_e32 v104, 16, v144
	v_ashrrev_i32_e32 v105, 31, v104
	v_lshlrev_b64 v[104:105], 12, v[104:105]
	v_cvt_pk_bf16_f32 v115, v106, v107
	global_store_dwordx4 v[138:139], v[112:115], off offset:256
	s_mov_b64 s[2:3], 0x80000
	s_mov_b32 s58, s55
	v_lshl_add_u64 v[112:113], v[146:147], 0, v[104:105]
	v_cvt_pk_bf16_f32 v104, v116, v117
	v_cvt_pk_bf16_f32 v105, v118, v119
	v_cvt_pk_bf16_f32 v106, v108, v109
	v_cvt_pk_bf16_f32 v107, v110, v111
	global_store_dwordx4 v[112:113], v[104:107], off
	v_cvt_pk_bf16_f32 v96, v96, v97
	v_cvt_pk_bf16_f32 v97, v98, v99
	v_cvt_pk_bf16_f32 v98, v88, v89
	v_or_b32_e32 v88, 32, v144
	v_ashrrev_i32_e32 v89, 31, v88
	v_lshlrev_b64 v[88:89], 12, v[88:89]
	v_cvt_pk_bf16_f32 v99, v90, v91
	global_store_dwordx4 v[112:113], v[96:99], off offset:256
	s_mov_b32 s62, s14
	s_mov_b32 s66, s15
	v_lshl_add_u64 v[96:97], v[146:147], 0, v[88:89]
	v_cvt_pk_bf16_f32 v88, v100, v101
	v_cvt_pk_bf16_f32 v89, v102, v103
	v_cvt_pk_bf16_f32 v90, v92, v93
	v_cvt_pk_bf16_f32 v91, v94, v95
	global_store_dwordx4 v[96:97], v[88:91], off
	v_cvt_pk_bf16_f32 v80, v80, v81
	v_cvt_pk_bf16_f32 v81, v82, v83
	v_cvt_pk_bf16_f32 v82, v72, v73
	v_or_b32_e32 v72, 48, v144
	v_ashrrev_i32_e32 v73, 31, v72
	v_lshlrev_b64 v[72:73], 12, v[72:73]
	v_cvt_pk_bf16_f32 v83, v74, v75
	global_store_dwordx4 v[96:97], v[80:83], off offset:256
	s_mov_b32 s63, s59
	s_mov_b64 s[4:5], s[28:29]
	v_lshl_add_u64 v[80:81], v[146:147], 0, v[72:73]
	v_cvt_pk_bf16_f32 v72, v84, v85
	v_cvt_pk_bf16_f32 v73, v86, v87
	v_cvt_pk_bf16_f32 v74, v76, v77
	v_cvt_pk_bf16_f32 v75, v78, v79
	global_store_dwordx4 v[80:81], v[72:75], off
	v_cvt_pk_bf16_f32 v68, v68, v69
	v_cvt_pk_bf16_f32 v69, v70, v71
	v_cvt_pk_bf16_f32 v70, v64, v65
	v_lshl_add_u64 v[64:65], v[138:139], 0, s[2:3]
	s_mov_b32 s2, 0x80000
	v_cvt_pk_bf16_f32 v71, v66, v67
	global_store_dwordx4 v[80:81], v[68:71], off offset:256
	v_cvt_pk_bf16_f32 v60, v60, v61
	v_cvt_pk_bf16_f32 v61, v62, v63
	v_cvt_pk_bf16_f32 v62, v56, v57
	v_add_co_u32_e32 v56, vcc, s2, v138
	v_cvt_pk_bf16_f32 v63, v58, v59
	s_mov_b64 s[2:3], 0x90000
	s_nop 0
	v_addc_co_u32_e32 v57, vcc, 0, v139, vcc
	global_store_dwordx4 v[56:57], v[60:63], off
	v_cvt_pk_bf16_f32 v48, v48, v49
	v_cvt_pk_bf16_f32 v49, v50, v51
	v_cvt_pk_bf16_f32 v50, v40, v41
	v_cvt_pk_bf16_f32 v51, v42, v43
	global_store_dwordx4 v[64:65], v[48:51], off offset:256
	v_cvt_pk_bf16_f32 v40, v52, v53
	v_cvt_pk_bf16_f32 v41, v54, v55
	v_cvt_pk_bf16_f32 v42, v44, v45
	v_cvt_pk_bf16_f32 v43, v46, v47
	s_nop 1
	v_lshl_add_u64 v[48:49], v[138:139], 0, s[2:3]
	s_mov_b32 s2, 0x90000
	v_add_co_u32_e32 v44, vcc, s2, v138
	s_mov_b64 s[2:3], 0xa0000
	s_nop 0
	v_addc_co_u32_e32 v45, vcc, 0, v139, vcc
	global_store_dwordx4 v[44:45], v[40:43], off
	v_cvt_pk_bf16_f32 v32, v32, v33
	v_cvt_pk_bf16_f32 v33, v34, v35
	v_cvt_pk_bf16_f32 v34, v24, v25
	v_cvt_pk_bf16_f32 v35, v26, v27
	global_store_dwordx4 v[48:49], v[32:35], off offset:256
	v_cvt_pk_bf16_f32 v24, v36, v37
	v_cvt_pk_bf16_f32 v25, v38, v39
	v_cvt_pk_bf16_f32 v26, v28, v29
	v_cvt_pk_bf16_f32 v27, v30, v31
	s_nop 1
	v_lshl_add_u64 v[32:33], v[138:139], 0, s[2:3]
	s_mov_b32 s2, 0xa0000
	v_add_co_u32_e32 v28, vcc, s2, v138
	s_mov_b64 s[2:3], 0xb0000
	s_nop 0
	v_addc_co_u32_e32 v29, vcc, 0, v139, vcc
	global_store_dwordx4 v[28:29], v[24:27], off
	v_cvt_pk_bf16_f32 v16, v16, v17
	v_cvt_pk_bf16_f32 v17, v18, v19
	v_cvt_pk_bf16_f32 v18, v8, v9
	v_cvt_pk_bf16_f32 v19, v10, v11
	global_store_dwordx4 v[32:33], v[16:19], off offset:256
	v_cvt_pk_bf16_f32 v8, v20, v21
	v_cvt_pk_bf16_f32 v9, v22, v23
	v_cvt_pk_bf16_f32 v10, v12, v13
	v_cvt_pk_bf16_f32 v11, v14, v15
	s_nop 1
	v_lshl_add_u64 v[16:17], v[138:139], 0, s[2:3]
	s_mov_b32 s2, 0xb0000
	v_add_co_u32_e32 v12, vcc, s2, v138
	s_mov_b64 s[2:3], s[12:13]
	s_nop 0
	v_addc_co_u32_e32 v13, vcc, 0, v139, vcc
	s_and_b64 vcc, exec, s[0:1]
	global_store_dwordx4 v[12:13], v[8:11], off
	v_cvt_pk_bf16_f32 v4, v4, v5
	v_cvt_pk_bf16_f32 v5, v6, v7
	v_cvt_pk_bf16_f32 v6, v0, v1
	v_cvt_pk_bf16_f32 v7, v2, v3
	global_store_dwordx4 v[16:17], v[4:7], off offset:256
	s_cbranch_vccz .LBB0_122
	s_waitcnt vmcnt(0)
	s_cmpk_gt_u32 s36, 0xff
	s_cbranch_scc1 .LBB0_136
	s_barrier

.LBB0_198:
	v_add_u32_e32 v141, 0x10000, v139
	ds_read_b128 v[142:145], v141
	ds_read_b128 v[146:149], v141 offset:1024
	ds_read_b128 v[150:153], v141 offset:2048
	ds_read_b128 v[154:157], v141 offset:3072
	ds_read_b128 v[158:161], v140
	ds_read_b128 v[164:167], v140 offset:1024
	ds_read_b128 v[168:171], v140 offset:2048
	ds_read_b128 v[172:175], v140 offset:3072
	ds_read_b128 v[176:179], v140 offset:4096
	ds_read_b128 v[180:183], v140 offset:5120
	ds_read_b128 v[184:187], v140 offset:6144
	ds_read_b128 v[188:191], v140 offset:7168
	v_add_u32_e32 v141, 0x14000, v139
	ds_read_b128 v[194:197], v141
	ds_read_b128 v[198:201], v141 offset:1024
	ds_read_b128 v[202:205], v141 offset:2048
	ds_read_b128 v[206:209], v141 offset:3072
	s_add_u32 s2, s0, 0xf2ce0080
	s_addc_u32 s3, s1, -1
	s_cmp_lg_u32 vcc_lo, 4
	s_cselect_b32 s2, s2, 0
	s_cselect_b32 s3, s3, 0
	s_add_u32 s4, s16, s2
	s_addc_u32 s5, s17, s3
	s_add_i32 s9, 0, 0x10000
	s_add_u32 s2, s10, s2
	s_addc_u32 s3, s11, s3
	v_lshl_add_u64 v[218:219], v[134:135], 0, s[0:1]
	s_add_i32 m0, s49, 0xc000
	s_nop 0
	global_load_lds_dwordx4 v[218:219], off
	v_lshl_add_u64 v[220:221], v[136:137], 0, s[0:1]
	s_add_i32 m0, s49, 0xe000
	s_nop 0
	global_load_lds_dwordx4 v[220:221], off
	s_waitcnt vmcnt(8)
	s_waitcnt lgkmcnt(0)
	s_barrier
	s_setprio 1
	v_mfma_f32_16x16x32_bf16 v[124:127], v[142:145], v[158:161], v[124:127]
	v_mfma_f32_16x16x32_bf16 v[120:123], v[150:153], v[158:161], v[120:123]
	v_mfma_f32_16x16x32_bf16 v[116:119], v[142:145], v[168:171], v[116:119]
	v_mfma_f32_16x16x32_bf16 v[108:111], v[150:153], v[168:171], v[108:111]
	v_mfma_f32_16x16x32_bf16 v[100:103], v[142:145], v[176:179], v[100:103]
	v_mfma_f32_16x16x32_bf16 v[92:95], v[150:153], v[176:179], v[92:95]
	v_mfma_f32_16x16x32_bf16 v[84:87], v[142:145], v[184:187], v[84:87]
	v_mfma_f32_16x16x32_bf16 v[76:79], v[150:153], v[184:187], v[76:79]
	v_mfma_f32_16x16x32_bf16 v[124:127], v[146:149], v[164:167], v[124:127]
	v_mfma_f32_16x16x32_bf16 v[120:123], v[154:157], v[164:167], v[120:123]
	v_mfma_f32_16x16x32_bf16 v[116:119], v[146:149], v[172:175], v[116:119]
	v_mfma_f32_16x16x32_bf16 v[108:111], v[154:157], v[172:175], v[108:111]
	v_mfma_f32_16x16x32_bf16 v[100:103], v[146:149], v[180:183], v[100:103]
	v_mfma_f32_16x16x32_bf16 v[92:95], v[154:157], v[180:183], v[92:95]
	v_mfma_f32_16x16x32_bf16 v[84:87], v[146:149], v[188:191], v[84:87]
	v_mfma_f32_16x16x32_bf16 v[76:79], v[154:157], v[188:191], v[76:79]
	v_mfma_f32_16x16x32_bf16 v[112:115], v[194:197], v[158:161], v[112:115]
	v_mfma_f32_16x16x32_bf16 v[104:107], v[202:205], v[158:161], v[104:107]
	v_mfma_f32_16x16x32_bf16 v[96:99], v[194:197], v[168:171], v[96:99]
	v_mfma_f32_16x16x32_bf16 v[88:91], v[202:205], v[168:171], v[88:91]
	v_mfma_f32_16x16x32_bf16 v[80:83], v[194:197], v[176:179], v[80:83]
	v_mfma_f32_16x16x32_bf16 v[72:75], v[202:205], v[176:179], v[72:75]
	v_mfma_f32_16x16x32_bf16 v[68:71], v[194:197], v[184:187], v[68:71]
	v_mfma_f32_16x16x32_bf16 v[64:67], v[202:205], v[184:187], v[64:67]
	v_mfma_f32_16x16x32_bf16 v[112:115], v[198:201], v[164:167], v[112:115]
	v_mfma_f32_16x16x32_bf16 v[104:107], v[206:209], v[164:167], v[104:107]
	v_mfma_f32_16x16x32_bf16 v[96:99], v[198:201], v[172:175], v[96:99]
	v_mfma_f32_16x16x32_bf16 v[88:91], v[206:209], v[172:175], v[88:91]
	v_mfma_f32_16x16x32_bf16 v[80:83], v[198:201], v[180:183], v[80:83]
	v_mfma_f32_16x16x32_bf16 v[72:75], v[206:209], v[180:183], v[72:75]
	v_mfma_f32_16x16x32_bf16 v[68:71], v[198:201], v[188:191], v[68:71]
	v_mfma_f32_16x16x32_bf16 v[64:67], v[206:209], v[188:191], v[64:67]
	s_setprio 0
	s_barrier
	ds_read_b128 v[158:161], v140 offset:16384
	ds_read_b128 v[164:167], v140 offset:17408
	ds_read_b128 v[168:171], v140 offset:18432
	ds_read_b128 v[172:175], v140 offset:19456
	ds_read_b128 v[176:179], v140 offset:20480
	ds_read_b128 v[180:183], v140 offset:21504
	ds_read_b128 v[184:187], v140 offset:22528
	ds_read_b128 v[188:191], v140 offset:23552
	s_add_i32 vcc_hi, 0, 0x14000
	s_add_i32 s9, s9, s48
	v_lshl_add_u64 v[210:211], s[2:3], 0, v[192:193]
	s_mov_b32 m0, s9
	s_nop 0
	global_load_lds_dwordx4 v[210:211], off
	v_lshl_add_u64 v[212:213], s[2:3], 0, v[132:133]
	s_add_i32 m0, s9, 0x2000
	s_nop 0
	global_load_lds_dwordx4 v[212:213], off
	s_mov_b32 m0, s49
	v_lshl_add_u64 v[214:215], s[4:5], 0, v[128:129]
	global_load_lds_dwordx4 v[214:215], off
	v_lshl_add_u64 v[216:217], s[4:5], 0, v[130:131]
	s_mov_b32 m0, s58
	s_nop 0
	global_load_lds_dwordx4 v[216:217], off
	s_add_u32 s46, s2, 0x80000
	s_addc_u32 s47, s3, 0
	s_add_i32 s9, vcc_hi, s48
	v_lshl_add_u64 v[218:219], s[46:47], 0, v[192:193]
	s_mov_b32 m0, s9
	s_nop 0
	global_load_lds_dwordx4 v[218:219], off
	v_lshl_add_u64 v[220:221], s[46:47], 0, v[132:133]
	s_add_i32 m0, s9, 0x2000
	s_nop 0
	global_load_lds_dwordx4 v[220:221], off
	s_waitcnt vmcnt(8)
	s_waitcnt lgkmcnt(0)
	s_barrier
	s_setprio 1
	v_mfma_f32_16x16x32_bf16 v[60:63], v[142:145], v[158:161], v[60:63]
	v_mfma_f32_16x16x32_bf16 v[56:59], v[150:153], v[158:161], v[56:59]
	v_mfma_f32_16x16x32_bf16 v[52:55], v[142:145], v[168:171], v[52:55]
	v_mfma_f32_16x16x32_bf16 v[44:47], v[150:153], v[168:171], v[44:47]
	v_mfma_f32_16x16x32_bf16 v[36:39], v[142:145], v[176:179], v[36:39]
	v_mfma_f32_16x16x32_bf16 v[28:31], v[150:153], v[176:179], v[28:31]
	v_mfma_f32_16x16x32_bf16 v[20:23], v[142:145], v[184:187], v[20:23]
	v_mfma_f32_16x16x32_bf16 v[12:15], v[150:153], v[184:187], v[12:15]
	v_mfma_f32_16x16x32_bf16 v[60:63], v[146:149], v[164:167], v[60:63]
	v_mfma_f32_16x16x32_bf16 v[56:59], v[154:157], v[164:167], v[56:59]
	v_mfma_f32_16x16x32_bf16 v[52:55], v[146:149], v[172:175], v[52:55]
	v_mfma_f32_16x16x32_bf16 v[44:47], v[154:157], v[172:175], v[44:47]
	v_mfma_f32_16x16x32_bf16 v[36:39], v[146:149], v[180:183], v[36:39]
	v_mfma_f32_16x16x32_bf16 v[28:31], v[154:157], v[180:183], v[28:31]
	v_mfma_f32_16x16x32_bf16 v[20:23], v[146:149], v[188:191], v[20:23]
	v_mfma_f32_16x16x32_bf16 v[12:15], v[154:157], v[188:191], v[12:15]
	v_mfma_f32_16x16x32_bf16 v[48:51], v[194:197], v[158:161], v[48:51]
	v_mfma_f32_16x16x32_bf16 v[40:43], v[202:205], v[158:161], v[40:43]
	v_mfma_f32_16x16x32_bf16 v[32:35], v[194:197], v[168:171], v[32:35]
	v_mfma_f32_16x16x32_bf16 v[24:27], v[202:205], v[168:171], v[24:27]
	v_mfma_f32_16x16x32_bf16 v[16:19], v[194:197], v[176:179], v[16:19]
	v_mfma_f32_16x16x32_bf16 v[8:11], v[202:205], v[176:179], v[8:11]
	v_mfma_f32_16x16x32_bf16 v[4:7], v[194:197], v[184:187], v[4:7]
	v_mfma_f32_16x16x32_bf16 v[0:3], v[202:205], v[184:187], v[0:3]
	v_mfma_f32_16x16x32_bf16 v[48:51], v[198:201], v[164:167], v[48:51]
	v_mfma_f32_16x16x32_bf16 v[40:43], v[206:209], v[164:167], v[40:43]
	v_mfma_f32_16x16x32_bf16 v[32:35], v[198:201], v[172:175], v[32:35]
	v_mfma_f32_16x16x32_bf16 v[24:27], v[206:209], v[172:175], v[24:27]
	v_mfma_f32_16x16x32_bf16 v[16:19], v[198:201], v[180:183], v[16:19]
	v_mfma_f32_16x16x32_bf16 v[8:11], v[206:209], v[180:183], v[8:11]
	v_mfma_f32_16x16x32_bf16 v[4:7], v[198:201], v[188:191], v[4:7]
	v_mfma_f32_16x16x32_bf16 v[0:3], v[206:209], v[188:191], v[0:3]
	s_setprio 0
	s_barrier
	v_add_u32_e32 v141, 0x18000, v139
	ds_read_b128 v[142:145], v141
	ds_read_b128 v[146:149], v141 offset:1024
	ds_read_b128 v[150:153], v141 offset:2048
	ds_read_b128 v[154:157], v141 offset:3072
	ds_read_b128 v[158:161], v140 offset:32768
	ds_read_b128 v[164:167], v140 offset:33792
	ds_read_b128 v[168:171], v140 offset:34816
	ds_read_b128 v[172:175], v140 offset:35840
	ds_read_b128 v[176:179], v140 offset:36864
	ds_read_b128 v[180:183], v140 offset:37888
	ds_read_b128 v[184:187], v140 offset:38912
	ds_read_b128 v[188:191], v140 offset:39936
	v_add_u32_e32 v141, 0x1c000, v139
	ds_read_b128 v[194:197], v141
	ds_read_b128 v[198:201], v141 offset:1024
	ds_read_b128 v[202:205], v141 offset:2048
	ds_read_b128 v[206:209], v141 offset:3072
	s_add_i32 s9, 0, 0x18000
	s_add_u32 s4, s4, 0x20000
	s_addc_u32 s5, s5, 0
	s_mov_b32 m0, s59
	v_lshl_add_u64 v[218:219], s[4:5], 0, v[128:129]
	global_load_lds_dwordx4 v[218:219], off
	v_lshl_add_u64 v[220:221], s[4:5], 0, v[130:131]
	s_mov_b32 m0, s62
	s_nop 0
	global_load_lds_dwordx4 v[220:221], off
	s_waitcnt vmcnt(8)
	s_waitcnt lgkmcnt(0)
	s_barrier
	s_setprio 1
	v_mfma_f32_16x16x32_bf16 v[124:127], v[142:145], v[158:161], v[124:127]
	v_mfma_f32_16x16x32_bf16 v[120:123], v[150:153], v[158:161], v[120:123]
	v_mfma_f32_16x16x32_bf16 v[116:119], v[142:145], v[168:171], v[116:119]
	v_mfma_f32_16x16x32_bf16 v[108:111], v[150:153], v[168:171], v[108:111]
	v_mfma_f32_16x16x32_bf16 v[100:103], v[142:145], v[176:179], v[100:103]
	v_mfma_f32_16x16x32_bf16 v[92:95], v[150:153], v[176:179], v[92:95]
	v_mfma_f32_16x16x32_bf16 v[84:87], v[142:145], v[184:187], v[84:87]
	v_mfma_f32_16x16x32_bf16 v[76:79], v[150:153], v[184:187], v[76:79]
	v_mfma_f32_16x16x32_bf16 v[124:127], v[146:149], v[164:167], v[124:127]
	v_mfma_f32_16x16x32_bf16 v[120:123], v[154:157], v[164:167], v[120:123]
	v_mfma_f32_16x16x32_bf16 v[116:119], v[146:149], v[172:175], v[116:119]
	v_mfma_f32_16x16x32_bf16 v[108:111], v[154:157], v[172:175], v[108:111]
	v_mfma_f32_16x16x32_bf16 v[100:103], v[146:149], v[180:183], v[100:103]
	v_mfma_f32_16x16x32_bf16 v[92:95], v[154:157], v[180:183], v[92:95]
	v_mfma_f32_16x16x32_bf16 v[84:87], v[146:149], v[188:191], v[84:87]
	v_mfma_f32_16x16x32_bf16 v[76:79], v[154:157], v[188:191], v[76:79]
	v_mfma_f32_16x16x32_bf16 v[112:115], v[194:197], v[158:161], v[112:115]
	v_mfma_f32_16x16x32_bf16 v[104:107], v[202:205], v[158:161], v[104:107]
	v_mfma_f32_16x16x32_bf16 v[96:99], v[194:197], v[168:171], v[96:99]
	v_mfma_f32_16x16x32_bf16 v[88:91], v[202:205], v[168:171], v[88:91]
	v_mfma_f32_16x16x32_bf16 v[80:83], v[194:197], v[176:179], v[80:83]
	v_mfma_f32_16x16x32_bf16 v[72:75], v[202:205], v[176:179], v[72:75]
	v_mfma_f32_16x16x32_bf16 v[68:71], v[194:197], v[184:187], v[68:71]
	v_mfma_f32_16x16x32_bf16 v[64:67], v[202:205], v[184:187], v[64:67]
	v_mfma_f32_16x16x32_bf16 v[112:115], v[198:201], v[164:167], v[112:115]
	v_mfma_f32_16x16x32_bf16 v[104:107], v[206:209], v[164:167], v[104:107]
	v_mfma_f32_16x16x32_bf16 v[96:99], v[198:201], v[172:175], v[96:99]
	v_mfma_f32_16x16x32_bf16 v[88:91], v[206:209], v[172:175], v[88:91]
	v_mfma_f32_16x16x32_bf16 v[80:83], v[198:201], v[180:183], v[80:83]
	v_mfma_f32_16x16x32_bf16 v[72:75], v[206:209], v[180:183], v[72:75]
	v_mfma_f32_16x16x32_bf16 v[68:71], v[198:201], v[188:191], v[68:71]
	v_mfma_f32_16x16x32_bf16 v[64:67], v[206:209], v[188:191], v[64:67]
	s_setprio 0
	s_barrier
	ds_read_b128 v[158:161], v140 offset:49152
	ds_read_b128 v[164:167], v140 offset:50176
	ds_read_b128 v[168:171], v140 offset:51200
	ds_read_b128 v[172:175], v140 offset:52224
	ds_read_b128 v[176:179], v140 offset:53248
	ds_read_b128 v[180:183], v140 offset:54272
	ds_read_b128 v[184:187], v140 offset:55296
	ds_read_b128 v[188:191], v140 offset:56320
	s_add_i32 s4, 0, 0x1c000
	s_add_i32 s5, s9, s48
	v_lshl_add_u64 v[210:211], v[210:211], 0, s[72:73]
	s_mov_b32 m0, s5
	s_nop 0
	global_load_lds_dwordx4 v[210:211], off
	v_lshl_add_u64 v[210:211], v[212:213], 0, s[72:73]
	s_add_i32 m0, s5, 0x2000
	s_nop 0
	global_load_lds_dwordx4 v[210:211], off
	s_mov_b32 m0, s63
	v_lshl_add_u64 v[210:211], v[214:215], 0, s[72:73]
	global_load_lds_dwordx4 v[210:211], off
	v_lshl_add_u64 v[210:211], v[216:217], 0, s[72:73]
	s_mov_b32 m0, s64
	s_nop 0
	global_load_lds_dwordx4 v[210:211], off
	s_add_u32 s2, s2, 0x80080
	s_addc_u32 s3, s3, 0
	s_add_i32 s4, s4, s48
	v_lshl_add_u64 v[218:219], s[2:3], 0, v[192:193]
	s_mov_b32 m0, s4
	s_nop 0
	global_load_lds_dwordx4 v[218:219], off
	v_lshl_add_u64 v[220:221], s[2:3], 0, v[132:133]
	s_add_i32 m0, s4, 0x2000
	s_nop 0
	global_load_lds_dwordx4 v[220:221], off
	s_waitcnt vmcnt(8)
	s_waitcnt lgkmcnt(0)
	s_barrier
	s_setprio 1
	v_mfma_f32_16x16x32_bf16 v[60:63], v[142:145], v[158:161], v[60:63]
	v_mfma_f32_16x16x32_bf16 v[56:59], v[150:153], v[158:161], v[56:59]
	v_mfma_f32_16x16x32_bf16 v[52:55], v[142:145], v[168:171], v[52:55]
	v_mfma_f32_16x16x32_bf16 v[44:47], v[150:153], v[168:171], v[44:47]
	v_mfma_f32_16x16x32_bf16 v[36:39], v[142:145], v[176:179], v[36:39]
	v_mfma_f32_16x16x32_bf16 v[28:31], v[150:153], v[176:179], v[28:31]
	v_mfma_f32_16x16x32_bf16 v[20:23], v[142:145], v[184:187], v[20:23]
	v_mfma_f32_16x16x32_bf16 v[12:15], v[150:153], v[184:187], v[12:15]
	v_mfma_f32_16x16x32_bf16 v[60:63], v[146:149], v[164:167], v[60:63]
	v_mfma_f32_16x16x32_bf16 v[56:59], v[154:157], v[164:167], v[56:59]
	v_mfma_f32_16x16x32_bf16 v[52:55], v[146:149], v[172:175], v[52:55]
	v_mfma_f32_16x16x32_bf16 v[44:47], v[154:157], v[172:175], v[44:47]
	v_mfma_f32_16x16x32_bf16 v[36:39], v[146:149], v[180:183], v[36:39]
	v_mfma_f32_16x16x32_bf16 v[28:31], v[154:157], v[180:183], v[28:31]
	v_mfma_f32_16x16x32_bf16 v[20:23], v[146:149], v[188:191], v[20:23]
	v_mfma_f32_16x16x32_bf16 v[12:15], v[154:157], v[188:191], v[12:15]
	v_mfma_f32_16x16x32_bf16 v[48:51], v[194:197], v[158:161], v[48:51]
	v_mfma_f32_16x16x32_bf16 v[40:43], v[202:205], v[158:161], v[40:43]
	v_mfma_f32_16x16x32_bf16 v[32:35], v[194:197], v[168:171], v[32:35]
	v_mfma_f32_16x16x32_bf16 v[24:27], v[202:205], v[168:171], v[24:27]
	v_mfma_f32_16x16x32_bf16 v[16:19], v[194:197], v[176:179], v[16:19]
	v_mfma_f32_16x16x32_bf16 v[8:11], v[202:205], v[176:179], v[8:11]
	v_mfma_f32_16x16x32_bf16 v[4:7], v[194:197], v[184:187], v[4:7]
	v_mfma_f32_16x16x32_bf16 v[0:3], v[202:205], v[184:187], v[0:3]
	v_mfma_f32_16x16x32_bf16 v[48:51], v[198:201], v[164:167], v[48:51]
	v_mfma_f32_16x16x32_bf16 v[40:43], v[206:209], v[164:167], v[40:43]
	v_mfma_f32_16x16x32_bf16 v[32:35], v[198:201], v[172:175], v[32:35]
	v_mfma_f32_16x16x32_bf16 v[24:27], v[206:209], v[172:175], v[24:27]
	v_mfma_f32_16x16x32_bf16 v[16:19], v[198:201], v[180:183], v[16:19]
	v_mfma_f32_16x16x32_bf16 v[8:11], v[206:209], v[180:183], v[8:11]
	v_mfma_f32_16x16x32_bf16 v[4:7], v[198:201], v[188:191], v[4:7]
	v_mfma_f32_16x16x32_bf16 v[0:3], v[206:209], v[188:191], v[0:3]
	s_setprio 0
	s_add_i32 vcc_lo, vcc_lo, 2
	s_add_u32 s0, s0, 0x100
	s_addc_u32 s1, s1, 0
	s_cmp_gt_u32 vcc_lo, 5
	s_barrier
	s_cbranch_scc0 .LBB0_198
	v_and_b32_e32 v128, 63, v138
	v_mov_b32 v128, v128
	s_or_b32 s0, s74, s81
	v_and_or_b32 v130, v128, 15, s71
	v_ashrrev_i32_e32 v128, 1, v128
	v_and_b32_e32 v128, -8, v128
	v_add_u32_e32 v128, s0, v128
	v_ashrrev_i32_e32 v131, 31, v130
	v_ashrrev_i32_e32 v129, 31, v128
	v_lshlrev_b64 v[132:133], 12, v[130:131]
	v_lshl_add_u64 v[132:133], s[14:15], 0, v[132:133]
	v_lshlrev_b64 v[134:135], 1, v[128:129]
	v_lshl_add_u64 v[128:129], v[132:133], 0, v[134:135]
	v_cvt_pk_bf16_f32 v124, v124, v125
	v_cvt_pk_bf16_f32 v125, v126, v127
	v_cvt_pk_bf16_f32 v126, v120, v121
	v_cvt_pk_bf16_f32 v127, v122, v123
	global_store_dwordx4 v[128:129], v[124:127], off
	v_cvt_pk_bf16_f32 v112, v112, v113
	v_cvt_pk_bf16_f32 v113, v114, v115
	v_cvt_pk_bf16_f32 v114, v104, v105
	v_or_b32_e32 v104, 16, v130
	v_ashrrev_i32_e32 v105, 31, v104
	v_lshlrev_b64 v[104:105], 12, v[104:105]
	v_lshl_add_u64 v[104:105], s[14:15], 0, v[104:105]
	v_cvt_pk_bf16_f32 v115, v106, v107
	global_store_dwordx4 v[128:129], v[112:115], off offset:256
	s_mov_b64 s[0:1], 0x80000
	s_cmpk_lt_u32 s31, 0x100
	v_lshl_add_u64 v[112:113], v[104:105], 0, v[134:135]
	v_cvt_pk_bf16_f32 v104, v116, v117
	v_cvt_pk_bf16_f32 v105, v118, v119
	v_cvt_pk_bf16_f32 v106, v108, v109
	v_cvt_pk_bf16_f32 v107, v110, v111
	global_store_dwordx4 v[112:113], v[104:107], off
	v_cvt_pk_bf16_f32 v96, v96, v97
	v_cvt_pk_bf16_f32 v97, v98, v99
	v_cvt_pk_bf16_f32 v98, v88, v89
	v_or_b32_e32 v88, 32, v130
	v_ashrrev_i32_e32 v89, 31, v88
	v_lshlrev_b64 v[88:89], 12, v[88:89]
	v_lshl_add_u64 v[88:89], s[14:15], 0, v[88:89]
	v_cvt_pk_bf16_f32 v99, v90, v91
	global_store_dwordx4 v[112:113], v[96:99], off offset:256
	s_nop 1
	v_lshl_add_u64 v[96:97], v[88:89], 0, v[134:135]
	v_cvt_pk_bf16_f32 v88, v100, v101
	v_cvt_pk_bf16_f32 v89, v102, v103
	v_cvt_pk_bf16_f32 v90, v92, v93
	v_cvt_pk_bf16_f32 v91, v94, v95
	global_store_dwordx4 v[96:97], v[88:91], off
	v_cvt_pk_bf16_f32 v80, v80, v81
	v_cvt_pk_bf16_f32 v81, v82, v83
	v_cvt_pk_bf16_f32 v82, v72, v73
	v_or_b32_e32 v72, 48, v130
	v_ashrrev_i32_e32 v73, 31, v72
	v_lshlrev_b64 v[72:73], 12, v[72:73]
	v_lshl_add_u64 v[72:73], s[14:15], 0, v[72:73]
	v_cvt_pk_bf16_f32 v83, v74, v75
	global_store_dwordx4 v[96:97], v[80:83], off offset:256
	s_nop 1
	v_lshl_add_u64 v[80:81], v[72:73], 0, v[134:135]
	v_cvt_pk_bf16_f32 v72, v84, v85
	v_cvt_pk_bf16_f32 v73, v86, v87
	v_cvt_pk_bf16_f32 v74, v76, v77
	v_cvt_pk_bf16_f32 v75, v78, v79
	global_store_dwordx4 v[80:81], v[72:75], off
	v_cvt_pk_bf16_f32 v68, v68, v69
	v_cvt_pk_bf16_f32 v69, v70, v71
	v_cvt_pk_bf16_f32 v70, v64, v65
	v_lshl_add_u64 v[64:65], v[128:129], 0, s[0:1]
	s_mov_b32 s0, 0x80000
	v_cvt_pk_bf16_f32 v71, v66, v67
	global_store_dwordx4 v[80:81], v[68:71], off offset:256
	v_cvt_pk_bf16_f32 v60, v60, v61
	v_cvt_pk_bf16_f32 v61, v62, v63
	v_cvt_pk_bf16_f32 v62, v56, v57
	v_add_co_u32_e32 v56, vcc, s0, v128
	v_cvt_pk_bf16_f32 v63, v58, v59
	s_mov_b64 s[0:1], 0x90000
	s_nop 0
	v_addc_co_u32_e32 v57, vcc, 0, v129, vcc
	global_store_dwordx4 v[56:57], v[60:63], off
	v_cvt_pk_bf16_f32 v48, v48, v49
	v_cvt_pk_bf16_f32 v49, v50, v51
	v_cvt_pk_bf16_f32 v50, v40, v41
	v_cvt_pk_bf16_f32 v51, v42, v43
	global_store_dwordx4 v[64:65], v[48:51], off offset:256
	v_cvt_pk_bf16_f32 v40, v52, v53
	v_cvt_pk_bf16_f32 v41, v54, v55
	v_cvt_pk_bf16_f32 v42, v44, v45
	v_cvt_pk_bf16_f32 v43, v46, v47
	s_nop 1
	v_lshl_add_u64 v[48:49], v[128:129], 0, s[0:1]
	s_mov_b32 s0, 0x90000
	v_add_co_u32_e32 v44, vcc, s0, v128
	s_mov_b64 s[0:1], 0xa0000
	s_nop 0
	v_addc_co_u32_e32 v45, vcc, 0, v129, vcc
	global_store_dwordx4 v[44:45], v[40:43], off
	v_cvt_pk_bf16_f32 v32, v32, v33
	v_cvt_pk_bf16_f32 v33, v34, v35
	v_cvt_pk_bf16_f32 v34, v24, v25
	v_cvt_pk_bf16_f32 v35, v26, v27
	global_store_dwordx4 v[48:49], v[32:35], off offset:256
	v_cvt_pk_bf16_f32 v24, v36, v37
	v_cvt_pk_bf16_f32 v25, v38, v39
	v_cvt_pk_bf16_f32 v26, v28, v29
	v_cvt_pk_bf16_f32 v27, v30, v31
	s_nop 1
	v_lshl_add_u64 v[32:33], v[128:129], 0, s[0:1]
	s_mov_b32 s0, 0xa0000
	v_add_co_u32_e32 v28, vcc, s0, v128
	s_mov_b64 s[0:1], 0xb0000
	s_nop 0
	v_addc_co_u32_e32 v29, vcc, 0, v129, vcc
	global_store_dwordx4 v[28:29], v[24:27], off
	v_cvt_pk_bf16_f32 v16, v16, v17
	v_cvt_pk_bf16_f32 v17, v18, v19
	v_cvt_pk_bf16_f32 v18, v8, v9
	v_cvt_pk_bf16_f32 v19, v10, v11
	global_store_dwordx4 v[32:33], v[16:19], off offset:256
	v_cvt_pk_bf16_f32 v8, v20, v21
	v_cvt_pk_bf16_f32 v9, v22, v23
	v_cvt_pk_bf16_f32 v10, v12, v13
	v_cvt_pk_bf16_f32 v11, v14, v15
	s_nop 1
	v_lshl_add_u64 v[16:17], v[128:129], 0, s[0:1]
	s_mov_b32 s0, 0xb0000
	v_add_co_u32_e32 v12, vcc, s0, v128
	s_nop 1
	v_addc_co_u32_e32 v13, vcc, 0, v129, vcc
	global_store_dwordx4 v[12:13], v[8:11], off
	v_cvt_pk_bf16_f32 v4, v4, v5
	v_cvt_pk_bf16_f32 v5, v6, v7
	v_cvt_pk_bf16_f32 v6, v0, v1
	v_cvt_pk_bf16_f32 v7, v2, v3
	global_store_dwordx4 v[16:17], v[4:7], off offset:256
	s_waitcnt vmcnt(0)
	s_cbranch_scc0 .LBB0_201
	s_barrier

.LBB0_242:
	v_add_u32_e32 v138, 0x10000, v141
	ds_read_b128 v[144:147], v138
	ds_read_b128 v[148:151], v138 offset:1024
	ds_read_b128 v[152:155], v138 offset:2048
	ds_read_b128 v[156:159], v138 offset:3072
	ds_read_b128 v[160:163], v142
	ds_read_b128 v[164:167], v142 offset:1024
	ds_read_b128 v[168:171], v142 offset:2048
	ds_read_b128 v[172:175], v142 offset:3072
	ds_read_b128 v[176:179], v142 offset:4096
	ds_read_b128 v[180:183], v142 offset:5120
	ds_read_b128 v[184:187], v142 offset:6144
	ds_read_b128 v[188:191], v142 offset:7168
	v_add_u32_e32 v138, 0x14000, v141
	ds_read_b128 v[194:197], v138
	ds_read_b128 v[198:201], v138 offset:1024
	ds_read_b128 v[202:205], v138 offset:2048
	ds_read_b128 v[206:209], v138 offset:3072
	s_add_i32 s79, s4, 2
	s_add_u32 s5, s2, 0xffe00080
	s_addc_u32 s9, s3, -1
	s_add_i32 s46, 0, 0x10000
	s_cmp_eq_u32 s64, s4
	s_cselect_b32 s4, s36, s75
	s_cselect_b32 s39, s29, s9
	s_cselect_b32 s38, s28, s5
	s_cselect_b32 s5, s37, s78
	v_lshl_add_u64 v[138:139], s[2:3], 0, v[134:135]
	s_add_i32 m0, s50, 0xc000
	s_nop 0
	global_load_lds_dwordx4 v[138:139], off
	v_lshl_add_u64 v[138:139], s[2:3], 0, v[136:137]
	s_add_i32 m0, s50, 0xe000
	s_nop 0
	global_load_lds_dwordx4 v[138:139], off
	s_waitcnt vmcnt(8)
	s_waitcnt lgkmcnt(0)
	s_barrier
	s_setprio 1
	v_mfma_f32_16x16x32_bf16 v[124:127], v[144:147], v[160:163], v[124:127]
	v_mfma_f32_16x16x32_bf16 v[120:123], v[152:155], v[160:163], v[120:123]
	v_mfma_f32_16x16x32_bf16 v[116:119], v[144:147], v[168:171], v[116:119]
	v_mfma_f32_16x16x32_bf16 v[108:111], v[152:155], v[168:171], v[108:111]
	v_mfma_f32_16x16x32_bf16 v[100:103], v[144:147], v[176:179], v[100:103]
	v_mfma_f32_16x16x32_bf16 v[92:95], v[152:155], v[176:179], v[92:95]
	v_mfma_f32_16x16x32_bf16 v[84:87], v[144:147], v[184:187], v[84:87]
	v_mfma_f32_16x16x32_bf16 v[76:79], v[152:155], v[184:187], v[76:79]
	v_mfma_f32_16x16x32_bf16 v[124:127], v[148:151], v[164:167], v[124:127]
	v_mfma_f32_16x16x32_bf16 v[120:123], v[156:159], v[164:167], v[120:123]
	v_mfma_f32_16x16x32_bf16 v[116:119], v[148:151], v[172:175], v[116:119]
	v_mfma_f32_16x16x32_bf16 v[108:111], v[156:159], v[172:175], v[108:111]
	v_mfma_f32_16x16x32_bf16 v[100:103], v[148:151], v[180:183], v[100:103]
	v_mfma_f32_16x16x32_bf16 v[92:95], v[156:159], v[180:183], v[92:95]
	v_mfma_f32_16x16x32_bf16 v[84:87], v[148:151], v[188:191], v[84:87]
	v_mfma_f32_16x16x32_bf16 v[76:79], v[156:159], v[188:191], v[76:79]
	v_mfma_f32_16x16x32_bf16 v[112:115], v[194:197], v[160:163], v[112:115]
	v_mfma_f32_16x16x32_bf16 v[104:107], v[202:205], v[160:163], v[104:107]
	v_mfma_f32_16x16x32_bf16 v[96:99], v[194:197], v[168:171], v[96:99]
	v_mfma_f32_16x16x32_bf16 v[88:91], v[202:205], v[168:171], v[88:91]
	v_mfma_f32_16x16x32_bf16 v[80:83], v[194:197], v[176:179], v[80:83]
	v_mfma_f32_16x16x32_bf16 v[72:75], v[202:205], v[176:179], v[72:75]
	v_mfma_f32_16x16x32_bf16 v[68:71], v[194:197], v[184:187], v[68:71]
	v_mfma_f32_16x16x32_bf16 v[64:67], v[202:205], v[184:187], v[64:67]
	v_mfma_f32_16x16x32_bf16 v[112:115], v[198:201], v[164:167], v[112:115]
	v_mfma_f32_16x16x32_bf16 v[104:107], v[206:209], v[164:167], v[104:107]
	v_mfma_f32_16x16x32_bf16 v[96:99], v[198:201], v[172:175], v[96:99]
	v_mfma_f32_16x16x32_bf16 v[88:91], v[206:209], v[172:175], v[88:91]
	v_mfma_f32_16x16x32_bf16 v[80:83], v[198:201], v[180:183], v[80:83]
	v_mfma_f32_16x16x32_bf16 v[72:75], v[206:209], v[180:183], v[72:75]
	v_mfma_f32_16x16x32_bf16 v[68:71], v[198:201], v[188:191], v[68:71]
	v_mfma_f32_16x16x32_bf16 v[64:67], v[206:209], v[188:191], v[64:67]
	s_setprio 0
	s_barrier
	ds_read_b128 v[160:163], v142 offset:16384
	ds_read_b128 v[164:167], v142 offset:17408
	ds_read_b128 v[168:171], v142 offset:18432
	ds_read_b128 v[172:175], v142 offset:19456
	ds_read_b128 v[176:179], v142 offset:20480
	ds_read_b128 v[180:183], v142 offset:21504
	ds_read_b128 v[184:187], v142 offset:22528
	ds_read_b128 v[188:191], v142 offset:23552
	s_add_i32 s9, 0, 0x14000
	s_add_i32 s46, s46, s49
	v_lshl_add_u64 v[138:139], s[4:5], 0, v[192:193]
	s_mov_b32 m0, s46
	v_lshl_add_u64 v[210:211], s[4:5], 0, v[132:133]
	global_load_lds_dwordx4 v[138:139], off
	s_add_i32 m0, s46, 0x2000
	s_nop 0
	global_load_lds_dwordx4 v[210:211], off
	s_mov_b32 m0, s50
	v_lshl_add_u64 v[212:213], s[38:39], 0, v[128:129]
	global_load_lds_dwordx4 v[212:213], off
	v_lshl_add_u64 v[214:215], s[38:39], 0, v[130:131]
	s_mov_b32 m0, s51
	s_nop 0
	global_load_lds_dwordx4 v[214:215], off
	s_add_u32 s46, s4, 0x200000
	s_addc_u32 s47, s5, 0
	s_add_i32 s9, s9, s49
	v_lshl_add_u64 v[218:219], s[46:47], 0, v[192:193]
	s_mov_b32 m0, s9
	s_nop 0
	global_load_lds_dwordx4 v[218:219], off
	v_lshl_add_u64 v[220:221], s[46:47], 0, v[132:133]
	s_add_i32 m0, s9, 0x2000
	s_nop 0
	global_load_lds_dwordx4 v[220:221], off
	s_waitcnt vmcnt(8)
	s_waitcnt lgkmcnt(0)
	s_barrier
	s_setprio 1
	v_mfma_f32_16x16x32_bf16 v[60:63], v[144:147], v[160:163], v[60:63]
	v_mfma_f32_16x16x32_bf16 v[56:59], v[152:155], v[160:163], v[56:59]
	v_mfma_f32_16x16x32_bf16 v[52:55], v[144:147], v[168:171], v[52:55]
	v_mfma_f32_16x16x32_bf16 v[44:47], v[152:155], v[168:171], v[44:47]
	v_mfma_f32_16x16x32_bf16 v[36:39], v[144:147], v[176:179], v[36:39]
	v_mfma_f32_16x16x32_bf16 v[28:31], v[152:155], v[176:179], v[28:31]
	v_mfma_f32_16x16x32_bf16 v[20:23], v[144:147], v[184:187], v[20:23]
	v_mfma_f32_16x16x32_bf16 v[12:15], v[152:155], v[184:187], v[12:15]
	v_mfma_f32_16x16x32_bf16 v[60:63], v[148:151], v[164:167], v[60:63]
	v_mfma_f32_16x16x32_bf16 v[56:59], v[156:159], v[164:167], v[56:59]
	v_mfma_f32_16x16x32_bf16 v[52:55], v[148:151], v[172:175], v[52:55]
	v_mfma_f32_16x16x32_bf16 v[44:47], v[156:159], v[172:175], v[44:47]
	v_mfma_f32_16x16x32_bf16 v[36:39], v[148:151], v[180:183], v[36:39]
	v_mfma_f32_16x16x32_bf16 v[28:31], v[156:159], v[180:183], v[28:31]
	v_mfma_f32_16x16x32_bf16 v[20:23], v[148:151], v[188:191], v[20:23]
	v_mfma_f32_16x16x32_bf16 v[12:15], v[156:159], v[188:191], v[12:15]
	v_mfma_f32_16x16x32_bf16 v[48:51], v[194:197], v[160:163], v[48:51]
	v_mfma_f32_16x16x32_bf16 v[40:43], v[202:205], v[160:163], v[40:43]
	v_mfma_f32_16x16x32_bf16 v[32:35], v[194:197], v[168:171], v[32:35]
	v_mfma_f32_16x16x32_bf16 v[24:27], v[202:205], v[168:171], v[24:27]
	v_mfma_f32_16x16x32_bf16 v[16:19], v[194:197], v[176:179], v[16:19]
	v_mfma_f32_16x16x32_bf16 v[8:11], v[202:205], v[176:179], v[8:11]
	v_mfma_f32_16x16x32_bf16 v[4:7], v[194:197], v[184:187], v[4:7]
	v_mfma_f32_16x16x32_bf16 v[0:3], v[202:205], v[184:187], v[0:3]
	v_mfma_f32_16x16x32_bf16 v[48:51], v[198:201], v[164:167], v[48:51]
	v_mfma_f32_16x16x32_bf16 v[40:43], v[206:209], v[164:167], v[40:43]
	v_mfma_f32_16x16x32_bf16 v[32:35], v[198:201], v[172:175], v[32:35]
	v_mfma_f32_16x16x32_bf16 v[24:27], v[206:209], v[172:175], v[24:27]
	v_mfma_f32_16x16x32_bf16 v[16:19], v[198:201], v[180:183], v[16:19]
	v_mfma_f32_16x16x32_bf16 v[8:11], v[206:209], v[180:183], v[8:11]
	v_mfma_f32_16x16x32_bf16 v[4:7], v[198:201], v[188:191], v[4:7]
	v_mfma_f32_16x16x32_bf16 v[0:3], v[206:209], v[188:191], v[0:3]
	s_setprio 0
	s_barrier
	v_add_u32_e32 v143, 0x18000, v141
	ds_read_b128 v[144:147], v143
	ds_read_b128 v[148:151], v143 offset:1024
	ds_read_b128 v[152:155], v143 offset:2048
	ds_read_b128 v[156:159], v143 offset:3072
	ds_read_b128 v[160:163], v142 offset:32768
	ds_read_b128 v[164:167], v142 offset:33792
	ds_read_b128 v[168:171], v142 offset:34816
	ds_read_b128 v[172:175], v142 offset:35840
	ds_read_b128 v[176:179], v142 offset:36864
	ds_read_b128 v[180:183], v142 offset:37888
	ds_read_b128 v[184:187], v142 offset:38912
	ds_read_b128 v[188:191], v142 offset:39936
	v_add_u32_e32 v143, 0x1c000, v141
	ds_read_b128 v[194:197], v143
	ds_read_b128 v[198:201], v143 offset:1024
	ds_read_b128 v[202:205], v143 offset:2048
	ds_read_b128 v[206:209], v143 offset:3072
	s_add_i32 s9, 0, 0x18000
	s_add_u32 s38, s38, 0x200000
	s_addc_u32 s39, s39, 0
	s_mov_b32 m0, s52
	v_lshl_add_u64 v[218:219], s[38:39], 0, v[128:129]
	global_load_lds_dwordx4 v[218:219], off
	v_lshl_add_u64 v[220:221], s[38:39], 0, v[130:131]
	s_mov_b32 m0, s53
	s_nop 0
	global_load_lds_dwordx4 v[220:221], off
	s_waitcnt vmcnt(8)
	s_waitcnt lgkmcnt(0)
	s_barrier
	s_setprio 1
	v_mfma_f32_16x16x32_bf16 v[124:127], v[144:147], v[160:163], v[124:127]
	v_mfma_f32_16x16x32_bf16 v[120:123], v[152:155], v[160:163], v[120:123]
	v_mfma_f32_16x16x32_bf16 v[116:119], v[144:147], v[168:171], v[116:119]
	v_mfma_f32_16x16x32_bf16 v[108:111], v[152:155], v[168:171], v[108:111]
	v_mfma_f32_16x16x32_bf16 v[100:103], v[144:147], v[176:179], v[100:103]
	v_mfma_f32_16x16x32_bf16 v[92:95], v[152:155], v[176:179], v[92:95]
	v_mfma_f32_16x16x32_bf16 v[84:87], v[144:147], v[184:187], v[84:87]
	v_mfma_f32_16x16x32_bf16 v[76:79], v[152:155], v[184:187], v[76:79]
	v_mfma_f32_16x16x32_bf16 v[124:127], v[148:151], v[164:167], v[124:127]
	v_mfma_f32_16x16x32_bf16 v[120:123], v[156:159], v[164:167], v[120:123]
	v_mfma_f32_16x16x32_bf16 v[116:119], v[148:151], v[172:175], v[116:119]
	v_mfma_f32_16x16x32_bf16 v[108:111], v[156:159], v[172:175], v[108:111]
	v_mfma_f32_16x16x32_bf16 v[100:103], v[148:151], v[180:183], v[100:103]
	v_mfma_f32_16x16x32_bf16 v[92:95], v[156:159], v[180:183], v[92:95]
	v_mfma_f32_16x16x32_bf16 v[84:87], v[148:151], v[188:191], v[84:87]
	v_mfma_f32_16x16x32_bf16 v[76:79], v[156:159], v[188:191], v[76:79]
	v_mfma_f32_16x16x32_bf16 v[112:115], v[194:197], v[160:163], v[112:115]
	v_mfma_f32_16x16x32_bf16 v[104:107], v[202:205], v[160:163], v[104:107]
	v_mfma_f32_16x16x32_bf16 v[96:99], v[194:197], v[168:171], v[96:99]
	v_mfma_f32_16x16x32_bf16 v[88:91], v[202:205], v[168:171], v[88:91]
	v_mfma_f32_16x16x32_bf16 v[80:83], v[194:197], v[176:179], v[80:83]
	v_mfma_f32_16x16x32_bf16 v[72:75], v[202:205], v[176:179], v[72:75]
	v_mfma_f32_16x16x32_bf16 v[68:71], v[194:197], v[184:187], v[68:71]
	v_mfma_f32_16x16x32_bf16 v[64:67], v[202:205], v[184:187], v[64:67]
	v_mfma_f32_16x16x32_bf16 v[112:115], v[198:201], v[164:167], v[112:115]
	v_mfma_f32_16x16x32_bf16 v[104:107], v[206:209], v[164:167], v[104:107]
	v_mfma_f32_16x16x32_bf16 v[96:99], v[198:201], v[172:175], v[96:99]
	v_mfma_f32_16x16x32_bf16 v[88:91], v[206:209], v[172:175], v[88:91]
	v_mfma_f32_16x16x32_bf16 v[80:83], v[198:201], v[180:183], v[80:83]
	v_mfma_f32_16x16x32_bf16 v[72:75], v[206:209], v[180:183], v[72:75]
	v_mfma_f32_16x16x32_bf16 v[68:71], v[198:201], v[188:191], v[68:71]
	v_mfma_f32_16x16x32_bf16 v[64:67], v[206:209], v[188:191], v[64:67]
	s_setprio 0
	s_barrier
	ds_read_b128 v[160:163], v142 offset:49152
	ds_read_b128 v[164:167], v142 offset:50176
	ds_read_b128 v[168:171], v142 offset:51200
	ds_read_b128 v[172:175], v142 offset:52224
	ds_read_b128 v[176:179], v142 offset:53248
	ds_read_b128 v[180:183], v142 offset:54272
	ds_read_b128 v[184:187], v142 offset:55296
	ds_read_b128 v[188:191], v142 offset:56320
	s_add_i32 s38, 0, 0x1c000
	s_add_i32 s9, s9, s49
	v_lshl_add_u64 v[138:139], v[138:139], 0, s[72:73]
	s_mov_b32 m0, s9
	s_nop 0
	global_load_lds_dwordx4 v[138:139], off
	v_lshl_add_u64 v[138:139], v[210:211], 0, s[72:73]
	s_add_i32 m0, s9, 0x2000
	s_nop 0
	global_load_lds_dwordx4 v[138:139], off
	s_mov_b32 m0, s54
	v_lshl_add_u64 v[138:139], v[212:213], 0, s[72:73]
	global_load_lds_dwordx4 v[138:139], off
	v_lshl_add_u64 v[138:139], v[214:215], 0, s[72:73]
	s_mov_b32 m0, s55
	s_nop 0
	global_load_lds_dwordx4 v[138:139], off
	s_add_u32 s4, s4, 0x200080
	s_addc_u32 s5, s5, 0
	s_add_i32 s9, s38, s49
	v_lshl_add_u64 v[138:139], s[4:5], 0, v[192:193]
	s_mov_b32 m0, s9
	s_nop 0
	global_load_lds_dwordx4 v[138:139], off
	v_lshl_add_u64 v[138:139], s[4:5], 0, v[132:133]
	s_add_i32 m0, s9, 0x2000
	s_nop 0
	global_load_lds_dwordx4 v[138:139], off
	s_waitcnt vmcnt(8)
	s_waitcnt lgkmcnt(0)
	s_barrier
	s_setprio 1
	v_mfma_f32_16x16x32_bf16 v[60:63], v[144:147], v[160:163], v[60:63]
	v_mfma_f32_16x16x32_bf16 v[56:59], v[152:155], v[160:163], v[56:59]
	v_mfma_f32_16x16x32_bf16 v[52:55], v[144:147], v[168:171], v[52:55]
	v_mfma_f32_16x16x32_bf16 v[44:47], v[152:155], v[168:171], v[44:47]
	v_mfma_f32_16x16x32_bf16 v[36:39], v[144:147], v[176:179], v[36:39]
	v_mfma_f32_16x16x32_bf16 v[28:31], v[152:155], v[176:179], v[28:31]
	v_mfma_f32_16x16x32_bf16 v[20:23], v[144:147], v[184:187], v[20:23]
	v_mfma_f32_16x16x32_bf16 v[12:15], v[152:155], v[184:187], v[12:15]
	v_mfma_f32_16x16x32_bf16 v[60:63], v[148:151], v[164:167], v[60:63]
	v_mfma_f32_16x16x32_bf16 v[56:59], v[156:159], v[164:167], v[56:59]
	v_mfma_f32_16x16x32_bf16 v[52:55], v[148:151], v[172:175], v[52:55]
	v_mfma_f32_16x16x32_bf16 v[44:47], v[156:159], v[172:175], v[44:47]
	v_mfma_f32_16x16x32_bf16 v[36:39], v[148:151], v[180:183], v[36:39]
	v_mfma_f32_16x16x32_bf16 v[28:31], v[156:159], v[180:183], v[28:31]
	v_mfma_f32_16x16x32_bf16 v[20:23], v[148:151], v[188:191], v[20:23]
	v_mfma_f32_16x16x32_bf16 v[12:15], v[156:159], v[188:191], v[12:15]
	v_mfma_f32_16x16x32_bf16 v[48:51], v[194:197], v[160:163], v[48:51]
	v_mfma_f32_16x16x32_bf16 v[40:43], v[202:205], v[160:163], v[40:43]
	v_mfma_f32_16x16x32_bf16 v[32:35], v[194:197], v[168:171], v[32:35]
	v_mfma_f32_16x16x32_bf16 v[24:27], v[202:205], v[168:171], v[24:27]
	v_mfma_f32_16x16x32_bf16 v[16:19], v[194:197], v[176:179], v[16:19]
	v_mfma_f32_16x16x32_bf16 v[8:11], v[202:205], v[176:179], v[8:11]
	v_mfma_f32_16x16x32_bf16 v[4:7], v[194:197], v[184:187], v[4:7]
	v_mfma_f32_16x16x32_bf16 v[0:3], v[202:205], v[184:187], v[0:3]
	v_mfma_f32_16x16x32_bf16 v[48:51], v[198:201], v[164:167], v[48:51]
	v_mfma_f32_16x16x32_bf16 v[40:43], v[206:209], v[164:167], v[40:43]
	v_mfma_f32_16x16x32_bf16 v[32:35], v[198:201], v[172:175], v[32:35]
	v_mfma_f32_16x16x32_bf16 v[24:27], v[206:209], v[172:175], v[24:27]
	v_mfma_f32_16x16x32_bf16 v[16:19], v[198:201], v[180:183], v[16:19]
	v_mfma_f32_16x16x32_bf16 v[8:11], v[206:209], v[180:183], v[8:11]
	v_mfma_f32_16x16x32_bf16 v[4:7], v[198:201], v[188:191], v[4:7]
	v_mfma_f32_16x16x32_bf16 v[0:3], v[206:209], v[188:191], v[0:3]
	s_setprio 0
	s_add_u32 s2, s2, 0x100
	s_addc_u32 s3, s3, 0
	s_add_u32 s75, s75, 0x100
	s_addc_u32 s78, s78, 0
	s_cmp_ge_i32 s79, s71
	s_mov_b32 s4, s79
	s_barrier
	s_cbranch_scc0 .LBB0_242
	v_sub_co_u32_e64 v138, s[2:3], s74, 1
	s_nop 0
	v_readfirstlane_b32 s64, v138
	s_lshl_b64 s[4:5], s[64:65], 22
	v_readlane_b32 s38, v252, 9
	v_readlane_b32 s39, v252, 10
	s_add_u32 s4, s38, s4
	s_addc_u32 s5, s39, s5
	s_sub_i32 s9, s69, 32
	s_and_b64 s[2:3], s[2:3], exec
	v_readlane_b32 s38, v252, 7
	s_cselect_b32 s2, s69, s9
	v_readlane_b32 s39, v252, 8
	s_cselect_b32 s5, s39, s5
	s_cselect_b32 s4, s38, s4
	s_ashr_i32 s3, s2, 31
	s_lshl_b64 s[2:3], s[2:3], 20
	s_add_u32 s2, s4, s2
	v_mov_b32 v139, v140
	s_addc_u32 s3, s5, s3
	v_ashrrev_i32_e32 v138, 1, v139
	s_lshl_b32 s4, s66, 8
	v_and_b32_e32 v138, -8, v138
	s_or_b32 s4, s4, s59
	v_add_u32_e32 v138, s4, v138
	v_and_or_b32 v144, v139, 15, s58
	v_ashrrev_i32_e32 v139, 31, v138
	v_ashrrev_i32_e32 v145, 31, v144
	v_lshl_add_u64 v[146:147], v[138:139], 1, s[2:3]
	v_lshlrev_b64 v[138:139], 12, v[144:145]
	v_lshl_add_u64 v[138:139], v[146:147], 0, v[138:139]
	v_cvt_pk_bf16_f32 v124, v124, v125
	v_cvt_pk_bf16_f32 v125, v126, v127
	v_cvt_pk_bf16_f32 v126, v120, v121
	v_cvt_pk_bf16_f32 v127, v122, v123
	global_store_dwordx4 v[138:139], v[124:127], off
	v_cvt_pk_bf16_f32 v112, v112, v113
	v_cvt_pk_bf16_f32 v113, v114, v115
	v_cvt_pk_bf16_f32 v114, v104, v105
	v_or_b32_e32 v104, 16, v144
	v_ashrrev_i32_e32 v105, 31, v104
	v_lshlrev_b64 v[104:105], 12, v[104:105]
	v_cvt_pk_bf16_f32 v115, v106, v107
	global_store_dwordx4 v[138:139], v[112:115], off offset:256
	s_mov_b64 s[2:3], 0x80000
	s_mov_b32 s66, s63
	v_lshl_add_u64 v[112:113], v[146:147], 0, v[104:105]
	v_cvt_pk_bf16_f32 v104, v116, v117
	v_cvt_pk_bf16_f32 v105, v118, v119
	v_cvt_pk_bf16_f32 v106, v108, v109
	v_cvt_pk_bf16_f32 v107, v110, v111
	global_store_dwordx4 v[112:113], v[104:107], off
	v_cvt_pk_bf16_f32 v96, v96, v97
	v_cvt_pk_bf16_f32 v97, v98, v99
	v_cvt_pk_bf16_f32 v98, v88, v89
	v_or_b32_e32 v88, 32, v144
	v_ashrrev_i32_e32 v89, 31, v88
	v_lshlrev_b64 v[88:89], 12, v[88:89]
	v_cvt_pk_bf16_f32 v99, v90, v91
	global_store_dwordx4 v[112:113], v[96:99], off offset:256
	s_mov_b32 s69, s34
	s_mov_b32 s74, s35
	v_lshl_add_u64 v[96:97], v[146:147], 0, v[88:89]
	v_cvt_pk_bf16_f32 v88, v100, v101
	v_cvt_pk_bf16_f32 v89, v102, v103
	v_cvt_pk_bf16_f32 v90, v92, v93
	v_cvt_pk_bf16_f32 v91, v94, v95
	global_store_dwordx4 v[96:97], v[88:91], off
	v_cvt_pk_bf16_f32 v80, v80, v81
	v_cvt_pk_bf16_f32 v81, v82, v83
	v_cvt_pk_bf16_f32 v82, v72, v73
	v_or_b32_e32 v72, 48, v144
	v_ashrrev_i32_e32 v73, 31, v72
	v_lshlrev_b64 v[72:73], 12, v[72:73]
	v_cvt_pk_bf16_f32 v83, v74, v75
	global_store_dwordx4 v[96:97], v[80:83], off offset:256
	s_mov_b32 s71, s67
	s_mov_b64 s[4:5], s[36:37]
	v_lshl_add_u64 v[80:81], v[146:147], 0, v[72:73]
	v_cvt_pk_bf16_f32 v72, v84, v85
	v_cvt_pk_bf16_f32 v73, v86, v87
	v_cvt_pk_bf16_f32 v74, v76, v77
	v_cvt_pk_bf16_f32 v75, v78, v79
	global_store_dwordx4 v[80:81], v[72:75], off
	v_cvt_pk_bf16_f32 v68, v68, v69
	v_cvt_pk_bf16_f32 v69, v70, v71
	v_cvt_pk_bf16_f32 v70, v64, v65
	v_lshl_add_u64 v[64:65], v[138:139], 0, s[2:3]
	s_mov_b32 s2, 0x80000
	v_cvt_pk_bf16_f32 v71, v66, v67
	global_store_dwordx4 v[80:81], v[68:71], off offset:256
	v_cvt_pk_bf16_f32 v60, v60, v61
	v_cvt_pk_bf16_f32 v61, v62, v63
	v_cvt_pk_bf16_f32 v62, v56, v57
	v_add_co_u32_e32 v56, vcc, s2, v138
	v_cvt_pk_bf16_f32 v63, v58, v59
	s_mov_b64 s[2:3], 0x90000
	s_nop 0
	v_addc_co_u32_e32 v57, vcc, 0, v139, vcc
	global_store_dwordx4 v[56:57], v[60:63], off
	v_cvt_pk_bf16_f32 v48, v48, v49
	v_cvt_pk_bf16_f32 v49, v50, v51
	v_cvt_pk_bf16_f32 v50, v40, v41
	v_cvt_pk_bf16_f32 v51, v42, v43
	global_store_dwordx4 v[64:65], v[48:51], off offset:256
	v_cvt_pk_bf16_f32 v40, v52, v53
	v_cvt_pk_bf16_f32 v41, v54, v55
	v_cvt_pk_bf16_f32 v42, v44, v45
	v_cvt_pk_bf16_f32 v43, v46, v47
	s_mov_b64 s[78:79], 0x2000
	s_nop 0
	v_lshl_add_u64 v[48:49], v[138:139], 0, s[2:3]
	s_mov_b32 s2, 0x90000
	v_add_co_u32_e32 v44, vcc, s2, v138
	s_mov_b64 s[2:3], 0xa0000
	s_nop 0
	v_addc_co_u32_e32 v45, vcc, 0, v139, vcc
	global_store_dwordx4 v[44:45], v[40:43], off
	v_cvt_pk_bf16_f32 v32, v32, v33
	v_cvt_pk_bf16_f32 v33, v34, v35
	v_cvt_pk_bf16_f32 v34, v24, v25
	v_cvt_pk_bf16_f32 v35, v26, v27
	global_store_dwordx4 v[48:49], v[32:35], off offset:256
	v_cvt_pk_bf16_f32 v24, v36, v37
	v_cvt_pk_bf16_f32 v25, v38, v39
	v_cvt_pk_bf16_f32 v26, v28, v29
	v_cvt_pk_bf16_f32 v27, v30, v31
	s_nop 1
	v_lshl_add_u64 v[32:33], v[138:139], 0, s[2:3]
	s_mov_b32 s2, 0xa0000
	v_add_co_u32_e32 v28, vcc, s2, v138
	s_mov_b64 s[2:3], 0xb0000
	s_nop 0
	v_addc_co_u32_e32 v29, vcc, 0, v139, vcc
	global_store_dwordx4 v[28:29], v[24:27], off
	v_cvt_pk_bf16_f32 v16, v16, v17
	v_cvt_pk_bf16_f32 v17, v18, v19
	v_cvt_pk_bf16_f32 v18, v8, v9
	v_cvt_pk_bf16_f32 v19, v10, v11
	global_store_dwordx4 v[32:33], v[16:19], off offset:256
	v_cvt_pk_bf16_f32 v8, v20, v21
	v_cvt_pk_bf16_f32 v9, v22, v23
	v_cvt_pk_bf16_f32 v10, v12, v13
	v_cvt_pk_bf16_f32 v11, v14, v15
	s_nop 1
	v_lshl_add_u64 v[16:17], v[138:139], 0, s[2:3]
	s_mov_b32 s2, 0xb0000
	v_add_co_u32_e32 v12, vcc, s2, v138
	s_mov_b64 s[2:3], s[28:29]
	s_nop 0
	v_addc_co_u32_e32 v13, vcc, 0, v139, vcc
	s_and_b64 vcc, exec, s[14:15]
	global_store_dwordx4 v[12:13], v[8:11], off
	v_cvt_pk_bf16_f32 v4, v4, v5
	v_cvt_pk_bf16_f32 v5, v6, v7
	v_cvt_pk_bf16_f32 v6, v0, v1
	v_cvt_pk_bf16_f32 v7, v2, v3
	global_store_dwordx4 v[16:17], v[4:7], off offset:256
	s_cbranch_vccz .LBB0_232
	s_waitcnt vmcnt(0)
	s_cmpk_gt_u32 s40, 0xff
	s_cbranch_scc1 .LBB0_246
	s_barrier

.LBB0_256:
	v_add_u32_e32 v138, 0x10000, v141
	ds_read_b128 v[144:147], v138
	ds_read_b128 v[148:151], v138 offset:1024
	ds_read_b128 v[152:155], v138 offset:2048
	ds_read_b128 v[156:159], v138 offset:3072
	ds_read_b128 v[160:163], v142
	ds_read_b128 v[164:167], v142 offset:1024
	ds_read_b128 v[168:171], v142 offset:2048
	ds_read_b128 v[172:175], v142 offset:3072
	ds_read_b128 v[176:179], v142 offset:4096
	ds_read_b128 v[180:183], v142 offset:5120
	ds_read_b128 v[184:187], v142 offset:6144
	ds_read_b128 v[188:191], v142 offset:7168
	v_add_u32_e32 v138, 0x14000, v141
	ds_read_b128 v[194:197], v138
	ds_read_b128 v[198:201], v138 offset:1024
	ds_read_b128 v[202:205], v138 offset:2048
	ds_read_b128 v[206:209], v138 offset:3072
	s_add_u32 s4, s2, 0xfff80080
	s_addc_u32 s5, s3, -1
	s_add_i32 s9, 0, 0x10000
	s_cmp_eq_u32 s69, 28
	s_cselect_b32 s49, s35, s5
	s_cselect_b32 s48, s34, s4
	s_cselect_b32 s5, s37, s29
	s_cselect_b32 s4, s36, s15
	v_lshl_add_u64 v[138:139], s[2:3], 0, v[134:135]
	s_add_i32 m0, s39, 0xc000
	s_nop 0
	global_load_lds_dwordx4 v[138:139], off
	v_lshl_add_u64 v[138:139], s[2:3], 0, v[136:137]
	s_add_i32 m0, s39, 0xe000
	s_nop 0
	global_load_lds_dwordx4 v[138:139], off
	s_waitcnt vmcnt(8)
	s_waitcnt lgkmcnt(0)
	s_barrier
	s_setprio 1
	v_mfma_f32_16x16x32_bf16 v[124:127], v[144:147], v[160:163], v[124:127]
	v_mfma_f32_16x16x32_bf16 v[120:123], v[152:155], v[160:163], v[120:123]
	v_mfma_f32_16x16x32_bf16 v[108:111], v[144:147], v[168:171], v[108:111]
	v_mfma_f32_16x16x32_bf16 v[104:107], v[152:155], v[168:171], v[104:107]
	v_mfma_f32_16x16x32_bf16 v[92:95], v[144:147], v[176:179], v[92:95]
	v_mfma_f32_16x16x32_bf16 v[88:91], v[152:155], v[176:179], v[88:91]
	v_mfma_f32_16x16x32_bf16 v[76:79], v[144:147], v[184:187], v[76:79]
	v_mfma_f32_16x16x32_bf16 v[72:75], v[152:155], v[184:187], v[72:75]
	v_mfma_f32_16x16x32_bf16 v[124:127], v[148:151], v[164:167], v[124:127]
	v_mfma_f32_16x16x32_bf16 v[120:123], v[156:159], v[164:167], v[120:123]
	v_mfma_f32_16x16x32_bf16 v[108:111], v[148:151], v[172:175], v[108:111]
	v_mfma_f32_16x16x32_bf16 v[104:107], v[156:159], v[172:175], v[104:107]
	v_mfma_f32_16x16x32_bf16 v[92:95], v[148:151], v[180:183], v[92:95]
	v_mfma_f32_16x16x32_bf16 v[88:91], v[156:159], v[180:183], v[88:91]
	v_mfma_f32_16x16x32_bf16 v[76:79], v[148:151], v[188:191], v[76:79]
	v_mfma_f32_16x16x32_bf16 v[72:75], v[156:159], v[188:191], v[72:75]
	v_mfma_f32_16x16x32_bf16 v[116:119], v[194:197], v[160:163], v[116:119]
	v_mfma_f32_16x16x32_bf16 v[112:115], v[202:205], v[160:163], v[112:115]
	v_mfma_f32_16x16x32_bf16 v[100:103], v[194:197], v[168:171], v[100:103]
	v_mfma_f32_16x16x32_bf16 v[96:99], v[202:205], v[168:171], v[96:99]
	v_mfma_f32_16x16x32_bf16 v[84:87], v[194:197], v[176:179], v[84:87]
	v_mfma_f32_16x16x32_bf16 v[80:83], v[202:205], v[176:179], v[80:83]
	v_mfma_f32_16x16x32_bf16 v[68:71], v[194:197], v[184:187], v[68:71]
	v_mfma_f32_16x16x32_bf16 v[64:67], v[202:205], v[184:187], v[64:67]
	v_mfma_f32_16x16x32_bf16 v[116:119], v[198:201], v[164:167], v[116:119]
	v_mfma_f32_16x16x32_bf16 v[112:115], v[206:209], v[164:167], v[112:115]
	v_mfma_f32_16x16x32_bf16 v[100:103], v[198:201], v[172:175], v[100:103]
	v_mfma_f32_16x16x32_bf16 v[96:99], v[206:209], v[172:175], v[96:99]
	v_mfma_f32_16x16x32_bf16 v[84:87], v[198:201], v[180:183], v[84:87]
	v_mfma_f32_16x16x32_bf16 v[80:83], v[206:209], v[180:183], v[80:83]
	v_mfma_f32_16x16x32_bf16 v[68:71], v[198:201], v[188:191], v[68:71]
	v_mfma_f32_16x16x32_bf16 v[64:67], v[206:209], v[188:191], v[64:67]
	s_setprio 0
	s_barrier
	ds_read_b128 v[160:163], v142 offset:16384
	ds_read_b128 v[164:167], v142 offset:17408
	ds_read_b128 v[168:171], v142 offset:18432
	ds_read_b128 v[172:175], v142 offset:19456
	ds_read_b128 v[176:179], v142 offset:20480
	ds_read_b128 v[180:183], v142 offset:21504
	ds_read_b128 v[184:187], v142 offset:22528
	ds_read_b128 v[188:191], v142 offset:23552
	s_add_i32 s71, 0, 0x14000
	s_add_i32 s9, s9, s50
	v_lshl_add_u64 v[138:139], s[4:5], 0, v[192:193]
	s_mov_b32 m0, s9
	v_lshl_add_u64 v[210:211], s[4:5], 0, v[128:129]
	global_load_lds_dwordx4 v[138:139], off
	s_add_i32 m0, s9, 0x2000
	s_nop 0
	global_load_lds_dwordx4 v[210:211], off
	s_mov_b32 m0, s39
	v_lshl_add_u64 v[212:213], s[48:49], 0, v[132:133]
	global_load_lds_dwordx4 v[212:213], off
	v_lshl_add_u64 v[214:215], s[48:49], 0, v[130:131]
	s_mov_b32 m0, s54
	s_nop 0
	global_load_lds_dwordx4 v[214:215], off
	s_add_u32 s46, s4, 0x80000
	s_addc_u32 s47, s5, 0
	s_add_i32 s9, s71, s50
	v_lshl_add_u64 v[218:219], s[46:47], 0, v[192:193]
	s_mov_b32 m0, s9
	s_nop 0
	global_load_lds_dwordx4 v[218:219], off
	v_lshl_add_u64 v[220:221], s[46:47], 0, v[128:129]
	s_add_i32 m0, s9, 0x2000
	s_nop 0
	global_load_lds_dwordx4 v[220:221], off
	s_waitcnt vmcnt(8)
	s_waitcnt lgkmcnt(0)
	s_barrier
	s_setprio 1
	v_mfma_f32_16x16x32_bf16 v[60:63], v[144:147], v[160:163], v[60:63]
	v_mfma_f32_16x16x32_bf16 v[56:59], v[152:155], v[160:163], v[56:59]
	v_mfma_f32_16x16x32_bf16 v[44:47], v[144:147], v[168:171], v[44:47]
	v_mfma_f32_16x16x32_bf16 v[40:43], v[152:155], v[168:171], v[40:43]
	v_mfma_f32_16x16x32_bf16 v[28:31], v[144:147], v[176:179], v[28:31]
	v_mfma_f32_16x16x32_bf16 v[24:27], v[152:155], v[176:179], v[24:27]
	v_mfma_f32_16x16x32_bf16 v[12:15], v[144:147], v[184:187], v[12:15]
	v_mfma_f32_16x16x32_bf16 v[8:11], v[152:155], v[184:187], v[8:11]
	v_mfma_f32_16x16x32_bf16 v[60:63], v[148:151], v[164:167], v[60:63]
	v_mfma_f32_16x16x32_bf16 v[56:59], v[156:159], v[164:167], v[56:59]
	v_mfma_f32_16x16x32_bf16 v[44:47], v[148:151], v[172:175], v[44:47]
	v_mfma_f32_16x16x32_bf16 v[40:43], v[156:159], v[172:175], v[40:43]
	v_mfma_f32_16x16x32_bf16 v[28:31], v[148:151], v[180:183], v[28:31]
	v_mfma_f32_16x16x32_bf16 v[24:27], v[156:159], v[180:183], v[24:27]
	v_mfma_f32_16x16x32_bf16 v[12:15], v[148:151], v[188:191], v[12:15]
	v_mfma_f32_16x16x32_bf16 v[8:11], v[156:159], v[188:191], v[8:11]
	v_mfma_f32_16x16x32_bf16 v[52:55], v[194:197], v[160:163], v[52:55]
	v_mfma_f32_16x16x32_bf16 v[48:51], v[202:205], v[160:163], v[48:51]
	v_mfma_f32_16x16x32_bf16 v[36:39], v[194:197], v[168:171], v[36:39]
	v_mfma_f32_16x16x32_bf16 v[32:35], v[202:205], v[168:171], v[32:35]
	v_mfma_f32_16x16x32_bf16 v[20:23], v[194:197], v[176:179], v[20:23]
	v_mfma_f32_16x16x32_bf16 v[16:19], v[202:205], v[176:179], v[16:19]
	v_mfma_f32_16x16x32_bf16 v[4:7], v[194:197], v[184:187], v[4:7]
	v_mfma_f32_16x16x32_bf16 v[0:3], v[202:205], v[184:187], v[0:3]
	v_mfma_f32_16x16x32_bf16 v[52:55], v[198:201], v[164:167], v[52:55]
	v_mfma_f32_16x16x32_bf16 v[48:51], v[206:209], v[164:167], v[48:51]
	v_mfma_f32_16x16x32_bf16 v[36:39], v[198:201], v[172:175], v[36:39]
	v_mfma_f32_16x16x32_bf16 v[32:35], v[206:209], v[172:175], v[32:35]
	v_mfma_f32_16x16x32_bf16 v[20:23], v[198:201], v[180:183], v[20:23]
	v_mfma_f32_16x16x32_bf16 v[16:19], v[206:209], v[180:183], v[16:19]
	v_mfma_f32_16x16x32_bf16 v[4:7], v[198:201], v[188:191], v[4:7]
	v_mfma_f32_16x16x32_bf16 v[0:3], v[206:209], v[188:191], v[0:3]
	s_setprio 0
	s_barrier
	v_add_u32_e32 v143, 0x18000, v141
	ds_read_b128 v[144:147], v143
	ds_read_b128 v[148:151], v143 offset:1024
	ds_read_b128 v[152:155], v143 offset:2048
	ds_read_b128 v[156:159], v143 offset:3072
	ds_read_b128 v[160:163], v142 offset:32768
	ds_read_b128 v[164:167], v142 offset:33792
	ds_read_b128 v[168:171], v142 offset:34816
	ds_read_b128 v[172:175], v142 offset:35840
	ds_read_b128 v[176:179], v142 offset:36864
	ds_read_b128 v[180:183], v142 offset:37888
	ds_read_b128 v[184:187], v142 offset:38912
	ds_read_b128 v[188:191], v142 offset:39936
	v_add_u32_e32 v143, 0x1c000, v141
	ds_read_b128 v[194:197], v143
	ds_read_b128 v[198:201], v143 offset:1024
	ds_read_b128 v[202:205], v143 offset:2048
	ds_read_b128 v[206:209], v143 offset:3072
	s_add_i32 s9, 0, 0x18000
	s_add_u32 s46, s48, 0x80000
	s_addc_u32 s47, s49, 0
	s_mov_b32 m0, s55
	v_lshl_add_u64 v[218:219], s[46:47], 0, v[132:133]
	global_load_lds_dwordx4 v[218:219], off
	v_lshl_add_u64 v[220:221], s[46:47], 0, v[130:131]
	s_mov_b32 m0, s58
	s_nop 0
	global_load_lds_dwordx4 v[220:221], off
	s_waitcnt vmcnt(8)
	s_waitcnt lgkmcnt(0)
	s_barrier
	s_setprio 1
	v_mfma_f32_16x16x32_bf16 v[124:127], v[144:147], v[160:163], v[124:127]
	v_mfma_f32_16x16x32_bf16 v[120:123], v[152:155], v[160:163], v[120:123]
	v_mfma_f32_16x16x32_bf16 v[108:111], v[144:147], v[168:171], v[108:111]
	v_mfma_f32_16x16x32_bf16 v[104:107], v[152:155], v[168:171], v[104:107]
	v_mfma_f32_16x16x32_bf16 v[92:95], v[144:147], v[176:179], v[92:95]
	v_mfma_f32_16x16x32_bf16 v[88:91], v[152:155], v[176:179], v[88:91]
	v_mfma_f32_16x16x32_bf16 v[76:79], v[144:147], v[184:187], v[76:79]
	v_mfma_f32_16x16x32_bf16 v[72:75], v[152:155], v[184:187], v[72:75]
	v_mfma_f32_16x16x32_bf16 v[124:127], v[148:151], v[164:167], v[124:127]
	v_mfma_f32_16x16x32_bf16 v[120:123], v[156:159], v[164:167], v[120:123]
	v_mfma_f32_16x16x32_bf16 v[108:111], v[148:151], v[172:175], v[108:111]
	v_mfma_f32_16x16x32_bf16 v[104:107], v[156:159], v[172:175], v[104:107]
	v_mfma_f32_16x16x32_bf16 v[92:95], v[148:151], v[180:183], v[92:95]
	v_mfma_f32_16x16x32_bf16 v[88:91], v[156:159], v[180:183], v[88:91]
	v_mfma_f32_16x16x32_bf16 v[76:79], v[148:151], v[188:191], v[76:79]
	v_mfma_f32_16x16x32_bf16 v[72:75], v[156:159], v[188:191], v[72:75]
	v_mfma_f32_16x16x32_bf16 v[116:119], v[194:197], v[160:163], v[116:119]
	v_mfma_f32_16x16x32_bf16 v[112:115], v[202:205], v[160:163], v[112:115]
	v_mfma_f32_16x16x32_bf16 v[100:103], v[194:197], v[168:171], v[100:103]
	v_mfma_f32_16x16x32_bf16 v[96:99], v[202:205], v[168:171], v[96:99]
	v_mfma_f32_16x16x32_bf16 v[84:87], v[194:197], v[176:179], v[84:87]
	v_mfma_f32_16x16x32_bf16 v[80:83], v[202:205], v[176:179], v[80:83]
	v_mfma_f32_16x16x32_bf16 v[68:71], v[194:197], v[184:187], v[68:71]
	v_mfma_f32_16x16x32_bf16 v[64:67], v[202:205], v[184:187], v[64:67]
	v_mfma_f32_16x16x32_bf16 v[116:119], v[198:201], v[164:167], v[116:119]
	v_mfma_f32_16x16x32_bf16 v[112:115], v[206:209], v[164:167], v[112:115]
	v_mfma_f32_16x16x32_bf16 v[100:103], v[198:201], v[172:175], v[100:103]
	v_mfma_f32_16x16x32_bf16 v[96:99], v[206:209], v[172:175], v[96:99]
	v_mfma_f32_16x16x32_bf16 v[84:87], v[198:201], v[180:183], v[84:87]
	v_mfma_f32_16x16x32_bf16 v[80:83], v[206:209], v[180:183], v[80:83]
	v_mfma_f32_16x16x32_bf16 v[68:71], v[198:201], v[188:191], v[68:71]
	v_mfma_f32_16x16x32_bf16 v[64:67], v[206:209], v[188:191], v[64:67]
	s_setprio 0
	s_barrier
	ds_read_b128 v[160:163], v142 offset:49152
	ds_read_b128 v[164:167], v142 offset:50176
	ds_read_b128 v[168:171], v142 offset:51200
	ds_read_b128 v[172:175], v142 offset:52224
	ds_read_b128 v[176:179], v142 offset:53248
	ds_read_b128 v[180:183], v142 offset:54272
	ds_read_b128 v[184:187], v142 offset:55296
	ds_read_b128 v[188:191], v142 offset:56320
	s_add_i32 s46, 0, 0x1c000
	s_add_i32 s9, s9, s50
	v_lshl_add_u64 v[138:139], v[138:139], 0, s[72:73]
	s_mov_b32 m0, s9
	s_nop 0
	global_load_lds_dwordx4 v[138:139], off
	v_lshl_add_u64 v[138:139], v[210:211], 0, s[72:73]
	s_add_i32 m0, s9, 0x2000
	s_nop 0
	global_load_lds_dwordx4 v[138:139], off
	s_mov_b32 m0, s59
	v_lshl_add_u64 v[138:139], v[212:213], 0, s[72:73]
	global_load_lds_dwordx4 v[138:139], off
	v_lshl_add_u64 v[138:139], v[214:215], 0, s[72:73]
	s_mov_b32 m0, s62
	s_nop 0
	global_load_lds_dwordx4 v[138:139], off
	s_add_u32 s4, s4, 0x80080
	s_addc_u32 s5, s5, 0
	s_add_i32 s9, s46, s50
	v_lshl_add_u64 v[138:139], s[4:5], 0, v[192:193]
	s_mov_b32 m0, s9
	s_nop 0
	global_load_lds_dwordx4 v[138:139], off
	v_lshl_add_u64 v[138:139], s[4:5], 0, v[128:129]
	s_add_i32 m0, s9, 0x2000
	s_nop 0
	global_load_lds_dwordx4 v[138:139], off
	s_waitcnt vmcnt(8)
	s_waitcnt lgkmcnt(0)
	s_barrier
	s_setprio 1
	v_mfma_f32_16x16x32_bf16 v[60:63], v[144:147], v[160:163], v[60:63]
	v_mfma_f32_16x16x32_bf16 v[56:59], v[152:155], v[160:163], v[56:59]
	v_mfma_f32_16x16x32_bf16 v[44:47], v[144:147], v[168:171], v[44:47]
	v_mfma_f32_16x16x32_bf16 v[40:43], v[152:155], v[168:171], v[40:43]
	v_mfma_f32_16x16x32_bf16 v[28:31], v[144:147], v[176:179], v[28:31]
	v_mfma_f32_16x16x32_bf16 v[24:27], v[152:155], v[176:179], v[24:27]
	v_mfma_f32_16x16x32_bf16 v[12:15], v[144:147], v[184:187], v[12:15]
	v_mfma_f32_16x16x32_bf16 v[8:11], v[152:155], v[184:187], v[8:11]
	v_mfma_f32_16x16x32_bf16 v[60:63], v[148:151], v[164:167], v[60:63]
	v_mfma_f32_16x16x32_bf16 v[56:59], v[156:159], v[164:167], v[56:59]
	v_mfma_f32_16x16x32_bf16 v[44:47], v[148:151], v[172:175], v[44:47]
	v_mfma_f32_16x16x32_bf16 v[40:43], v[156:159], v[172:175], v[40:43]
	v_mfma_f32_16x16x32_bf16 v[28:31], v[148:151], v[180:183], v[28:31]
	v_mfma_f32_16x16x32_bf16 v[24:27], v[156:159], v[180:183], v[24:27]
	v_mfma_f32_16x16x32_bf16 v[12:15], v[148:151], v[188:191], v[12:15]
	v_mfma_f32_16x16x32_bf16 v[8:11], v[156:159], v[188:191], v[8:11]
	v_mfma_f32_16x16x32_bf16 v[52:55], v[194:197], v[160:163], v[52:55]
	v_mfma_f32_16x16x32_bf16 v[48:51], v[202:205], v[160:163], v[48:51]
	v_mfma_f32_16x16x32_bf16 v[36:39], v[194:197], v[168:171], v[36:39]
	v_mfma_f32_16x16x32_bf16 v[32:35], v[202:205], v[168:171], v[32:35]
	v_mfma_f32_16x16x32_bf16 v[20:23], v[194:197], v[176:179], v[20:23]
	v_mfma_f32_16x16x32_bf16 v[16:19], v[202:205], v[176:179], v[16:19]
	v_mfma_f32_16x16x32_bf16 v[4:7], v[194:197], v[184:187], v[4:7]
	v_mfma_f32_16x16x32_bf16 v[0:3], v[202:205], v[184:187], v[0:3]
	v_mfma_f32_16x16x32_bf16 v[52:55], v[198:201], v[164:167], v[52:55]
	v_mfma_f32_16x16x32_bf16 v[48:51], v[206:209], v[164:167], v[48:51]
	v_mfma_f32_16x16x32_bf16 v[36:39], v[198:201], v[172:175], v[36:39]
	v_mfma_f32_16x16x32_bf16 v[32:35], v[206:209], v[172:175], v[32:35]
	v_mfma_f32_16x16x32_bf16 v[20:23], v[198:201], v[180:183], v[20:23]
	v_mfma_f32_16x16x32_bf16 v[16:19], v[206:209], v[180:183], v[16:19]
	v_mfma_f32_16x16x32_bf16 v[4:7], v[198:201], v[188:191], v[4:7]
	v_mfma_f32_16x16x32_bf16 v[0:3], v[206:209], v[188:191], v[0:3]
	s_setprio 0
	s_add_i32 s69, s69, 2
	s_add_u32 s2, s2, 0x100
	s_addc_u32 s3, s3, 0
	s_add_u32 s15, s15, 0x100
	s_addc_u32 s29, s29, 0
	s_cmp_gt_u32 s69, 29
	s_barrier
	s_cbranch_scc0 .LBB0_256
	s_lshl_b32 s2, s38, 8
	v_mov_b32 v138, v140
	s_add_i32 s2, s2, s63
	v_and_or_b32 v144, v138, 15, s2
	s_lshl_b32 s2, s67, 8
	v_ashrrev_i32_e32 v138, 1, v138
	v_max_f32_e32 v120, v120, v120
	s_or_b32 s2, s2, s64
	v_and_b32_e32 v138, -8, v138
	v_max_f32_e32 v120, 0, v120
	v_max_f32_e32 v121, v121, v121
	v_max_f32_e32 v122, v122, v122
	v_add_u32_e32 v138, s2, v138
	v_ashrrev_i32_e32 v145, 31, v144
	v_readlane_b32 s2, v252, 63
	v_mul_f32_e32 v143, v120, v120
	v_max_f32_e32 v120, v125, v125
	v_max_f32_e32 v121, 0, v121
	v_max_f32_e32 v122, 0, v122
	v_ashrrev_i32_e32 v139, 31, v138
	v_lshlrev_b64 v[146:147], 14, v[144:145]
	v_readlane_b32 s3, v253, 0
	v_max_f32_e32 v124, v124, v124
	v_max_f32_e32 v120, 0, v120
	v_mul_f32_e32 v125, v121, v121
	v_max_f32_e32 v121, v126, v126
	v_mul_f32_e32 v126, v122, v122
	v_max_f32_e32 v122, v127, v127
	v_max_f32_e32 v123, v123, v123
	v_lshl_add_u64 v[146:147], s[2:3], 0, v[146:147]
	v_lshlrev_b64 v[148:149], 1, v[138:139]
	v_max_f32_e32 v124, 0, v124
	v_mul_f32_e32 v120, v120, v120
	v_max_f32_e32 v121, 0, v121
	v_max_f32_e32 v122, 0, v122
	v_max_f32_e32 v123, 0, v123
	v_max_f32_e32 v112, v112, v112
	v_lshl_add_u64 v[138:139], v[146:147], 0, v[148:149]
	v_mul_f32_e32 v124, v124, v124
	v_mul_f32_e32 v121, v121, v121
	v_mul_f32_e32 v122, v122, v122
	v_mul_f32_e32 v123, v123, v123
	v_cvt_pk_bf16_f32 v120, v124, v120
	v_max_f32_e32 v112, 0, v112
	v_max_f32_e32 v113, v113, v113
	v_max_f32_e32 v114, v114, v114
	v_cvt_pk_bf16_f32 v121, v121, v122
	v_cvt_pk_bf16_f32 v122, v143, v125
	v_cvt_pk_bf16_f32 v123, v126, v123
	global_store_dwordx4 v[138:139], v[120:123], off
	v_max_f32_e32 v113, 0, v113
	v_max_f32_e32 v114, 0, v114
	v_mul_f32_e32 v120, v112, v112
	v_max_f32_e32 v112, v117, v117
	v_max_f32_e32 v116, v116, v116
	v_max_f32_e32 v112, 0, v112
	v_mul_f32_e32 v117, v113, v113
	v_max_f32_e32 v113, v118, v118
	v_mul_f32_e32 v118, v114, v114
	v_max_f32_e32 v114, v119, v119
	v_max_f32_e32 v115, v115, v115
	v_max_f32_e32 v116, 0, v116
	v_mul_f32_e32 v112, v112, v112
	v_max_f32_e32 v113, 0, v113
	v_max_f32_e32 v114, 0, v114
	v_max_f32_e32 v115, 0, v115
	v_mul_f32_e32 v116, v116, v116
	v_mul_f32_e32 v113, v113, v113
	v_mul_f32_e32 v114, v114, v114
	v_mul_f32_e32 v115, v115, v115
	v_cvt_pk_bf16_f32 v112, v116, v112
	v_max_f32_e32 v104, v104, v104
	v_cvt_pk_bf16_f32 v113, v113, v114
	v_cvt_pk_bf16_f32 v114, v120, v117
	v_cvt_pk_bf16_f32 v115, v118, v115
	global_store_dwordx4 v[138:139], v[112:115], off offset:256
	v_max_f32_e32 v104, 0, v104
	v_max_f32_e32 v105, v105, v105
	v_or_b32_e32 v112, 16, v144
	v_max_f32_e32 v106, v106, v106
	v_ashrrev_i32_e32 v113, 31, v112
	v_mul_f32_e32 v114, v104, v104
	v_max_f32_e32 v104, v109, v109
	v_max_f32_e32 v105, 0, v105
	v_max_f32_e32 v106, 0, v106
	v_lshlrev_b64 v[112:113], 14, v[112:113]
	v_max_f32_e32 v108, v108, v108
	v_max_f32_e32 v104, 0, v104
	v_mul_f32_e32 v109, v105, v105
	v_max_f32_e32 v105, v110, v110
	v_mul_f32_e32 v110, v106, v106
	v_max_f32_e32 v106, v111, v111
	v_max_f32_e32 v107, v107, v107
	v_lshl_add_u64 v[112:113], s[2:3], 0, v[112:113]
	v_max_f32_e32 v108, 0, v108
	v_mul_f32_e32 v104, v104, v104
	v_max_f32_e32 v105, 0, v105
	v_max_f32_e32 v106, 0, v106
	v_max_f32_e32 v107, 0, v107
	v_max_f32_e32 v96, v96, v96
	v_lshl_add_u64 v[112:113], v[112:113], 0, v[148:149]
	v_mul_f32_e32 v108, v108, v108
	v_mul_f32_e32 v105, v105, v105
	v_mul_f32_e32 v106, v106, v106
	v_mul_f32_e32 v107, v107, v107
	v_cvt_pk_bf16_f32 v104, v108, v104
	v_max_f32_e32 v96, 0, v96
	v_max_f32_e32 v97, v97, v97
	v_max_f32_e32 v98, v98, v98
	v_cvt_pk_bf16_f32 v105, v105, v106
	v_cvt_pk_bf16_f32 v106, v114, v109
	v_cvt_pk_bf16_f32 v107, v110, v107
	global_store_dwordx4 v[112:113], v[104:107], off
	v_max_f32_e32 v97, 0, v97
	v_max_f32_e32 v98, 0, v98
	v_mul_f32_e32 v104, v96, v96
	v_max_f32_e32 v96, v101, v101
	v_max_f32_e32 v100, v100, v100
	v_max_f32_e32 v96, 0, v96
	v_mul_f32_e32 v101, v97, v97
	v_max_f32_e32 v97, v102, v102
	v_mul_f32_e32 v102, v98, v98
	v_max_f32_e32 v98, v103, v103
	v_max_f32_e32 v99, v99, v99
	v_max_f32_e32 v100, 0, v100
	v_mul_f32_e32 v96, v96, v96
	v_max_f32_e32 v97, 0, v97
	v_max_f32_e32 v98, 0, v98
	v_max_f32_e32 v99, 0, v99
	v_mul_f32_e32 v100, v100, v100
	v_mul_f32_e32 v97, v97, v97
	v_mul_f32_e32 v98, v98, v98
	v_mul_f32_e32 v99, v99, v99
	v_cvt_pk_bf16_f32 v96, v100, v96
	v_max_f32_e32 v88, v88, v88
	v_cvt_pk_bf16_f32 v97, v97, v98
	v_cvt_pk_bf16_f32 v98, v104, v101
	v_cvt_pk_bf16_f32 v99, v102, v99
	global_store_dwordx4 v[112:113], v[96:99], off offset:256
	v_max_f32_e32 v88, 0, v88
	v_max_f32_e32 v89, v89, v89
	v_or_b32_e32 v96, 32, v144
	v_max_f32_e32 v90, v90, v90
	v_ashrrev_i32_e32 v97, 31, v96
	v_mul_f32_e32 v98, v88, v88
	v_max_f32_e32 v88, v93, v93
	v_max_f32_e32 v89, 0, v89
	v_max_f32_e32 v90, 0, v90
	v_lshlrev_b64 v[96:97], 14, v[96:97]
	v_max_f32_e32 v92, v92, v92
	v_max_f32_e32 v88, 0, v88
	v_mul_f32_e32 v93, v89, v89
	v_max_f32_e32 v89, v94, v94
	v_mul_f32_e32 v94, v90, v90
	v_max_f32_e32 v90, v95, v95
	v_max_f32_e32 v91, v91, v91
	v_lshl_add_u64 v[96:97], s[2:3], 0, v[96:97]
	v_max_f32_e32 v92, 0, v92
	v_mul_f32_e32 v88, v88, v88
	v_max_f32_e32 v89, 0, v89
	v_max_f32_e32 v90, 0, v90
	v_max_f32_e32 v91, 0, v91
	v_max_f32_e32 v80, v80, v80
	v_lshl_add_u64 v[96:97], v[96:97], 0, v[148:149]
	v_mul_f32_e32 v92, v92, v92
	v_mul_f32_e32 v89, v89, v89
	v_mul_f32_e32 v90, v90, v90
	v_mul_f32_e32 v91, v91, v91
	v_cvt_pk_bf16_f32 v88, v92, v88
	v_max_f32_e32 v80, 0, v80
	v_max_f32_e32 v81, v81, v81
	v_max_f32_e32 v82, v82, v82
	v_cvt_pk_bf16_f32 v89, v89, v90
	v_cvt_pk_bf16_f32 v90, v98, v93
	v_cvt_pk_bf16_f32 v91, v94, v91
	global_store_dwordx4 v[96:97], v[88:91], off
	v_max_f32_e32 v81, 0, v81
	v_max_f32_e32 v82, 0, v82
	v_mul_f32_e32 v88, v80, v80
	v_max_f32_e32 v80, v85, v85
	v_max_f32_e32 v84, v84, v84
	v_max_f32_e32 v80, 0, v80
	v_mul_f32_e32 v85, v81, v81
	v_max_f32_e32 v81, v86, v86
	v_mul_f32_e32 v86, v82, v82
	v_max_f32_e32 v82, v87, v87
	v_max_f32_e32 v83, v83, v83
	v_max_f32_e32 v84, 0, v84
	v_mul_f32_e32 v80, v80, v80
	v_max_f32_e32 v81, 0, v81
	v_max_f32_e32 v82, 0, v82
	v_max_f32_e32 v83, 0, v83
	v_mul_f32_e32 v84, v84, v84
	v_mul_f32_e32 v81, v81, v81
	v_mul_f32_e32 v82, v82, v82
	v_mul_f32_e32 v83, v83, v83
	v_cvt_pk_bf16_f32 v80, v84, v80
	v_max_f32_e32 v72, v72, v72
	v_cvt_pk_bf16_f32 v81, v81, v82
	v_cvt_pk_bf16_f32 v82, v88, v85
	v_cvt_pk_bf16_f32 v83, v86, v83
	global_store_dwordx4 v[96:97], v[80:83], off offset:256
	v_max_f32_e32 v72, 0, v72
	v_max_f32_e32 v73, v73, v73
	v_or_b32_e32 v80, 48, v144
	v_max_f32_e32 v74, v74, v74
	v_ashrrev_i32_e32 v81, 31, v80
	v_mul_f32_e32 v82, v72, v72
	v_max_f32_e32 v72, v77, v77
	v_max_f32_e32 v73, 0, v73
	v_max_f32_e32 v74, 0, v74
	v_lshlrev_b64 v[80:81], 14, v[80:81]
	v_max_f32_e32 v76, v76, v76
	v_max_f32_e32 v72, 0, v72
	v_mul_f32_e32 v77, v73, v73
	v_max_f32_e32 v73, v78, v78
	v_mul_f32_e32 v78, v74, v74
	v_max_f32_e32 v74, v79, v79
	v_max_f32_e32 v75, v75, v75
	v_lshl_add_u64 v[80:81], s[2:3], 0, v[80:81]
	v_max_f32_e32 v76, 0, v76
	v_mul_f32_e32 v72, v72, v72
	v_max_f32_e32 v73, 0, v73
	v_max_f32_e32 v74, 0, v74
	v_max_f32_e32 v75, 0, v75
	v_max_f32_e32 v64, v64, v64
	v_max_f32_e32 v65, v65, v65
	v_max_f32_e32 v66, v66, v66
	v_lshl_add_u64 v[80:81], v[80:81], 0, v[148:149]
	v_mul_f32_e32 v76, v76, v76
	v_mul_f32_e32 v73, v73, v73
	v_mul_f32_e32 v74, v74, v74
	v_mul_f32_e32 v75, v75, v75
	v_cvt_pk_bf16_f32 v72, v76, v72
	v_max_f32_e32 v64, 0, v64
	v_max_f32_e32 v65, 0, v65
	v_max_f32_e32 v66, 0, v66
	v_cvt_pk_bf16_f32 v73, v73, v74
	v_cvt_pk_bf16_f32 v74, v82, v77
	v_cvt_pk_bf16_f32 v75, v78, v75
	global_store_dwordx4 v[80:81], v[72:75], off
	v_max_f32_e32 v68, v68, v68
	v_max_f32_e32 v67, v67, v67
	v_mul_f32_e32 v72, v64, v64
	v_max_f32_e32 v64, v69, v69
	v_mul_f32_e32 v69, v65, v65
	v_max_f32_e32 v65, v70, v70
	v_mul_f32_e32 v70, v66, v66
	v_max_f32_e32 v66, v71, v71
	v_max_f32_e32 v64, 0, v64
	v_max_f32_e32 v65, 0, v65
	v_max_f32_e32 v66, 0, v66
	v_max_f32_e32 v68, 0, v68
	v_mul_f32_e32 v64, v64, v64
	v_mul_f32_e32 v65, v65, v65
	v_max_f32_e32 v67, 0, v67
	v_mul_f32_e32 v66, v66, v66
	v_max_f32_e32 v56, v56, v56
	v_mul_f32_e32 v68, v68, v68
	v_mul_f32_e32 v67, v67, v67
	v_cvt_pk_bf16_f32 v64, v68, v64
	v_cvt_pk_bf16_f32 v65, v65, v66
	v_cvt_pk_bf16_f32 v66, v72, v69
	v_max_f32_e32 v56, 0, v56
	v_max_f32_e32 v57, v57, v57
	v_max_f32_e32 v58, v58, v58
	v_cvt_pk_bf16_f32 v67, v70, v67
	global_store_dwordx4 v[80:81], v[64:67], off offset:256
	v_max_f32_e32 v60, v60, v60
	v_max_f32_e32 v57, 0, v57
	v_mul_f32_e32 v66, v56, v56
	v_max_f32_e32 v56, v61, v61
	v_max_f32_e32 v58, 0, v58
	s_mov_b64 s[2:3], 0x200000
	v_max_f32_e32 v60, 0, v60
	v_max_f32_e32 v56, 0, v56
	v_mul_f32_e32 v61, v57, v57
	v_max_f32_e32 v57, v62, v62
	v_mul_f32_e32 v62, v58, v58
	v_max_f32_e32 v58, v63, v63
	v_lshl_add_u64 v[64:65], v[138:139], 0, s[2:3]
	v_mul_f32_e32 v60, v60, v60
	v_mul_f32_e32 v56, v56, v56
	v_max_f32_e32 v57, 0, v57
	v_max_f32_e32 v58, 0, v58
	v_max_f32_e32 v59, v59, v59
	s_mov_b32 s2, 0x200000
	v_mul_f32_e32 v57, v57, v57
	v_max_f32_e32 v59, 0, v59
	v_mul_f32_e32 v58, v58, v58
	v_cvt_pk_bf16_f32 v56, v60, v56
	v_add_co_u32_e32 v60, vcc, s2, v138
	v_max_f32_e32 v48, v48, v48
	v_max_f32_e32 v49, v49, v49
	v_max_f32_e32 v50, v50, v50
	v_mul_f32_e32 v59, v59, v59
	v_cvt_pk_bf16_f32 v57, v57, v58
	v_cvt_pk_bf16_f32 v58, v66, v61
	v_addc_co_u32_e32 v61, vcc, 0, v139, vcc
	v_max_f32_e32 v48, 0, v48
	v_max_f32_e32 v49, 0, v49
	v_max_f32_e32 v50, 0, v50
	v_cvt_pk_bf16_f32 v59, v62, v59
	global_store_dwordx4 v[60:61], v[56:59], off
	v_max_f32_e32 v52, v52, v52
	v_max_f32_e32 v51, v51, v51
	v_mul_f32_e32 v56, v48, v48
	v_max_f32_e32 v48, v53, v53
	v_mul_f32_e32 v53, v49, v49
	v_max_f32_e32 v49, v54, v54
	v_mul_f32_e32 v54, v50, v50
	v_max_f32_e32 v50, v55, v55
	v_max_f32_e32 v48, 0, v48
	v_max_f32_e32 v49, 0, v49
	v_max_f32_e32 v50, 0, v50
	v_max_f32_e32 v52, 0, v52
	v_mul_f32_e32 v48, v48, v48
	v_mul_f32_e32 v49, v49, v49
	v_max_f32_e32 v51, 0, v51
	v_mul_f32_e32 v50, v50, v50
	v_max_f32_e32 v40, v40, v40
	v_mul_f32_e32 v52, v52, v52
	v_mul_f32_e32 v51, v51, v51
	v_cvt_pk_bf16_f32 v48, v52, v48
	v_cvt_pk_bf16_f32 v49, v49, v50
	v_cvt_pk_bf16_f32 v50, v56, v53
	v_max_f32_e32 v40, 0, v40
	v_max_f32_e32 v41, v41, v41
	v_max_f32_e32 v42, v42, v42
	v_cvt_pk_bf16_f32 v51, v54, v51
	global_store_dwordx4 v[64:65], v[48:51], off offset:256
	v_max_f32_e32 v44, v44, v44
	v_max_f32_e32 v41, 0, v41
	v_mul_f32_e32 v50, v40, v40
	v_max_f32_e32 v40, v45, v45
	v_max_f32_e32 v42, 0, v42
	s_mov_b64 s[2:3], 0x240000
	v_max_f32_e32 v44, 0, v44
	v_max_f32_e32 v40, 0, v40
	v_mul_f32_e32 v45, v41, v41
	v_max_f32_e32 v41, v46, v46
	v_mul_f32_e32 v46, v42, v42
	v_max_f32_e32 v42, v47, v47
	v_lshl_add_u64 v[48:49], v[138:139], 0, s[2:3]
	v_mul_f32_e32 v44, v44, v44
	v_mul_f32_e32 v40, v40, v40
	v_max_f32_e32 v41, 0, v41
	v_max_f32_e32 v42, 0, v42
	v_max_f32_e32 v43, v43, v43
	s_mov_b32 s2, 0x240000
	v_mul_f32_e32 v41, v41, v41
	v_max_f32_e32 v43, 0, v43
	v_mul_f32_e32 v42, v42, v42
	v_cvt_pk_bf16_f32 v40, v44, v40
	v_add_co_u32_e32 v44, vcc, s2, v138
	v_max_f32_e32 v32, v32, v32
	v_max_f32_e32 v33, v33, v33
	v_max_f32_e32 v34, v34, v34
	v_mul_f32_e32 v43, v43, v43
	v_cvt_pk_bf16_f32 v41, v41, v42
	v_cvt_pk_bf16_f32 v42, v50, v45
	v_addc_co_u32_e32 v45, vcc, 0, v139, vcc
	v_max_f32_e32 v32, 0, v32
	v_max_f32_e32 v33, 0, v33
	v_max_f32_e32 v34, 0, v34
	v_cvt_pk_bf16_f32 v43, v46, v43
	global_store_dwordx4 v[44:45], v[40:43], off
	v_max_f32_e32 v36, v36, v36
	v_max_f32_e32 v35, v35, v35
	v_mul_f32_e32 v40, v32, v32
	v_max_f32_e32 v32, v37, v37
	v_mul_f32_e32 v37, v33, v33
	v_max_f32_e32 v33, v38, v38
	v_mul_f32_e32 v38, v34, v34
	v_max_f32_e32 v34, v39, v39
	v_max_f32_e32 v32, 0, v32
	v_max_f32_e32 v33, 0, v33
	v_max_f32_e32 v34, 0, v34
	v_max_f32_e32 v36, 0, v36
	v_mul_f32_e32 v32, v32, v32
	v_mul_f32_e32 v33, v33, v33
	v_max_f32_e32 v35, 0, v35
	v_mul_f32_e32 v34, v34, v34
	v_max_f32_e32 v24, v24, v24
	v_mul_f32_e32 v36, v36, v36
	v_mul_f32_e32 v35, v35, v35
	v_cvt_pk_bf16_f32 v32, v36, v32
	v_cvt_pk_bf16_f32 v33, v33, v34
	v_cvt_pk_bf16_f32 v34, v40, v37
	v_max_f32_e32 v24, 0, v24
	v_max_f32_e32 v25, v25, v25
	v_max_f32_e32 v26, v26, v26
	v_cvt_pk_bf16_f32 v35, v38, v35
	global_store_dwordx4 v[48:49], v[32:35], off offset:256
	v_max_f32_e32 v28, v28, v28
	v_max_f32_e32 v25, 0, v25
	v_mul_f32_e32 v34, v24, v24
	v_max_f32_e32 v24, v29, v29
	v_max_f32_e32 v26, 0, v26
	s_mov_b64 s[2:3], 0x280000
	v_max_f32_e32 v28, 0, v28
	v_max_f32_e32 v24, 0, v24
	v_mul_f32_e32 v29, v25, v25
	v_max_f32_e32 v25, v30, v30
	v_mul_f32_e32 v30, v26, v26
	v_max_f32_e32 v26, v31, v31
	v_lshl_add_u64 v[32:33], v[138:139], 0, s[2:3]
	v_mul_f32_e32 v28, v28, v28
	v_mul_f32_e32 v24, v24, v24
	v_max_f32_e32 v25, 0, v25
	v_max_f32_e32 v26, 0, v26
	v_max_f32_e32 v27, v27, v27
	s_mov_b32 s2, 0x280000
	v_mul_f32_e32 v25, v25, v25
	v_max_f32_e32 v27, 0, v27
	v_mul_f32_e32 v26, v26, v26
	v_cvt_pk_bf16_f32 v24, v28, v24
	v_add_co_u32_e32 v28, vcc, s2, v138
	v_max_f32_e32 v16, v16, v16
	v_max_f32_e32 v17, v17, v17
	v_max_f32_e32 v18, v18, v18
	v_mul_f32_e32 v27, v27, v27
	v_cvt_pk_bf16_f32 v25, v25, v26
	v_cvt_pk_bf16_f32 v26, v34, v29
	v_addc_co_u32_e32 v29, vcc, 0, v139, vcc
	v_max_f32_e32 v16, 0, v16
	v_max_f32_e32 v17, 0, v17
	v_max_f32_e32 v18, 0, v18
	v_cvt_pk_bf16_f32 v27, v30, v27
	global_store_dwordx4 v[28:29], v[24:27], off
	v_max_f32_e32 v20, v20, v20
	v_max_f32_e32 v19, v19, v19
	v_mul_f32_e32 v24, v16, v16
	v_max_f32_e32 v16, v21, v21
	v_mul_f32_e32 v21, v17, v17
	v_max_f32_e32 v17, v22, v22
	v_mul_f32_e32 v22, v18, v18
	v_max_f32_e32 v18, v23, v23
	v_max_f32_e32 v16, 0, v16
	v_max_f32_e32 v17, 0, v17
	v_max_f32_e32 v18, 0, v18
	v_max_f32_e32 v20, 0, v20
	v_mul_f32_e32 v16, v16, v16
	v_mul_f32_e32 v17, v17, v17
	v_max_f32_e32 v19, 0, v19
	v_mul_f32_e32 v18, v18, v18
	v_max_f32_e32 v8, v8, v8
	v_mul_f32_e32 v20, v20, v20
	v_mul_f32_e32 v19, v19, v19
	v_cvt_pk_bf16_f32 v16, v20, v16
	v_cvt_pk_bf16_f32 v17, v17, v18
	v_cvt_pk_bf16_f32 v18, v24, v21
	v_max_f32_e32 v8, 0, v8
	v_max_f32_e32 v9, v9, v9
	v_max_f32_e32 v10, v10, v10
	v_cvt_pk_bf16_f32 v19, v22, v19
	global_store_dwordx4 v[32:33], v[16:19], off offset:256
	v_max_f32_e32 v12, v12, v12
	v_max_f32_e32 v9, 0, v9
	v_mul_f32_e32 v18, v8, v8
	v_max_f32_e32 v8, v13, v13
	v_max_f32_e32 v10, 0, v10
	s_mov_b64 s[2:3], 0x2c0000
	v_max_f32_e32 v12, 0, v12
	v_max_f32_e32 v8, 0, v8
	v_mul_f32_e32 v13, v9, v9
	v_max_f32_e32 v9, v14, v14
	v_mul_f32_e32 v14, v10, v10
	v_max_f32_e32 v10, v15, v15
	v_lshl_add_u64 v[16:17], v[138:139], 0, s[2:3]
	v_mul_f32_e32 v12, v12, v12
	v_mul_f32_e32 v8, v8, v8
	v_max_f32_e32 v9, 0, v9
	v_max_f32_e32 v10, 0, v10
	v_max_f32_e32 v11, v11, v11
	s_mov_b32 s2, 0x2c0000
	v_mul_f32_e32 v9, v9, v9
	v_max_f32_e32 v11, 0, v11
	v_mul_f32_e32 v10, v10, v10
	v_cvt_pk_bf16_f32 v8, v12, v8
	v_add_co_u32_e32 v12, vcc, s2, v138
	v_max_f32_e32 v0, v0, v0
	v_max_f32_e32 v1, v1, v1
	v_max_f32_e32 v2, v2, v2
	v_mul_f32_e32 v11, v11, v11
	v_cvt_pk_bf16_f32 v9, v9, v10
	v_cvt_pk_bf16_f32 v10, v18, v13
	v_addc_co_u32_e32 v13, vcc, 0, v139, vcc
	v_max_f32_e32 v0, 0, v0
	v_max_f32_e32 v1, 0, v1
	v_max_f32_e32 v2, 0, v2
	v_cvt_pk_bf16_f32 v11, v14, v11
	global_store_dwordx4 v[12:13], v[8:11], off
	v_max_f32_e32 v3, v3, v3
	v_max_f32_e32 v4, v4, v4
	v_mul_f32_e32 v8, v0, v0
	v_max_f32_e32 v0, v5, v5
	v_mul_f32_e32 v5, v1, v1
	v_max_f32_e32 v1, v6, v6
	v_mul_f32_e32 v6, v2, v2
	v_max_f32_e32 v2, v7, v7
	v_max_f32_e32 v0, 0, v0
	v_max_f32_e32 v1, 0, v1
	v_max_f32_e32 v2, 0, v2
	v_max_f32_e32 v3, 0, v3
	v_max_f32_e32 v4, 0, v4
	v_mul_f32_e32 v0, v0, v0
	v_mul_f32_e32 v1, v1, v1
	v_mul_f32_e32 v2, v2, v2
	v_mul_f32_e32 v3, v3, v3
	s_and_b64 vcc, exec, s[0:1]
	s_mov_b32 s67, s14
	s_mov_b32 s38, s28
	s_mov_b64 s[4:5], s[36:37]
	s_mov_b64 s[2:3], s[34:35]
	v_mul_f32_e32 v4, v4, v4
	v_cvt_pk_bf16_f32 v0, v4, v0
	v_cvt_pk_bf16_f32 v1, v1, v2
	v_cvt_pk_bf16_f32 v2, v8, v5
	v_cvt_pk_bf16_f32 v3, v6, v3
	global_store_dwordx4 v[16:17], v[0:3], off offset:256
	s_cbranch_vccz .LBB0_253
	s_waitcnt vmcnt(0)
	v_readlane_b32 s62, v254, 59
	s_cmpk_gt_u32 s41, 0xff
	v_readlane_b32 s55, v254, 57
	v_readlane_b32 s58, v254, 58
	v_readlane_b32 s63, v254, 60
	v_readlane_b32 s59, v255, 1
	s_movk_i32 s66, 0x3000
	v_readlane_b32 s49, v255, 18
	s_cbranch_scc1 .LBB0_260
	s_barrier

.LBB0_329:
	v_add_u32_e32 v140, 0x10000, v249
	ds_read_b128 v[128:131], v140
	ds_read_b128 v[132:135], v140 offset:1024
	ds_read_b128 v[136:139], v140 offset:2048
	ds_read_b128 v[140:143], v140 offset:3072
	ds_read_b128 v[144:147], v250
	ds_read_b128 v[148:151], v250 offset:1024
	ds_read_b128 v[152:155], v250 offset:2048
	ds_read_b128 v[156:159], v250 offset:3072
	ds_read_b128 v[160:163], v250 offset:4096
	ds_read_b128 v[164:167], v250 offset:5120
	ds_read_b128 v[168:171], v250 offset:6144
	ds_read_b128 v[172:175], v250 offset:7168
	v_add_u32_e32 v188, 0x14000, v249
	ds_read_b128 v[176:179], v188
	ds_read_b128 v[180:183], v188 offset:1024
	ds_read_b128 v[184:187], v188 offset:2048
	ds_read_b128 v[188:191], v188 offset:3072
	s_add_u32 s2, s0, 0xfff80080
	s_addc_u32 s3, s1, -1
	s_add_i32 s9, 0, 0x10000
	s_cmp_eq_u32 s40, 28
	s_cselect_b32 s5, s53, s3
	s_cselect_b32 s4, s52, s2
	s_cselect_b32 s3, s67, s37
	s_cselect_b32 s2, s66, s36
	v_lshl_add_u64 v[218:219], s[0:1], 0, v[202:203]
	s_add_i32 m0, s51, 0xc000
	s_nop 0
	global_load_lds_dwordx4 v[218:219], off
	v_lshl_add_u64 v[220:221], s[0:1], 0, v[204:205]
	s_add_i32 m0, s51, 0xe000
	s_nop 0
	global_load_lds_dwordx4 v[220:221], off
	s_waitcnt vmcnt(8)
	s_waitcnt lgkmcnt(0)
	s_barrier
	s_setprio 1
	v_mfma_f32_16x16x32_bf16 v[124:127], v[128:131], v[144:147], v[124:127]
	v_mfma_f32_16x16x32_bf16 v[120:123], v[136:139], v[144:147], v[120:123]
	v_mfma_f32_16x16x32_bf16 v[108:111], v[128:131], v[152:155], v[108:111]
	v_mfma_f32_16x16x32_bf16 v[104:107], v[136:139], v[152:155], v[104:107]
	v_mfma_f32_16x16x32_bf16 v[92:95], v[128:131], v[160:163], v[92:95]
	v_mfma_f32_16x16x32_bf16 v[88:91], v[136:139], v[160:163], v[88:91]
	v_mfma_f32_16x16x32_bf16 v[76:79], v[128:131], v[168:171], v[76:79]
	v_mfma_f32_16x16x32_bf16 v[72:75], v[136:139], v[168:171], v[72:75]
	v_mfma_f32_16x16x32_bf16 v[124:127], v[132:135], v[148:151], v[124:127]
	v_mfma_f32_16x16x32_bf16 v[120:123], v[140:143], v[148:151], v[120:123]
	v_mfma_f32_16x16x32_bf16 v[108:111], v[132:135], v[156:159], v[108:111]
	v_mfma_f32_16x16x32_bf16 v[104:107], v[140:143], v[156:159], v[104:107]
	v_mfma_f32_16x16x32_bf16 v[92:95], v[132:135], v[164:167], v[92:95]
	v_mfma_f32_16x16x32_bf16 v[88:91], v[140:143], v[164:167], v[88:91]
	v_mfma_f32_16x16x32_bf16 v[76:79], v[132:135], v[172:175], v[76:79]
	v_mfma_f32_16x16x32_bf16 v[72:75], v[140:143], v[172:175], v[72:75]
	v_mfma_f32_16x16x32_bf16 v[116:119], v[176:179], v[144:147], v[116:119]
	v_mfma_f32_16x16x32_bf16 v[112:115], v[184:187], v[144:147], v[112:115]
	v_mfma_f32_16x16x32_bf16 v[100:103], v[176:179], v[152:155], v[100:103]
	v_mfma_f32_16x16x32_bf16 v[96:99], v[184:187], v[152:155], v[96:99]
	v_mfma_f32_16x16x32_bf16 v[84:87], v[176:179], v[160:163], v[84:87]
	v_mfma_f32_16x16x32_bf16 v[80:83], v[184:187], v[160:163], v[80:83]
	v_mfma_f32_16x16x32_bf16 v[68:71], v[176:179], v[168:171], v[68:71]
	v_mfma_f32_16x16x32_bf16 v[64:67], v[184:187], v[168:171], v[64:67]
	v_mfma_f32_16x16x32_bf16 v[116:119], v[180:183], v[148:151], v[116:119]
	v_mfma_f32_16x16x32_bf16 v[112:115], v[188:191], v[148:151], v[112:115]
	v_mfma_f32_16x16x32_bf16 v[100:103], v[180:183], v[156:159], v[100:103]
	v_mfma_f32_16x16x32_bf16 v[96:99], v[188:191], v[156:159], v[96:99]
	v_mfma_f32_16x16x32_bf16 v[84:87], v[180:183], v[164:167], v[84:87]
	v_mfma_f32_16x16x32_bf16 v[80:83], v[188:191], v[164:167], v[80:83]
	v_mfma_f32_16x16x32_bf16 v[68:71], v[180:183], v[172:175], v[68:71]
	v_mfma_f32_16x16x32_bf16 v[64:67], v[188:191], v[172:175], v[64:67]
	s_setprio 0
	s_barrier
	ds_read_b128 v[144:147], v250 offset:16384
	ds_read_b128 v[148:151], v250 offset:17408
	ds_read_b128 v[152:155], v250 offset:18432
	ds_read_b128 v[156:159], v250 offset:19456
	ds_read_b128 v[160:163], v250 offset:20480
	ds_read_b128 v[164:167], v250 offset:21504
	ds_read_b128 v[168:171], v250 offset:22528
	ds_read_b128 v[172:175], v250 offset:23552
	s_add_i32 s41, 0, 0x14000
	s_add_i32 s9, s9, s50
	v_lshl_add_u64 v[206:207], s[2:3], 0, v[196:197]
	s_mov_b32 m0, s9
	s_nop 0
	global_load_lds_dwordx4 v[206:207], off
	v_lshl_add_u64 v[208:209], s[2:3], 0, v[200:201]
	s_add_i32 m0, s9, 0x2000
	s_nop 0
	global_load_lds_dwordx4 v[208:209], off
	s_mov_b32 m0, s51
	v_lshl_add_u64 v[210:211], s[4:5], 0, v[194:195]
	global_load_lds_dwordx4 v[210:211], off
	v_lshl_add_u64 v[212:213], s[4:5], 0, v[198:199]
	s_mov_b32 m0, s62
	s_nop 0
	global_load_lds_dwordx4 v[212:213], off
	s_add_u32 s46, s2, 0x80000
	s_addc_u32 s47, s3, 0
	s_add_i32 s9, s41, s50
	v_lshl_add_u64 v[218:219], s[46:47], 0, v[196:197]
	s_mov_b32 m0, s9
	s_nop 0
	global_load_lds_dwordx4 v[218:219], off
	v_lshl_add_u64 v[220:221], s[46:47], 0, v[200:201]
	s_add_i32 m0, s9, 0x2000
	s_nop 0
	global_load_lds_dwordx4 v[220:221], off
	s_waitcnt vmcnt(8)
	s_waitcnt lgkmcnt(0)
	s_barrier
	s_setprio 1
	v_mfma_f32_16x16x32_bf16 v[60:63], v[128:131], v[144:147], v[60:63]
	v_mfma_f32_16x16x32_bf16 v[56:59], v[136:139], v[144:147], v[56:59]
	v_mfma_f32_16x16x32_bf16 v[44:47], v[128:131], v[152:155], v[44:47]
	v_mfma_f32_16x16x32_bf16 v[40:43], v[136:139], v[152:155], v[40:43]
	v_mfma_f32_16x16x32_bf16 v[28:31], v[128:131], v[160:163], v[28:31]
	v_mfma_f32_16x16x32_bf16 v[24:27], v[136:139], v[160:163], v[24:27]
	v_mfma_f32_16x16x32_bf16 v[12:15], v[128:131], v[168:171], v[12:15]
	v_mfma_f32_16x16x32_bf16 v[8:11], v[136:139], v[168:171], v[8:11]
	v_mfma_f32_16x16x32_bf16 v[60:63], v[132:135], v[148:151], v[60:63]
	v_mfma_f32_16x16x32_bf16 v[56:59], v[140:143], v[148:151], v[56:59]
	v_mfma_f32_16x16x32_bf16 v[44:47], v[132:135], v[156:159], v[44:47]
	v_mfma_f32_16x16x32_bf16 v[40:43], v[140:143], v[156:159], v[40:43]
	v_mfma_f32_16x16x32_bf16 v[28:31], v[132:135], v[164:167], v[28:31]
	v_mfma_f32_16x16x32_bf16 v[24:27], v[140:143], v[164:167], v[24:27]
	v_mfma_f32_16x16x32_bf16 v[12:15], v[132:135], v[172:175], v[12:15]
	v_mfma_f32_16x16x32_bf16 v[8:11], v[140:143], v[172:175], v[8:11]
	v_mfma_f32_16x16x32_bf16 v[52:55], v[176:179], v[144:147], v[52:55]
	v_mfma_f32_16x16x32_bf16 v[48:51], v[184:187], v[144:147], v[48:51]
	v_mfma_f32_16x16x32_bf16 v[36:39], v[176:179], v[152:155], v[36:39]
	v_mfma_f32_16x16x32_bf16 v[32:35], v[184:187], v[152:155], v[32:35]
	v_mfma_f32_16x16x32_bf16 v[20:23], v[176:179], v[160:163], v[20:23]
	v_mfma_f32_16x16x32_bf16 v[16:19], v[184:187], v[160:163], v[16:19]
	v_mfma_f32_16x16x32_bf16 v[4:7], v[176:179], v[168:171], v[4:7]
	v_mfma_f32_16x16x32_bf16 v[0:3], v[184:187], v[168:171], v[0:3]
	v_mfma_f32_16x16x32_bf16 v[52:55], v[180:183], v[148:151], v[52:55]
	v_mfma_f32_16x16x32_bf16 v[48:51], v[188:191], v[148:151], v[48:51]
	v_mfma_f32_16x16x32_bf16 v[36:39], v[180:183], v[156:159], v[36:39]
	v_mfma_f32_16x16x32_bf16 v[32:35], v[188:191], v[156:159], v[32:35]
	v_mfma_f32_16x16x32_bf16 v[20:23], v[180:183], v[164:167], v[20:23]
	v_mfma_f32_16x16x32_bf16 v[16:19], v[188:191], v[164:167], v[16:19]
	v_mfma_f32_16x16x32_bf16 v[4:7], v[180:183], v[172:175], v[4:7]
	v_mfma_f32_16x16x32_bf16 v[0:3], v[188:191], v[172:175], v[0:3]
	s_setprio 0
	s_barrier
	v_add_u32_e32 v140, 0x18000, v249
	ds_read_b128 v[128:131], v140
	ds_read_b128 v[132:135], v140 offset:1024
	ds_read_b128 v[136:139], v140 offset:2048
	ds_read_b128 v[140:143], v140 offset:3072
	ds_read_b128 v[144:147], v250 offset:32768
	ds_read_b128 v[148:151], v250 offset:33792
	ds_read_b128 v[152:155], v250 offset:34816
	ds_read_b128 v[156:159], v250 offset:35840
	ds_read_b128 v[160:163], v250 offset:36864
	ds_read_b128 v[164:167], v250 offset:37888
	ds_read_b128 v[168:171], v250 offset:38912
	ds_read_b128 v[172:175], v250 offset:39936
	v_add_u32_e32 v188, 0x1c000, v249
	ds_read_b128 v[176:179], v188
	ds_read_b128 v[180:183], v188 offset:1024
	ds_read_b128 v[184:187], v188 offset:2048
	ds_read_b128 v[188:191], v188 offset:3072
	s_add_i32 s9, 0, 0x18000
	s_add_u32 s4, s4, 0x80000
	s_addc_u32 s5, s5, 0
	s_mov_b32 m0, s63
	v_lshl_add_u64 v[218:219], s[4:5], 0, v[194:195]
	global_load_lds_dwordx4 v[218:219], off
	v_lshl_add_u64 v[220:221], s[4:5], 0, v[198:199]
	s_mov_b32 m0, s69
	s_nop 0
	global_load_lds_dwordx4 v[220:221], off
	s_waitcnt vmcnt(8)
	s_waitcnt lgkmcnt(0)
	s_barrier
	s_setprio 1
	v_mfma_f32_16x16x32_bf16 v[124:127], v[128:131], v[144:147], v[124:127]
	v_mfma_f32_16x16x32_bf16 v[120:123], v[136:139], v[144:147], v[120:123]
	v_mfma_f32_16x16x32_bf16 v[108:111], v[128:131], v[152:155], v[108:111]
	v_mfma_f32_16x16x32_bf16 v[104:107], v[136:139], v[152:155], v[104:107]
	v_mfma_f32_16x16x32_bf16 v[92:95], v[128:131], v[160:163], v[92:95]
	v_mfma_f32_16x16x32_bf16 v[88:91], v[136:139], v[160:163], v[88:91]
	v_mfma_f32_16x16x32_bf16 v[76:79], v[128:131], v[168:171], v[76:79]
	v_mfma_f32_16x16x32_bf16 v[72:75], v[136:139], v[168:171], v[72:75]
	v_mfma_f32_16x16x32_bf16 v[124:127], v[132:135], v[148:151], v[124:127]
	v_mfma_f32_16x16x32_bf16 v[120:123], v[140:143], v[148:151], v[120:123]
	v_mfma_f32_16x16x32_bf16 v[108:111], v[132:135], v[156:159], v[108:111]
	v_mfma_f32_16x16x32_bf16 v[104:107], v[140:143], v[156:159], v[104:107]
	v_mfma_f32_16x16x32_bf16 v[92:95], v[132:135], v[164:167], v[92:95]
	v_mfma_f32_16x16x32_bf16 v[88:91], v[140:143], v[164:167], v[88:91]
	v_mfma_f32_16x16x32_bf16 v[76:79], v[132:135], v[172:175], v[76:79]
	v_mfma_f32_16x16x32_bf16 v[72:75], v[140:143], v[172:175], v[72:75]
	v_mfma_f32_16x16x32_bf16 v[116:119], v[176:179], v[144:147], v[116:119]
	v_mfma_f32_16x16x32_bf16 v[112:115], v[184:187], v[144:147], v[112:115]
	v_mfma_f32_16x16x32_bf16 v[100:103], v[176:179], v[152:155], v[100:103]
	v_mfma_f32_16x16x32_bf16 v[96:99], v[184:187], v[152:155], v[96:99]
	v_mfma_f32_16x16x32_bf16 v[84:87], v[176:179], v[160:163], v[84:87]
	v_mfma_f32_16x16x32_bf16 v[80:83], v[184:187], v[160:163], v[80:83]
	v_mfma_f32_16x16x32_bf16 v[68:71], v[176:179], v[168:171], v[68:71]
	v_mfma_f32_16x16x32_bf16 v[64:67], v[184:187], v[168:171], v[64:67]
	v_mfma_f32_16x16x32_bf16 v[116:119], v[180:183], v[148:151], v[116:119]
	v_mfma_f32_16x16x32_bf16 v[112:115], v[188:191], v[148:151], v[112:115]
	v_mfma_f32_16x16x32_bf16 v[100:103], v[180:183], v[156:159], v[100:103]
	v_mfma_f32_16x16x32_bf16 v[96:99], v[188:191], v[156:159], v[96:99]
	v_mfma_f32_16x16x32_bf16 v[84:87], v[180:183], v[164:167], v[84:87]
	v_mfma_f32_16x16x32_bf16 v[80:83], v[188:191], v[164:167], v[80:83]
	v_mfma_f32_16x16x32_bf16 v[68:71], v[180:183], v[172:175], v[68:71]
	v_mfma_f32_16x16x32_bf16 v[64:67], v[188:191], v[172:175], v[64:67]
	s_setprio 0
	s_barrier
	ds_read_b128 v[144:147], v250 offset:49152
	ds_read_b128 v[148:151], v250 offset:50176
	ds_read_b128 v[152:155], v250 offset:51200
	ds_read_b128 v[156:159], v250 offset:52224
	ds_read_b128 v[160:163], v250 offset:53248
	ds_read_b128 v[164:167], v250 offset:54272
	ds_read_b128 v[168:171], v250 offset:55296
	ds_read_b128 v[172:175], v250 offset:56320
	s_add_i32 s4, 0, 0x1c000
	s_add_i32 s5, s9, s50
	v_lshl_add_u64 v[206:207], v[206:207], 0, s[72:73]
	s_mov_b32 m0, s5
	s_nop 0
	global_load_lds_dwordx4 v[206:207], off
	v_lshl_add_u64 v[206:207], v[208:209], 0, s[72:73]
	s_add_i32 m0, s5, 0x2000
	s_nop 0
	global_load_lds_dwordx4 v[206:207], off
	s_mov_b32 m0, s71
	v_lshl_add_u64 v[206:207], v[210:211], 0, s[72:73]
	global_load_lds_dwordx4 v[206:207], off
	v_lshl_add_u64 v[206:207], v[212:213], 0, s[72:73]
	s_mov_b32 m0, s75
	s_nop 0
	global_load_lds_dwordx4 v[206:207], off
	s_add_u32 s2, s2, 0x80080
	s_addc_u32 s3, s3, 0
	s_add_i32 s4, s4, s50
	v_lshl_add_u64 v[218:219], s[2:3], 0, v[196:197]
	s_mov_b32 m0, s4
	s_nop 0
	global_load_lds_dwordx4 v[218:219], off
	v_lshl_add_u64 v[220:221], s[2:3], 0, v[200:201]
	s_add_i32 m0, s4, 0x2000
	s_nop 0
	global_load_lds_dwordx4 v[220:221], off
	s_waitcnt vmcnt(8)
	s_waitcnt lgkmcnt(0)
	s_barrier
	s_setprio 1
	v_mfma_f32_16x16x32_bf16 v[60:63], v[128:131], v[144:147], v[60:63]
	v_mfma_f32_16x16x32_bf16 v[56:59], v[136:139], v[144:147], v[56:59]
	v_mfma_f32_16x16x32_bf16 v[44:47], v[128:131], v[152:155], v[44:47]
	v_mfma_f32_16x16x32_bf16 v[40:43], v[136:139], v[152:155], v[40:43]
	v_mfma_f32_16x16x32_bf16 v[28:31], v[128:131], v[160:163], v[28:31]
	v_mfma_f32_16x16x32_bf16 v[24:27], v[136:139], v[160:163], v[24:27]
	v_mfma_f32_16x16x32_bf16 v[12:15], v[128:131], v[168:171], v[12:15]
	v_mfma_f32_16x16x32_bf16 v[8:11], v[136:139], v[168:171], v[8:11]
	v_mfma_f32_16x16x32_bf16 v[60:63], v[132:135], v[148:151], v[60:63]
	v_mfma_f32_16x16x32_bf16 v[56:59], v[140:143], v[148:151], v[56:59]
	v_mfma_f32_16x16x32_bf16 v[44:47], v[132:135], v[156:159], v[44:47]
	v_mfma_f32_16x16x32_bf16 v[40:43], v[140:143], v[156:159], v[40:43]
	v_mfma_f32_16x16x32_bf16 v[28:31], v[132:135], v[164:167], v[28:31]
	v_mfma_f32_16x16x32_bf16 v[24:27], v[140:143], v[164:167], v[24:27]
	v_mfma_f32_16x16x32_bf16 v[12:15], v[132:135], v[172:175], v[12:15]
	v_mfma_f32_16x16x32_bf16 v[8:11], v[140:143], v[172:175], v[8:11]
	v_mfma_f32_16x16x32_bf16 v[52:55], v[176:179], v[144:147], v[52:55]
	v_mfma_f32_16x16x32_bf16 v[48:51], v[184:187], v[144:147], v[48:51]
	v_mfma_f32_16x16x32_bf16 v[36:39], v[176:179], v[152:155], v[36:39]
	v_mfma_f32_16x16x32_bf16 v[32:35], v[184:187], v[152:155], v[32:35]
	v_mfma_f32_16x16x32_bf16 v[20:23], v[176:179], v[160:163], v[20:23]
	v_mfma_f32_16x16x32_bf16 v[16:19], v[184:187], v[160:163], v[16:19]
	v_mfma_f32_16x16x32_bf16 v[4:7], v[176:179], v[168:171], v[4:7]
	v_mfma_f32_16x16x32_bf16 v[0:3], v[184:187], v[168:171], v[0:3]
	v_mfma_f32_16x16x32_bf16 v[52:55], v[180:183], v[148:151], v[52:55]
	v_mfma_f32_16x16x32_bf16 v[48:51], v[188:191], v[148:151], v[48:51]
	v_mfma_f32_16x16x32_bf16 v[36:39], v[180:183], v[156:159], v[36:39]
	v_mfma_f32_16x16x32_bf16 v[32:35], v[188:191], v[156:159], v[32:35]
	v_mfma_f32_16x16x32_bf16 v[20:23], v[180:183], v[164:167], v[20:23]
	v_mfma_f32_16x16x32_bf16 v[16:19], v[188:191], v[164:167], v[16:19]
	v_mfma_f32_16x16x32_bf16 v[4:7], v[180:183], v[172:175], v[4:7]
	v_mfma_f32_16x16x32_bf16 v[0:3], v[188:191], v[172:175], v[0:3]
	s_setprio 0
	s_add_i32 s40, s40, 2
	s_add_u32 s0, s0, 0x100
	s_addc_u32 s1, s1, 0
	s_add_u32 s36, s36, 0x100
	s_addc_u32 s37, s37, 0
	s_cmp_gt_u32 s40, 29
	s_barrier
	s_cbranch_scc0 .LBB0_329
	v_mov_b32 v128, v248
	s_cmp_gt_u32 s38, 1
	v_and_b32_e32 v246, 15, v128
	v_ashrrev_i32_e32 v247, 4, v128
	s_mov_b64 s[0:1], -1
	s_cbranch_scc0 .LBB0_413
	s_and_b32 s4, s39, 3
	s_cmp_lg_u32 s38, 2
	s_cbranch_scc0 .LBB0_400
	s_lshl_b32 s40, s49, 8
	v_or_b32_e32 v128, s78, v246
	v_add_u32_e32 v134, s40, v128
	v_min_i32_e32 v130, 0x2000, v134
	v_lshlrev_b32_e32 v130, 8, v130
	v_add_lshl_u32 v206, v247, s85, 2
	v_readlane_b32 s0, v251, 61
	v_and_b32_e32 v192, 0x7cf00, v130
	v_or_b32_e32 v130, 16, v134
	v_ashrrev_i32_e32 v207, 31, v206
	v_readlane_b32 s1, v251, 62
	v_min_i32_e32 v130, 0x2000, v130
	v_or_b32_e32 v132, 32, v134
	v_lshl_add_u64 v[128:129], v[206:207], 2, s[0:1]
	v_lshlrev_b32_e32 v130, 8, v130
	v_min_i32_e32 v132, 0x2000, v132
	v_lshl_add_u64 v[210:211], v[128:129], 0, v[192:193]
	v_and_b32_e32 v192, 0x7ff00, v130
	v_lshlrev_b32_e32 v132, 8, v132
	v_lshl_add_u64 v[130:131], v[128:129], 0, v[192:193]
	v_and_b32_e32 v192, 0x7ff00, v132
	global_load_dwordx4 v[188:191], v[210:211], off offset:128
	global_load_dwordx4 v[176:179], v[130:131], off
	v_lshl_add_u64 v[132:133], v[128:129], 0, v[192:193]
	global_load_dwordx4 v[180:183], v[130:131], off offset:128
	global_load_dwordx4 v[168:171], v[132:133], off
	v_or_b32_e32 v130, 48, v134
	v_min_i32_e32 v130, 0x2000, v130
	v_lshlrev_b32_e32 v130, 8, v130
	v_and_b32_e32 v192, 0x7ff00, v130
	v_lshl_add_u64 v[130:131], v[128:129], 0, v[192:193]
	global_load_dwordx4 v[172:175], v[132:133], off offset:128
	global_load_dwordx4 v[160:163], v[130:131], off
	v_add_u32_e32 v132, 0x80, v134
	v_min_i32_e32 v132, 0x2000, v132
	v_lshlrev_b32_e32 v132, 8, v132
	v_and_b32_e32 v192, 0x7ff00, v132
	v_lshl_add_u64 v[132:133], v[128:129], 0, v[192:193]
	global_load_dwordx4 v[164:167], v[130:131], off offset:128
	global_load_dwordx4 v[152:155], v[132:133], off
	v_add_u32_e32 v130, 0x90, v134
	v_min_i32_e32 v130, 0x2000, v130
	v_lshlrev_b32_e32 v130, 8, v130
	v_and_b32_e32 v192, 0x7ff00, v130
	v_lshl_add_u64 v[130:131], v[128:129], 0, v[192:193]
	global_load_dwordx4 v[156:159], v[132:133], off offset:128
	global_load_dwordx4 v[144:147], v[130:131], off
	v_add_u32_e32 v132, 0xa0, v134
	v_min_i32_e32 v132, 0x2000, v132
	v_lshlrev_b32_e32 v132, 8, v132
	v_and_b32_e32 v192, 0x7ff00, v132
	v_lshl_add_u64 v[132:133], v[128:129], 0, v[192:193]
	global_load_dwordx4 v[148:151], v[130:131], off offset:128
	global_load_dwordx4 v[136:139], v[132:133], off
	v_add_u32_e32 v130, 0xb0, v134
	v_min_i32_e32 v130, 0x2000, v130
	v_lshlrev_b32_e32 v130, 8, v130
	v_and_b32_e32 v192, 0x7ff00, v130
	v_lshl_add_u64 v[128:129], v[128:129], 0, v[192:193]
	global_load_dwordx4 v[140:143], v[132:133], off offset:128
	s_nop 0
	global_load_dwordx4 v[132:135], v[128:129], off
	s_nop 0
	global_load_dwordx4 v[128:131], v[128:129], off offset:128
	s_add_i32 s2, s40, s78
	v_or_b32_e32 v208, s2, v246
	v_mov_b32_e32 v184, 1.0
	v_cmp_gt_i32_e32 vcc, s33, v208
	v_mov_b32_e32 v185, v184
	v_mov_b32_e32 v186, v184
	v_mov_b32_e32 v187, v184
	s_and_saveexec_b64 s[0:1], vcc
	s_cbranch_execz .LBB0_334
	global_load_dwordx4 v[184:187], v[210:211], off
